# GEMM K-loops: LDS-DMA loads use SGPR base + 32-bit VGPR offset or an immediate +128 (compensated in M0) instead of per-load 64-bit VALU address adds; on top of v17
# baseline (speedup 1.0000x reference)
; #define PG8_STAGE(bufoff, gbase, voff) do { _Pragma("unroll") for (int _i = 0; _i < 2; ++_i) \
;         __builtin_amdgcn_global_load_lds((const unsigned*)((const char*)(gbase) + (voff)[_i]), (PG8_LAS unsigned*)(lds + (bufoff) + ldsw + _i * 8192), 16, 0, 0); } while (0)
; #define PG8_LDA(dst, b, h) do { _Pragma("unroll") for (int m = 0; m < 4; ++m) _Pragma("unroll") for (int k = 0; k < 2; ++k) dst[m][k] = *(const PG8_LAS bf16x8*)(lds + PG8_SA(b, h) + aoff + m * 2048 + k * 1024); } while (0)
; #define PG8_WAIT_V(n) asm volatile("s_waitcnt vmcnt(" #n ")" ::: "memory")
; template <class Epi, class Sched, bool ALIGN_EPI = false, bool SP2 = false>
; __device__ __forceinline__ void gemm_phase(PG8_LAS unsigned char* lds, const Gemm g, const Sched& S, const Epi& E, const int tid) {
;     ...
;         for (int t = 0; t < nt; t += 2) {
;             if constexpr (Epi::KHOOK) { if (t == 8 || t == 16) E.khook(acc, cur, t, wr, wc, fr, fq); }
;             const bool last = (t == nt - 2);
;             const char* a1 = cA + (size_t)(t + 1) * kstep;
;             const char* a2 = last ? nA : cA + (size_t)(t + 2) * kstep; const char* b2 = last ? nB : cB + (size_t)(t + 2) * kstep;
;             const char* a3 = a2 + kstep; const char* b3 = b2 + kstep;
;             if (last && has_next) S.a_ready(nxt);
;             if constexpr (SP2) {
;             PG8_LDB(B0, 0, 0); PG8_LDB(B1, 0, 1); PG8_SCHED; PG8_LDA(At, 0, 0); PG8_STAGE(PG8_SA(1, 1), a1 + hstepA, voffA);
;             PG8_WAIT_V(8); PG8_WAIT_L(0); PG8_BAR; PG8_MMA(0, 0, At, B0); PG8_MMA(0, 1, At, B1); PG8_BAR; PG8_SCHED;
;             PG8_LDA(At, 0, 1); PG8_STAGE(PG8_SB(0, 0), b2, voffB); PG8_STAGE(PG8_SB(0, 1), b2 + hstepB, voffB); PG8_STAGE(PG8_SA(0, 0), a2, voffA);
;             PG8_WAIT_V(8); PG8_WAIT_L(0); PG8_BAR; PG8_MMA(1, 0, At, B0); PG8_MMA(1, 1, At, B1); PG8_BAR; PG8_SCHED;
;             PG8_LDB(B0, 1, 0); PG8_LDB(B1, 1, 1); PG8_SCHED; PG8_LDA(At, 1, 0); PG8_STAGE(PG8_SA(0, 1), a2 + hstepA, voffA);
;             PG8_WAIT_V(8); PG8_WAIT_L(0); PG8_BAR; PG8_MMA(0, 0, At, B0); PG8_MMA(0, 1, At, B1); PG8_BAR; PG8_SCHED;
;             PG8_LDA(At, 1, 1); PG8_STAGE(PG8_SB(1, 0), b3, voffB); PG8_STAGE(PG8_SB(1, 1), b3 + hstepB, voffB); PG8_STAGE(PG8_SA(1, 0), a3, voffA);
;             PG8_WAIT_V(8); PG8_WAIT_L(0); PG8_BAR; PG8_MMA(1, 0, At, B0); PG8_MMA(1, 1, At, B1); PG8_BAR; PG8_SCHED;
.LBB0_508:
	s_add_i32 s15, s12, 2
	s_add_u32 s54, s4, 0x80
	s_addc_u32 s13, s5, 0
	s_add_i32 s79, 0, 0x10000
	s_cmp_eq_u32 s74, s12
	s_cselect_b32 s13, s51, s13
	s_cselect_b32 s12, s50, s54
	v_add_u32_e32 v148, s79, v216
	s_cselect_b32 s55, s53, s14
	s_cselect_b32 s54, s52, s3
	s_add_i32 s80, 0, 0x14000
	s_waitcnt lgkmcnt(0)
	ds_read_b128 v[128:131], v148
	ds_read_b128 v[132:135], v148 offset:1024
	ds_read_b128 v[160:163], v148 offset:2048
	ds_read_b128 v[164:167], v148 offset:3072
	v_add_u32_e32 v148, s80, v216
	ds_read_b128 v[168:171], v148
	ds_read_b128 v[172:175], v148 offset:1024
	ds_read_b128 v[176:179], v148 offset:2048
	ds_read_b128 v[180:183], v148 offset:3072
	s_add_i32 m0, s66, 0xc000
	ds_read_b128 v[184:187], v222
	ds_read_b128 v[188:191], v222 offset:1024
	ds_read_b128 v[192:195], v222 offset:2048
	ds_read_b128 v[196:199], v222 offset:3072
	ds_read_b128 v[200:203], v222 offset:4096
	ds_read_b128 v[224:227], v222 offset:5120
	ds_read_b128 v[228:231], v222 offset:6144
	ds_read_b128 v[234:237], v222 offset:7168
	global_load_lds_dwordx4 v154, s[4:5]
	s_add_i32 m0, s66, 0xe000
	s_nop 0
	global_load_lds_dwordx4 v156, s[4:5]
	s_waitcnt vmcnt(8)
	s_waitcnt lgkmcnt(0)
	s_barrier
	s_setprio 1
	s_waitcnt lgkmcnt(0)
	v_mfma_f32_16x16x32_bf16 v[124:127], v[128:131], v[184:187], v[124:127]
	v_mfma_f32_16x16x32_bf16 v[120:123], v[160:163], v[184:187], v[120:123]
	v_mfma_f32_16x16x32_bf16 v[108:111], v[128:131], v[192:195], v[108:111]
	v_mfma_f32_16x16x32_bf16 v[104:107], v[160:163], v[192:195], v[104:107]
	v_mfma_f32_16x16x32_bf16 v[92:95], v[128:131], v[200:203], v[92:95]
	v_mfma_f32_16x16x32_bf16 v[88:91], v[160:163], v[200:203], v[88:91]
	v_mfma_f32_16x16x32_bf16 v[76:79], v[128:131], v[228:231], v[76:79]
	v_mfma_f32_16x16x32_bf16 v[72:75], v[160:163], v[228:231], v[72:75]
	v_mfma_f32_16x16x32_bf16 v[124:127], v[132:135], v[188:191], v[124:127]
	v_mfma_f32_16x16x32_bf16 v[120:123], v[164:167], v[188:191], v[120:123]
	v_mfma_f32_16x16x32_bf16 v[108:111], v[132:135], v[196:199], v[108:111]
	v_mfma_f32_16x16x32_bf16 v[104:107], v[164:167], v[196:199], v[104:107]
	v_mfma_f32_16x16x32_bf16 v[92:95], v[132:135], v[224:227], v[92:95]
	v_mfma_f32_16x16x32_bf16 v[88:91], v[164:167], v[224:227], v[88:91]
	v_mfma_f32_16x16x32_bf16 v[76:79], v[132:135], v[234:237], v[76:79]
	v_mfma_f32_16x16x32_bf16 v[72:75], v[164:167], v[234:237], v[72:75]
	s_setprio 0
	s_setprio 1
	v_mfma_f32_16x16x32_bf16 v[116:119], v[168:171], v[184:187], v[116:119]
	v_mfma_f32_16x16x32_bf16 v[112:115], v[176:179], v[184:187], v[112:115]
	v_mfma_f32_16x16x32_bf16 v[100:103], v[168:171], v[192:195], v[100:103]
	v_mfma_f32_16x16x32_bf16 v[96:99], v[176:179], v[192:195], v[96:99]
	v_mfma_f32_16x16x32_bf16 v[84:87], v[168:171], v[200:203], v[84:87]
	v_mfma_f32_16x16x32_bf16 v[80:83], v[176:179], v[200:203], v[80:83]
	v_mfma_f32_16x16x32_bf16 v[68:71], v[168:171], v[228:231], v[68:71]
	v_mfma_f32_16x16x32_bf16 v[64:67], v[176:179], v[228:231], v[64:67]
	v_mfma_f32_16x16x32_bf16 v[116:119], v[172:175], v[188:191], v[116:119]
	v_mfma_f32_16x16x32_bf16 v[112:115], v[180:183], v[188:191], v[112:115]
	v_mfma_f32_16x16x32_bf16 v[100:103], v[172:175], v[196:199], v[100:103]
	v_mfma_f32_16x16x32_bf16 v[96:99], v[180:183], v[196:199], v[96:99]
	v_mfma_f32_16x16x32_bf16 v[84:87], v[172:175], v[224:227], v[84:87]
	v_mfma_f32_16x16x32_bf16 v[80:83], v[180:183], v[224:227], v[80:83]
	v_mfma_f32_16x16x32_bf16 v[68:71], v[172:175], v[234:237], v[68:71]
	v_mfma_f32_16x16x32_bf16 v[64:67], v[180:183], v[234:237], v[64:67]
	s_setprio 0
	s_barrier
	s_add_i32 s79, s79, s61
	v_lshl_add_u64 v[204:205], s[54:55], 0, v[138:139]
	s_mov_b32 m0, s79
	ds_read_b128 v[184:187], v222 offset:16384
	ds_read_b128 v[188:191], v222 offset:17408
	ds_read_b128 v[192:195], v222 offset:18432
	ds_read_b128 v[196:199], v222 offset:19456
	ds_read_b128 v[200:203], v222 offset:20480
	ds_read_b128 v[224:227], v222 offset:21504
	ds_read_b128 v[228:231], v222 offset:22528
	ds_read_b128 v[234:237], v222 offset:23552
	global_load_lds_dwordx4 v[204:205], off
	s_add_i32 m0, s79, 0x2000
	v_lshl_add_u64 v[238:239], s[54:55], 0, v[142:143]
	s_add_u32 s54, s54, s28
	s_addc_u32 s55, s55, s29
	s_add_i32 s79, s80, s61
	global_load_lds_dwordx4 v[238:239], off
	v_lshl_add_u64 v[240:241], s[54:55], 0, v[138:139]
	s_mov_b32 m0, s79
	v_lshl_add_u64 v[242:243], s[54:55], 0, v[142:143]
	global_load_lds_dwordx4 v[240:241], off
	s_add_i32 m0, s79, 0x2000
	v_lshl_add_u64 v[244:245], s[12:13], 0, v[136:137]
	global_load_lds_dwordx4 v[242:243], off
	s_mov_b32 m0, s66
	v_lshl_add_u64 v[246:247], s[12:13], 0, v[140:141]
	global_load_lds_dwordx4 v[244:245], off
	s_mov_b32 m0, s67
	s_nop 0
	global_load_lds_dwordx4 v[246:247], off
	s_waitcnt vmcnt(8)
	s_waitcnt lgkmcnt(0)
	s_barrier
; #define PG8_STAGE(bufoff, gbase, voff) do { _Pragma("unroll") for (int _i = 0; _i < 2; ++_i) \
;         __builtin_amdgcn_global_load_lds((const unsigned*)((const char*)(gbase) + (voff)[_i]), (PG8_LAS unsigned*)(lds + (bufoff) + ldsw + _i * 8192), 16, 0, 0); } while (0)
; #define PG8_LDA(dst, b, h) do { _Pragma("unroll") for (int m = 0; m < 4; ++m) _Pragma("unroll") for (int k = 0; k < 2; ++k) dst[m][k] = *(const PG8_LAS bf16x8*)(lds + PG8_SA(b, h) + aoff + m * 2048 + k * 1024); } while (0)
; #define PG8_WAIT_V(n) asm volatile("s_waitcnt vmcnt(" #n ")" ::: "memory")
; template <class Epi, class Sched, bool ALIGN_EPI = false, bool SP2 = false>
; __device__ __forceinline__ void gemm_phase(PG8_LAS unsigned char* lds, const Gemm g, const Sched& S, const Epi& E, const int tid) {
;     ...
;         for (int t = 0; t < nt; t += 2) {
;             if constexpr (Epi::KHOOK) { if (t == 8 || t == 16) E.khook(acc, cur, t, wr, wc, fr, fq); }
;             const bool last = (t == nt - 2);
;             const char* a1 = cA + (size_t)(t + 1) * kstep;
;             const char* a2 = last ? nA : cA + (size_t)(t + 2) * kstep; const char* b2 = last ? nB : cB + (size_t)(t + 2) * kstep;
;             const char* a3 = a2 + kstep; const char* b3 = b2 + kstep;
;             if (last && has_next) S.a_ready(nxt);
;             if constexpr (SP2) {
;             PG8_LDB(B0, 0, 0); PG8_LDB(B1, 0, 1); PG8_SCHED; PG8_LDA(At, 0, 0); PG8_STAGE(PG8_SA(1, 1), a1 + hstepA, voffA);
;             PG8_WAIT_V(8); PG8_WAIT_L(0); PG8_BAR; PG8_MMA(0, 0, At, B0); PG8_MMA(0, 1, At, B1); PG8_BAR; PG8_SCHED;
;             PG8_LDA(At, 0, 1); PG8_STAGE(PG8_SB(0, 0), b2, voffB); PG8_STAGE(PG8_SB(0, 1), b2 + hstepB, voffB); PG8_STAGE(PG8_SA(0, 0), a2, voffA);
;             PG8_WAIT_V(8); PG8_WAIT_L(0); PG8_BAR; PG8_MMA(1, 0, At, B0); PG8_MMA(1, 1, At, B1); PG8_BAR; PG8_SCHED;
;             PG8_LDB(B0, 1, 0); PG8_LDB(B1, 1, 1); PG8_SCHED; PG8_LDA(At, 1, 0); PG8_STAGE(PG8_SA(0, 1), a2 + hstepA, voffA);
;             PG8_WAIT_V(8); PG8_WAIT_L(0); PG8_BAR; PG8_MMA(0, 0, At, B0); PG8_MMA(0, 1, At, B1); PG8_BAR; PG8_SCHED;
;             PG8_LDA(At, 1, 1); PG8_STAGE(PG8_SB(1, 0), b3, voffB); PG8_STAGE(PG8_SB(1, 1), b3 + hstepB, voffB); PG8_STAGE(PG8_SA(1, 0), a3, voffA);
;             PG8_WAIT_V(8); PG8_WAIT_L(0); PG8_BAR; PG8_MMA(1, 0, At, B0); PG8_MMA(1, 1, At, B1); PG8_BAR; PG8_SCHED;
	s_setprio 1
	s_waitcnt lgkmcnt(0)
	v_mfma_f32_16x16x32_bf16 v[60:63], v[128:131], v[184:187], v[60:63]
	v_mfma_f32_16x16x32_bf16 v[56:59], v[160:163], v[184:187], v[56:59]
	v_mfma_f32_16x16x32_bf16 v[44:47], v[128:131], v[192:195], v[44:47]
	v_mfma_f32_16x16x32_bf16 v[40:43], v[160:163], v[192:195], v[40:43]
	v_mfma_f32_16x16x32_bf16 v[28:31], v[128:131], v[200:203], v[28:31]
	v_mfma_f32_16x16x32_bf16 v[24:27], v[160:163], v[200:203], v[24:27]
	v_mfma_f32_16x16x32_bf16 v[12:15], v[128:131], v[228:231], v[12:15]
	v_mfma_f32_16x16x32_bf16 v[8:11], v[160:163], v[228:231], v[8:11]
	v_mfma_f32_16x16x32_bf16 v[60:63], v[132:135], v[188:191], v[60:63]
	v_mfma_f32_16x16x32_bf16 v[56:59], v[164:167], v[188:191], v[56:59]
	v_mfma_f32_16x16x32_bf16 v[44:47], v[132:135], v[196:199], v[44:47]
	v_mfma_f32_16x16x32_bf16 v[40:43], v[164:167], v[196:199], v[40:43]
	v_mfma_f32_16x16x32_bf16 v[28:31], v[132:135], v[224:227], v[28:31]
	v_mfma_f32_16x16x32_bf16 v[24:27], v[164:167], v[224:227], v[24:27]
	v_mfma_f32_16x16x32_bf16 v[12:15], v[132:135], v[234:237], v[12:15]
	v_mfma_f32_16x16x32_bf16 v[8:11], v[164:167], v[234:237], v[8:11]
	s_setprio 0
	s_setprio 1
	v_mfma_f32_16x16x32_bf16 v[52:55], v[168:171], v[184:187], v[52:55]
	v_mfma_f32_16x16x32_bf16 v[48:51], v[176:179], v[184:187], v[48:51]
	v_mfma_f32_16x16x32_bf16 v[36:39], v[168:171], v[192:195], v[36:39]
	v_mfma_f32_16x16x32_bf16 v[32:35], v[176:179], v[192:195], v[32:35]
	v_mfma_f32_16x16x32_bf16 v[20:23], v[168:171], v[200:203], v[20:23]
	v_mfma_f32_16x16x32_bf16 v[16:19], v[176:179], v[200:203], v[16:19]
	v_mfma_f32_16x16x32_bf16 v[4:7], v[168:171], v[228:231], v[4:7]
	v_mfma_f32_16x16x32_bf16 v[0:3], v[176:179], v[228:231], v[0:3]
	v_mfma_f32_16x16x32_bf16 v[52:55], v[172:175], v[188:191], v[52:55]
	v_mfma_f32_16x16x32_bf16 v[48:51], v[180:183], v[188:191], v[48:51]
	v_mfma_f32_16x16x32_bf16 v[36:39], v[172:175], v[196:199], v[36:39]
	v_mfma_f32_16x16x32_bf16 v[32:35], v[180:183], v[196:199], v[32:35]
	v_mfma_f32_16x16x32_bf16 v[20:23], v[172:175], v[224:227], v[20:23]
	v_mfma_f32_16x16x32_bf16 v[16:19], v[180:183], v[224:227], v[16:19]
	v_mfma_f32_16x16x32_bf16 v[4:7], v[172:175], v[234:237], v[4:7]
	v_mfma_f32_16x16x32_bf16 v[0:3], v[180:183], v[234:237], v[0:3]
	s_setprio 0
	s_barrier
	s_add_i32 s54, 0, 0x18000
	v_add_u32_e32 v148, s54, v216
	s_add_i32 s55, 0, 0x1c000
	ds_read_b128 v[128:131], v148
	ds_read_b128 v[132:135], v148 offset:1024
	ds_read_b128 v[160:163], v148 offset:2048
	ds_read_b128 v[164:167], v148 offset:3072
	v_add_u32_e32 v148, s55, v216
	ds_read_b128 v[168:171], v148
	ds_read_b128 v[172:175], v148 offset:1024
	ds_read_b128 v[176:179], v148 offset:2048
	ds_read_b128 v[180:183], v148 offset:3072
	s_add_u32 s12, s12, s26
	s_addc_u32 s13, s13, s27
	s_mov_b32 m0, s68
	ds_read_b128 v[184:187], v222 offset:32768
	ds_read_b128 v[188:191], v222 offset:33792
	ds_read_b128 v[192:195], v222 offset:34816
	ds_read_b128 v[196:199], v222 offset:35840
	ds_read_b128 v[200:203], v222 offset:36864
	ds_read_b128 v[224:227], v222 offset:37888
	ds_read_b128 v[228:231], v222 offset:38912
	ds_read_b128 v[234:237], v222 offset:39936
	global_load_lds_dwordx4 v136, s[12:13]
	s_mov_b32 m0, s69
	s_nop 0
	global_load_lds_dwordx4 v140, s[12:13]
	s_waitcnt vmcnt(8)
	s_waitcnt lgkmcnt(0)
	s_barrier
	s_setprio 1
	s_waitcnt lgkmcnt(0)
	v_mfma_f32_16x16x32_bf16 v[124:127], v[128:131], v[184:187], v[124:127]
	v_mfma_f32_16x16x32_bf16 v[120:123], v[160:163], v[184:187], v[120:123]
	v_mfma_f32_16x16x32_bf16 v[108:111], v[128:131], v[192:195], v[108:111]
	v_mfma_f32_16x16x32_bf16 v[104:107], v[160:163], v[192:195], v[104:107]
	v_mfma_f32_16x16x32_bf16 v[92:95], v[128:131], v[200:203], v[92:95]
	v_mfma_f32_16x16x32_bf16 v[88:91], v[160:163], v[200:203], v[88:91]
	v_mfma_f32_16x16x32_bf16 v[76:79], v[128:131], v[228:231], v[76:79]
	v_mfma_f32_16x16x32_bf16 v[72:75], v[160:163], v[228:231], v[72:75]
	v_mfma_f32_16x16x32_bf16 v[124:127], v[132:135], v[188:191], v[124:127]
	v_mfma_f32_16x16x32_bf16 v[120:123], v[164:167], v[188:191], v[120:123]
	v_mfma_f32_16x16x32_bf16 v[108:111], v[132:135], v[196:199], v[108:111]
	v_mfma_f32_16x16x32_bf16 v[104:107], v[164:167], v[196:199], v[104:107]
	v_mfma_f32_16x16x32_bf16 v[92:95], v[132:135], v[224:227], v[92:95]
	v_mfma_f32_16x16x32_bf16 v[88:91], v[164:167], v[224:227], v[88:91]
	v_mfma_f32_16x16x32_bf16 v[76:79], v[132:135], v[234:237], v[76:79]
	v_mfma_f32_16x16x32_bf16 v[72:75], v[164:167], v[234:237], v[72:75]
	s_setprio 0
	s_setprio 1
	v_mfma_f32_16x16x32_bf16 v[116:119], v[168:171], v[184:187], v[116:119]
	v_mfma_f32_16x16x32_bf16 v[112:115], v[176:179], v[184:187], v[112:115]
	v_mfma_f32_16x16x32_bf16 v[100:103], v[168:171], v[192:195], v[100:103]
	v_mfma_f32_16x16x32_bf16 v[96:99], v[176:179], v[192:195], v[96:99]
	v_mfma_f32_16x16x32_bf16 v[84:87], v[168:171], v[200:203], v[84:87]
	v_mfma_f32_16x16x32_bf16 v[80:83], v[176:179], v[200:203], v[80:83]
	v_mfma_f32_16x16x32_bf16 v[68:71], v[168:171], v[228:231], v[68:71]
	v_mfma_f32_16x16x32_bf16 v[64:67], v[176:179], v[228:231], v[64:67]
	v_mfma_f32_16x16x32_bf16 v[116:119], v[172:175], v[188:191], v[116:119]
	v_mfma_f32_16x16x32_bf16 v[112:115], v[180:183], v[188:191], v[112:115]
	v_mfma_f32_16x16x32_bf16 v[100:103], v[172:175], v[196:199], v[100:103]
	v_mfma_f32_16x16x32_bf16 v[96:99], v[180:183], v[196:199], v[96:99]
	v_mfma_f32_16x16x32_bf16 v[84:87], v[172:175], v[224:227], v[84:87]
	v_mfma_f32_16x16x32_bf16 v[80:83], v[180:183], v[224:227], v[80:83]
	v_mfma_f32_16x16x32_bf16 v[68:71], v[172:175], v[234:237], v[68:71]
	v_mfma_f32_16x16x32_bf16 v[64:67], v[180:183], v[234:237], v[64:67]
	s_setprio 0
	s_barrier
; #define PG8_STAGE(bufoff, gbase, voff) do { _Pragma("unroll") for (int _i = 0; _i < 2; ++_i) \
;         __builtin_amdgcn_global_load_lds((const unsigned*)((const char*)(gbase) + (voff)[_i]), (PG8_LAS unsigned*)(lds + (bufoff) + ldsw + _i * 8192), 16, 0, 0); } while (0)
; #define PG8_LDA(dst, b, h) do { _Pragma("unroll") for (int m = 0; m < 4; ++m) _Pragma("unroll") for (int k = 0; k < 2; ++k) dst[m][k] = *(const PG8_LAS bf16x8*)(lds + PG8_SA(b, h) + aoff + m * 2048 + k * 1024); } while (0)
; #define PG8_WAIT_V(n) asm volatile("s_waitcnt vmcnt(" #n ")" ::: "memory")
; template <class Epi, class Sched, bool ALIGN_EPI = false, bool SP2 = false>
; __device__ __forceinline__ void gemm_phase(PG8_LAS unsigned char* lds, const Gemm g, const Sched& S, const Epi& E, const int tid) {
;     ...
;         for (int t = 0; t < nt; t += 2) {
;             if constexpr (Epi::KHOOK) { if (t == 8 || t == 16) E.khook(acc, cur, t, wr, wc, fr, fq); }
;             const bool last = (t == nt - 2);
;             const char* a1 = cA + (size_t)(t + 1) * kstep;
;             const char* a2 = last ? nA : cA + (size_t)(t + 2) * kstep; const char* b2 = last ? nB : cB + (size_t)(t + 2) * kstep;
;             const char* a3 = a2 + kstep; const char* b3 = b2 + kstep;
;             if (last && has_next) S.a_ready(nxt);
;             if constexpr (SP2) {
;             PG8_LDB(B0, 0, 0); PG8_LDB(B1, 0, 1); PG8_SCHED; PG8_LDA(At, 0, 0); PG8_STAGE(PG8_SA(1, 1), a1 + hstepA, voffA);
;             PG8_WAIT_V(8); PG8_WAIT_L(0); PG8_BAR; PG8_MMA(0, 0, At, B0); PG8_MMA(0, 1, At, B1); PG8_BAR; PG8_SCHED;
;             PG8_LDA(At, 0, 1); PG8_STAGE(PG8_SB(0, 0), b2, voffB); PG8_STAGE(PG8_SB(0, 1), b2 + hstepB, voffB); PG8_STAGE(PG8_SA(0, 0), a2, voffA);
;             PG8_WAIT_V(8); PG8_WAIT_L(0); PG8_BAR; PG8_MMA(1, 0, At, B0); PG8_MMA(1, 1, At, B1); PG8_BAR; PG8_SCHED;
;             PG8_LDB(B0, 1, 0); PG8_LDB(B1, 1, 1); PG8_SCHED; PG8_LDA(At, 1, 0); PG8_STAGE(PG8_SA(0, 1), a2 + hstepA, voffA);
;             PG8_WAIT_V(8); PG8_WAIT_L(0); PG8_BAR; PG8_MMA(0, 0, At, B0); PG8_MMA(0, 1, At, B1); PG8_BAR; PG8_SCHED;
;             PG8_LDA(At, 1, 1); PG8_STAGE(PG8_SB(1, 0), b3, voffB); PG8_STAGE(PG8_SB(1, 1), b3 + hstepB, voffB); PG8_STAGE(PG8_SA(1, 0), a3, voffA);
;             PG8_WAIT_V(8); PG8_WAIT_L(0); PG8_BAR; PG8_MMA(1, 0, At, B0); PG8_MMA(1, 1, At, B1); PG8_BAR; PG8_SCHED;
	s_add_i32 s12, s54, s61
	s_add_i32 m0, s12, 0xffffff80
	ds_read_b128 v[184:187], v222 offset:49152
	ds_read_b128 v[188:191], v222 offset:50176
	ds_read_b128 v[192:195], v222 offset:51200
	ds_read_b128 v[196:199], v222 offset:52224
	ds_read_b128 v[200:203], v222 offset:53248
	ds_read_b128 v[224:227], v222 offset:54272
	ds_read_b128 v[228:231], v222 offset:55296
	ds_read_b128 v[234:237], v222 offset:56320
	global_load_lds_dwordx4 v[204:205], off offset:128
	s_add_i32 m0, s12, 0x1f80
	s_add_i32 s12, s55, s61
	global_load_lds_dwordx4 v[238:239], off offset:128
	s_add_i32 m0, s12, 0xffffff80
	s_nop 0
	global_load_lds_dwordx4 v[240:241], off offset:128
	s_add_i32 m0, s12, 0x1f80
	s_nop 0
	global_load_lds_dwordx4 v[242:243], off offset:128
	s_add_i32 m0, s72, 0xffffff80
	s_nop 0
	global_load_lds_dwordx4 v[244:245], off offset:128
	s_add_i32 m0, s73, 0xffffff80
	s_nop 0
	global_load_lds_dwordx4 v[246:247], off offset:128
	s_waitcnt vmcnt(8)
	s_waitcnt lgkmcnt(0)
	s_barrier
	s_setprio 1
	s_waitcnt lgkmcnt(0)
	v_mfma_f32_16x16x32_bf16 v[60:63], v[128:131], v[184:187], v[60:63]
	v_mfma_f32_16x16x32_bf16 v[56:59], v[160:163], v[184:187], v[56:59]
	v_mfma_f32_16x16x32_bf16 v[44:47], v[128:131], v[192:195], v[44:47]
	v_mfma_f32_16x16x32_bf16 v[40:43], v[160:163], v[192:195], v[40:43]
	v_mfma_f32_16x16x32_bf16 v[28:31], v[128:131], v[200:203], v[28:31]
	v_mfma_f32_16x16x32_bf16 v[24:27], v[160:163], v[200:203], v[24:27]
	v_mfma_f32_16x16x32_bf16 v[12:15], v[128:131], v[228:231], v[12:15]
	v_mfma_f32_16x16x32_bf16 v[8:11], v[160:163], v[228:231], v[8:11]
	v_mfma_f32_16x16x32_bf16 v[60:63], v[132:135], v[188:191], v[60:63]
	v_mfma_f32_16x16x32_bf16 v[56:59], v[164:167], v[188:191], v[56:59]
	v_mfma_f32_16x16x32_bf16 v[44:47], v[132:135], v[196:199], v[44:47]
	v_mfma_f32_16x16x32_bf16 v[40:43], v[164:167], v[196:199], v[40:43]
	v_mfma_f32_16x16x32_bf16 v[28:31], v[132:135], v[224:227], v[28:31]
	v_mfma_f32_16x16x32_bf16 v[24:27], v[164:167], v[224:227], v[24:27]
	v_mfma_f32_16x16x32_bf16 v[12:15], v[132:135], v[234:237], v[12:15]
	v_mfma_f32_16x16x32_bf16 v[8:11], v[164:167], v[234:237], v[8:11]
	s_setprio 0
	s_setprio 1
	v_mfma_f32_16x16x32_bf16 v[52:55], v[168:171], v[184:187], v[52:55]
	v_mfma_f32_16x16x32_bf16 v[48:51], v[176:179], v[184:187], v[48:51]
	v_mfma_f32_16x16x32_bf16 v[36:39], v[168:171], v[192:195], v[36:39]
	v_mfma_f32_16x16x32_bf16 v[32:35], v[176:179], v[192:195], v[32:35]
	v_mfma_f32_16x16x32_bf16 v[20:23], v[168:171], v[200:203], v[20:23]
	v_mfma_f32_16x16x32_bf16 v[16:19], v[176:179], v[200:203], v[16:19]
	v_mfma_f32_16x16x32_bf16 v[4:7], v[168:171], v[228:231], v[4:7]
	v_mfma_f32_16x16x32_bf16 v[0:3], v[176:179], v[228:231], v[0:3]
	v_mfma_f32_16x16x32_bf16 v[52:55], v[172:175], v[188:191], v[52:55]
	v_mfma_f32_16x16x32_bf16 v[48:51], v[180:183], v[188:191], v[48:51]
	v_mfma_f32_16x16x32_bf16 v[36:39], v[172:175], v[196:199], v[36:39]
	v_mfma_f32_16x16x32_bf16 v[32:35], v[180:183], v[196:199], v[32:35]
	v_mfma_f32_16x16x32_bf16 v[20:23], v[172:175], v[224:227], v[20:23]
	v_mfma_f32_16x16x32_bf16 v[16:19], v[180:183], v[224:227], v[16:19]
	v_mfma_f32_16x16x32_bf16 v[4:7], v[172:175], v[234:237], v[4:7]
	v_mfma_f32_16x16x32_bf16 v[0:3], v[180:183], v[234:237], v[0:3]
	s_setprio 0
	s_barrier
	s_add_u32 s4, s4, 0x100
	s_addc_u32 s5, s5, 0
	s_add_u32 s3, s3, 0x100
	s_addc_u32 s14, s14, 0
	s_cmp_ge_i32 s15, s70
	s_mov_b32 s12, s15
	s_cbranch_scc0 .LBB0_508
	v_readlane_b32 s79, v254, 40
	s_mov_b32 s80, 0xf800000

; #define PG8_STAGE(bufoff, gbase, voff) do { _Pragma("unroll") for (int _i = 0; _i < 2; ++_i) \
;         __builtin_amdgcn_global_load_lds((const unsigned*)((const char*)(gbase) + (voff)[_i]), (PG8_LAS unsigned*)(lds + (bufoff) + ldsw + _i * 8192), 16, 0, 0); } while (0)
; #define PG8_LDA(dst, b, h) do { _Pragma("unroll") for (int m = 0; m < 4; ++m) _Pragma("unroll") for (int k = 0; k < 2; ++k) dst[m][k] = *(const PG8_LAS bf16x8*)(lds + PG8_SA(b, h) + aoff + m * 2048 + k * 1024); } while (0)
; #define PG8_WAIT_V(n) asm volatile("s_waitcnt vmcnt(" #n ")" ::: "memory")
; template <class Epi, class Sched, bool ALIGN_EPI = false, bool SP2 = false>
; __device__ __forceinline__ void gemm_phase(PG8_LAS unsigned char* lds, const Gemm g, const Sched& S, const Epi& E, const int tid) {
;     ...
;         for (int t = 0; t < nt; t += 2) {
;             if constexpr (Epi::KHOOK) { if (t == 8 || t == 16) E.khook(acc, cur, t, wr, wc, fr, fq); }
;             const bool last = (t == nt - 2);
;             const char* a1 = cA + (size_t)(t + 1) * kstep;
;             const char* a2 = last ? nA : cA + (size_t)(t + 2) * kstep; const char* b2 = last ? nB : cB + (size_t)(t + 2) * kstep;
;             const char* a3 = a2 + kstep; const char* b3 = b2 + kstep;
;             if (last && has_next) S.a_ready(nxt);
;             if constexpr (SP2) {
;             PG8_LDB(B0, 0, 0); PG8_LDB(B1, 0, 1); PG8_SCHED; PG8_LDA(At, 0, 0); PG8_STAGE(PG8_SA(1, 1), a1 + hstepA, voffA);
;             PG8_WAIT_V(8); PG8_WAIT_L(0); PG8_BAR; PG8_MMA(0, 0, At, B0); PG8_MMA(0, 1, At, B1); PG8_BAR; PG8_SCHED;
;             PG8_LDA(At, 0, 1); PG8_STAGE(PG8_SB(0, 0), b2, voffB); PG8_STAGE(PG8_SB(0, 1), b2 + hstepB, voffB); PG8_STAGE(PG8_SA(0, 0), a2, voffA);
;             PG8_WAIT_V(8); PG8_WAIT_L(0); PG8_BAR; PG8_MMA(1, 0, At, B0); PG8_MMA(1, 1, At, B1); PG8_BAR; PG8_SCHED;
;             PG8_LDB(B0, 1, 0); PG8_LDB(B1, 1, 1); PG8_SCHED; PG8_LDA(At, 1, 0); PG8_STAGE(PG8_SA(0, 1), a2 + hstepA, voffA);
;             PG8_WAIT_V(8); PG8_WAIT_L(0); PG8_BAR; PG8_MMA(0, 0, At, B0); PG8_MMA(0, 1, At, B1); PG8_BAR; PG8_SCHED;
;             PG8_LDA(At, 1, 1); PG8_STAGE(PG8_SB(1, 0), b3, voffB); PG8_STAGE(PG8_SB(1, 1), b3 + hstepB, voffB); PG8_STAGE(PG8_SA(1, 0), a3, voffA);
;             PG8_WAIT_V(8); PG8_WAIT_L(0); PG8_BAR; PG8_MMA(1, 0, At, B0); PG8_MMA(1, 1, At, B1); PG8_BAR; PG8_SCHED;
.LBB0_745:
	s_add_i32 s42, s8, 2
	s_add_u32 s43, s4, 0x80
	s_addc_u32 s9, s5, 0
	s_add_i32 s69, 0, 0x10000
	s_cmp_eq_u32 s64, s8
	s_cselect_b32 s9, s39, s9
	s_cselect_b32 s8, s38, s43
	v_add_u32_e32 v140, s69, v157
	s_cselect_b32 s71, s41, s11
	s_cselect_b32 s70, s40, s10
	s_add_i32 s43, 0, 0x14000
	ds_read_b128 v[150:153], v140
	ds_read_b128 v[158:161], v140 offset:1024
	ds_read_b128 v[164:167], v140 offset:2048
	ds_read_b128 v[170:173], v140 offset:3072
	v_add_u32_e32 v140, s43, v157
	ds_read_b128 v[174:177], v140
	ds_read_b128 v[178:181], v140 offset:1024
	ds_read_b128 v[182:185], v140 offset:2048
	ds_read_b128 v[186:189], v140 offset:3072
	s_add_i32 m0, s57, 0xc000
	ds_read_b128 v[190:193], v169
	ds_read_b128 v[194:197], v169 offset:1024
	ds_read_b128 v[198:201], v169 offset:2048
	ds_read_b128 v[202:205], v169 offset:3072
	ds_read_b128 v[216:219], v169 offset:4096
	ds_read_b128 v[220:223], v169 offset:5120
	ds_read_b128 v[224:227], v169 offset:6144
	ds_read_b128 v[228:231], v169 offset:7168
	global_load_lds_dwordx4 v136, s[4:5]
	s_add_i32 m0, s57, 0xe000
	s_nop 0
	global_load_lds_dwordx4 v138, s[4:5]
	s_waitcnt vmcnt(8)
	s_waitcnt lgkmcnt(0)
	s_barrier
	s_setprio 1
	s_waitcnt lgkmcnt(0)
	v_mfma_f32_16x16x32_bf16 v[124:127], v[150:153], v[190:193], v[124:127]
	v_mfma_f32_16x16x32_bf16 v[120:123], v[164:167], v[190:193], v[120:123]
	v_mfma_f32_16x16x32_bf16 v[116:119], v[150:153], v[198:201], v[116:119]
	v_mfma_f32_16x16x32_bf16 v[112:115], v[164:167], v[198:201], v[112:115]
	v_mfma_f32_16x16x32_bf16 v[108:111], v[150:153], v[216:219], v[108:111]
	v_mfma_f32_16x16x32_bf16 v[104:107], v[164:167], v[216:219], v[104:107]
	v_mfma_f32_16x16x32_bf16 v[100:103], v[150:153], v[224:227], v[100:103]
	v_mfma_f32_16x16x32_bf16 v[96:99], v[164:167], v[224:227], v[96:99]
	v_mfma_f32_16x16x32_bf16 v[124:127], v[158:161], v[194:197], v[124:127]
	v_mfma_f32_16x16x32_bf16 v[120:123], v[170:173], v[194:197], v[120:123]
	v_mfma_f32_16x16x32_bf16 v[116:119], v[158:161], v[202:205], v[116:119]
	v_mfma_f32_16x16x32_bf16 v[112:115], v[170:173], v[202:205], v[112:115]
	v_mfma_f32_16x16x32_bf16 v[108:111], v[158:161], v[220:223], v[108:111]
	v_mfma_f32_16x16x32_bf16 v[104:107], v[170:173], v[220:223], v[104:107]
	v_mfma_f32_16x16x32_bf16 v[100:103], v[158:161], v[228:231], v[100:103]
	v_mfma_f32_16x16x32_bf16 v[96:99], v[170:173], v[228:231], v[96:99]
	s_setprio 0
	s_setprio 1
	v_mfma_f32_16x16x32_bf16 v[60:63], v[174:177], v[190:193], v[60:63]
	v_mfma_f32_16x16x32_bf16 v[56:59], v[182:185], v[190:193], v[56:59]
	v_mfma_f32_16x16x32_bf16 v[52:55], v[174:177], v[198:201], v[52:55]
	v_mfma_f32_16x16x32_bf16 v[48:51], v[182:185], v[198:201], v[48:51]
	v_mfma_f32_16x16x32_bf16 v[44:47], v[174:177], v[216:219], v[44:47]
	v_mfma_f32_16x16x32_bf16 v[40:43], v[182:185], v[216:219], v[40:43]
	v_mfma_f32_16x16x32_bf16 v[36:39], v[174:177], v[224:227], v[36:39]
	v_mfma_f32_16x16x32_bf16 v[32:35], v[182:185], v[224:227], v[32:35]
	v_mfma_f32_16x16x32_bf16 v[60:63], v[178:181], v[194:197], v[60:63]
	v_mfma_f32_16x16x32_bf16 v[56:59], v[186:189], v[194:197], v[56:59]
	v_mfma_f32_16x16x32_bf16 v[52:55], v[178:181], v[202:205], v[52:55]
	v_mfma_f32_16x16x32_bf16 v[48:51], v[186:189], v[202:205], v[48:51]
	v_mfma_f32_16x16x32_bf16 v[44:47], v[178:181], v[220:223], v[44:47]
	v_mfma_f32_16x16x32_bf16 v[40:43], v[186:189], v[220:223], v[40:43]
	v_mfma_f32_16x16x32_bf16 v[36:39], v[178:181], v[228:231], v[36:39]
	v_mfma_f32_16x16x32_bf16 v[32:35], v[186:189], v[228:231], v[32:35]
	s_setprio 0
	s_barrier
	s_add_i32 s69, s69, s52
	v_lshl_add_u64 v[140:141], s[70:71], 0, v[130:131]
	s_mov_b32 m0, s69
	ds_read_b128 v[190:193], v169 offset:16384
	ds_read_b128 v[194:197], v169 offset:17408
	ds_read_b128 v[198:201], v169 offset:18432
	ds_read_b128 v[202:205], v169 offset:19456
	ds_read_b128 v[216:219], v169 offset:20480
	ds_read_b128 v[220:223], v169 offset:21504
	ds_read_b128 v[224:227], v169 offset:22528
	ds_read_b128 v[228:231], v169 offset:23552
	global_load_lds_dwordx4 v[140:141], off
	s_add_i32 m0, s69, 0x2000
	v_lshl_add_u64 v[144:145], s[70:71], 0, v[134:135]
	s_add_u32 s70, s70, s18
	s_addc_u32 s71, s71, s19
	s_add_i32 s43, s43, s52
	global_load_lds_dwordx4 v[144:145], off
	v_lshl_add_u64 v[154:155], s[70:71], 0, v[130:131]
	s_mov_b32 m0, s43
	v_lshl_add_u64 v[234:235], s[70:71], 0, v[134:135]
	global_load_lds_dwordx4 v[154:155], off
	s_add_i32 m0, s43, 0x2000
	v_lshl_add_u64 v[236:237], s[8:9], 0, v[128:129]
	global_load_lds_dwordx4 v[234:235], off
	s_mov_b32 m0, s57
	v_lshl_add_u64 v[238:239], s[8:9], 0, v[132:133]
	global_load_lds_dwordx4 v[236:237], off
	s_mov_b32 m0, s58
	s_nop 0
	global_load_lds_dwordx4 v[238:239], off
	s_waitcnt vmcnt(8)
	s_waitcnt lgkmcnt(0)
	s_barrier
; #define PG8_STAGE(bufoff, gbase, voff) do { _Pragma("unroll") for (int _i = 0; _i < 2; ++_i) \
;         __builtin_amdgcn_global_load_lds((const unsigned*)((const char*)(gbase) + (voff)[_i]), (PG8_LAS unsigned*)(lds + (bufoff) + ldsw + _i * 8192), 16, 0, 0); } while (0)
; #define PG8_LDA(dst, b, h) do { _Pragma("unroll") for (int m = 0; m < 4; ++m) _Pragma("unroll") for (int k = 0; k < 2; ++k) dst[m][k] = *(const PG8_LAS bf16x8*)(lds + PG8_SA(b, h) + aoff + m * 2048 + k * 1024); } while (0)
; #define PG8_WAIT_V(n) asm volatile("s_waitcnt vmcnt(" #n ")" ::: "memory")
; template <class Epi, class Sched, bool ALIGN_EPI = false, bool SP2 = false>
; __device__ __forceinline__ void gemm_phase(PG8_LAS unsigned char* lds, const Gemm g, const Sched& S, const Epi& E, const int tid) {
;     ...
;         for (int t = 0; t < nt; t += 2) {
;             if constexpr (Epi::KHOOK) { if (t == 8 || t == 16) E.khook(acc, cur, t, wr, wc, fr, fq); }
;             const bool last = (t == nt - 2);
;             const char* a1 = cA + (size_t)(t + 1) * kstep;
;             const char* a2 = last ? nA : cA + (size_t)(t + 2) * kstep; const char* b2 = last ? nB : cB + (size_t)(t + 2) * kstep;
;             const char* a3 = a2 + kstep; const char* b3 = b2 + kstep;
;             if (last && has_next) S.a_ready(nxt);
;             if constexpr (SP2) {
;             PG8_LDB(B0, 0, 0); PG8_LDB(B1, 0, 1); PG8_SCHED; PG8_LDA(At, 0, 0); PG8_STAGE(PG8_SA(1, 1), a1 + hstepA, voffA);
;             PG8_WAIT_V(8); PG8_WAIT_L(0); PG8_BAR; PG8_MMA(0, 0, At, B0); PG8_MMA(0, 1, At, B1); PG8_BAR; PG8_SCHED;
;             PG8_LDA(At, 0, 1); PG8_STAGE(PG8_SB(0, 0), b2, voffB); PG8_STAGE(PG8_SB(0, 1), b2 + hstepB, voffB); PG8_STAGE(PG8_SA(0, 0), a2, voffA);
;             PG8_WAIT_V(8); PG8_WAIT_L(0); PG8_BAR; PG8_MMA(1, 0, At, B0); PG8_MMA(1, 1, At, B1); PG8_BAR; PG8_SCHED;
;             PG8_LDB(B0, 1, 0); PG8_LDB(B1, 1, 1); PG8_SCHED; PG8_LDA(At, 1, 0); PG8_STAGE(PG8_SA(0, 1), a2 + hstepA, voffA);
;             PG8_WAIT_V(8); PG8_WAIT_L(0); PG8_BAR; PG8_MMA(0, 0, At, B0); PG8_MMA(0, 1, At, B1); PG8_BAR; PG8_SCHED;
;             PG8_LDA(At, 1, 1); PG8_STAGE(PG8_SB(1, 0), b3, voffB); PG8_STAGE(PG8_SB(1, 1), b3 + hstepB, voffB); PG8_STAGE(PG8_SA(1, 0), a3, voffA);
;             PG8_WAIT_V(8); PG8_WAIT_L(0); PG8_BAR; PG8_MMA(1, 0, At, B0); PG8_MMA(1, 1, At, B1); PG8_BAR; PG8_SCHED;
	s_setprio 1
	s_waitcnt lgkmcnt(0)
	v_mfma_f32_16x16x32_bf16 v[92:95], v[150:153], v[190:193], v[92:95]
	v_mfma_f32_16x16x32_bf16 v[88:91], v[164:167], v[190:193], v[88:91]
	v_mfma_f32_16x16x32_bf16 v[84:87], v[150:153], v[198:201], v[84:87]
	v_mfma_f32_16x16x32_bf16 v[80:83], v[164:167], v[198:201], v[80:83]
	v_mfma_f32_16x16x32_bf16 v[76:79], v[150:153], v[216:219], v[76:79]
	v_mfma_f32_16x16x32_bf16 v[72:75], v[164:167], v[216:219], v[72:75]
	v_mfma_f32_16x16x32_bf16 v[68:71], v[150:153], v[224:227], v[68:71]
	v_mfma_f32_16x16x32_bf16 v[64:67], v[164:167], v[224:227], v[64:67]
	v_mfma_f32_16x16x32_bf16 v[92:95], v[158:161], v[194:197], v[92:95]
	v_mfma_f32_16x16x32_bf16 v[88:91], v[170:173], v[194:197], v[88:91]
	v_mfma_f32_16x16x32_bf16 v[84:87], v[158:161], v[202:205], v[84:87]
	v_mfma_f32_16x16x32_bf16 v[80:83], v[170:173], v[202:205], v[80:83]
	v_mfma_f32_16x16x32_bf16 v[76:79], v[158:161], v[220:223], v[76:79]
	v_mfma_f32_16x16x32_bf16 v[72:75], v[170:173], v[220:223], v[72:75]
	v_mfma_f32_16x16x32_bf16 v[68:71], v[158:161], v[228:231], v[68:71]
	v_mfma_f32_16x16x32_bf16 v[64:67], v[170:173], v[228:231], v[64:67]
	s_setprio 0
	s_setprio 1
	v_mfma_f32_16x16x32_bf16 v[28:31], v[174:177], v[190:193], v[28:31]
	v_mfma_f32_16x16x32_bf16 v[24:27], v[182:185], v[190:193], v[24:27]
	v_mfma_f32_16x16x32_bf16 v[20:23], v[174:177], v[198:201], v[20:23]
	v_mfma_f32_16x16x32_bf16 v[16:19], v[182:185], v[198:201], v[16:19]
	v_mfma_f32_16x16x32_bf16 v[12:15], v[174:177], v[216:219], v[12:15]
	v_mfma_f32_16x16x32_bf16 v[8:11], v[182:185], v[216:219], v[8:11]
	v_mfma_f32_16x16x32_bf16 v[4:7], v[174:177], v[224:227], v[4:7]
	v_mfma_f32_16x16x32_bf16 v[0:3], v[182:185], v[224:227], v[0:3]
	v_mfma_f32_16x16x32_bf16 v[28:31], v[178:181], v[194:197], v[28:31]
	v_mfma_f32_16x16x32_bf16 v[24:27], v[186:189], v[194:197], v[24:27]
	v_mfma_f32_16x16x32_bf16 v[20:23], v[178:181], v[202:205], v[20:23]
	v_mfma_f32_16x16x32_bf16 v[16:19], v[186:189], v[202:205], v[16:19]
	v_mfma_f32_16x16x32_bf16 v[12:15], v[178:181], v[220:223], v[12:15]
	v_mfma_f32_16x16x32_bf16 v[8:11], v[186:189], v[220:223], v[8:11]
	v_mfma_f32_16x16x32_bf16 v[4:7], v[178:181], v[228:231], v[4:7]
	v_mfma_f32_16x16x32_bf16 v[0:3], v[186:189], v[228:231], v[0:3]
	s_setprio 0
	s_barrier
	s_add_i32 s43, 0, 0x18000
	v_add_u32_e32 v142, s43, v157
	s_add_i32 s69, 0, 0x1c000
	ds_read_b128 v[150:153], v142
	ds_read_b128 v[158:161], v142 offset:1024
	ds_read_b128 v[164:167], v142 offset:2048
	ds_read_b128 v[170:173], v142 offset:3072
	v_add_u32_e32 v142, s69, v157
	ds_read_b128 v[174:177], v142
	ds_read_b128 v[178:181], v142 offset:1024
	ds_read_b128 v[182:185], v142 offset:2048
	ds_read_b128 v[186:189], v142 offset:3072
	s_add_u32 s8, s8, s16
	s_addc_u32 s9, s9, s17
	s_mov_b32 m0, s59
	ds_read_b128 v[190:193], v169 offset:32768
	ds_read_b128 v[194:197], v169 offset:33792
	ds_read_b128 v[198:201], v169 offset:34816
	ds_read_b128 v[202:205], v169 offset:35840
	ds_read_b128 v[216:219], v169 offset:36864
	ds_read_b128 v[220:223], v169 offset:37888
	ds_read_b128 v[224:227], v169 offset:38912
	ds_read_b128 v[228:231], v169 offset:39936
	global_load_lds_dwordx4 v128, s[8:9]
	s_mov_b32 m0, s60
	s_nop 0
	global_load_lds_dwordx4 v132, s[8:9]
	s_waitcnt vmcnt(8)
	s_waitcnt lgkmcnt(0)
	s_barrier
	s_setprio 1
	s_waitcnt lgkmcnt(0)
	v_mfma_f32_16x16x32_bf16 v[124:127], v[150:153], v[190:193], v[124:127]
	v_mfma_f32_16x16x32_bf16 v[120:123], v[164:167], v[190:193], v[120:123]
	v_mfma_f32_16x16x32_bf16 v[116:119], v[150:153], v[198:201], v[116:119]
	v_mfma_f32_16x16x32_bf16 v[112:115], v[164:167], v[198:201], v[112:115]
	v_mfma_f32_16x16x32_bf16 v[108:111], v[150:153], v[216:219], v[108:111]
	v_mfma_f32_16x16x32_bf16 v[104:107], v[164:167], v[216:219], v[104:107]
	v_mfma_f32_16x16x32_bf16 v[100:103], v[150:153], v[224:227], v[100:103]
	v_mfma_f32_16x16x32_bf16 v[96:99], v[164:167], v[224:227], v[96:99]
	v_mfma_f32_16x16x32_bf16 v[124:127], v[158:161], v[194:197], v[124:127]
	v_mfma_f32_16x16x32_bf16 v[120:123], v[170:173], v[194:197], v[120:123]
	v_mfma_f32_16x16x32_bf16 v[116:119], v[158:161], v[202:205], v[116:119]
	v_mfma_f32_16x16x32_bf16 v[112:115], v[170:173], v[202:205], v[112:115]
	v_mfma_f32_16x16x32_bf16 v[108:111], v[158:161], v[220:223], v[108:111]
	v_mfma_f32_16x16x32_bf16 v[104:107], v[170:173], v[220:223], v[104:107]
	v_mfma_f32_16x16x32_bf16 v[100:103], v[158:161], v[228:231], v[100:103]
	v_mfma_f32_16x16x32_bf16 v[96:99], v[170:173], v[228:231], v[96:99]
	s_setprio 0
	s_setprio 1
	v_mfma_f32_16x16x32_bf16 v[60:63], v[174:177], v[190:193], v[60:63]
	v_mfma_f32_16x16x32_bf16 v[56:59], v[182:185], v[190:193], v[56:59]
	v_mfma_f32_16x16x32_bf16 v[52:55], v[174:177], v[198:201], v[52:55]
	v_mfma_f32_16x16x32_bf16 v[48:51], v[182:185], v[198:201], v[48:51]
	v_mfma_f32_16x16x32_bf16 v[44:47], v[174:177], v[216:219], v[44:47]
	v_mfma_f32_16x16x32_bf16 v[40:43], v[182:185], v[216:219], v[40:43]
	v_mfma_f32_16x16x32_bf16 v[36:39], v[174:177], v[224:227], v[36:39]
	v_mfma_f32_16x16x32_bf16 v[32:35], v[182:185], v[224:227], v[32:35]
	v_mfma_f32_16x16x32_bf16 v[60:63], v[178:181], v[194:197], v[60:63]
	v_mfma_f32_16x16x32_bf16 v[56:59], v[186:189], v[194:197], v[56:59]
	v_mfma_f32_16x16x32_bf16 v[52:55], v[178:181], v[202:205], v[52:55]
	v_mfma_f32_16x16x32_bf16 v[48:51], v[186:189], v[202:205], v[48:51]
	v_mfma_f32_16x16x32_bf16 v[44:47], v[178:181], v[220:223], v[44:47]
	v_mfma_f32_16x16x32_bf16 v[40:43], v[186:189], v[220:223], v[40:43]
	v_mfma_f32_16x16x32_bf16 v[36:39], v[178:181], v[228:231], v[36:39]
	v_mfma_f32_16x16x32_bf16 v[32:35], v[186:189], v[228:231], v[32:35]
	s_setprio 0
	s_barrier
; #define PG8_STAGE(bufoff, gbase, voff) do { _Pragma("unroll") for (int _i = 0; _i < 2; ++_i) \
;         __builtin_amdgcn_global_load_lds((const unsigned*)((const char*)(gbase) + (voff)[_i]), (PG8_LAS unsigned*)(lds + (bufoff) + ldsw + _i * 8192), 16, 0, 0); } while (0)
; #define PG8_LDA(dst, b, h) do { _Pragma("unroll") for (int m = 0; m < 4; ++m) _Pragma("unroll") for (int k = 0; k < 2; ++k) dst[m][k] = *(const PG8_LAS bf16x8*)(lds + PG8_SA(b, h) + aoff + m * 2048 + k * 1024); } while (0)
; #define PG8_WAIT_V(n) asm volatile("s_waitcnt vmcnt(" #n ")" ::: "memory")
; template <class Epi, class Sched, bool ALIGN_EPI = false, bool SP2 = false>
; __device__ __forceinline__ void gemm_phase(PG8_LAS unsigned char* lds, const Gemm g, const Sched& S, const Epi& E, const int tid) {
;     ...
;         for (int t = 0; t < nt; t += 2) {
;             if constexpr (Epi::KHOOK) { if (t == 8 || t == 16) E.khook(acc, cur, t, wr, wc, fr, fq); }
;             const bool last = (t == nt - 2);
;             const char* a1 = cA + (size_t)(t + 1) * kstep;
;             const char* a2 = last ? nA : cA + (size_t)(t + 2) * kstep; const char* b2 = last ? nB : cB + (size_t)(t + 2) * kstep;
;             const char* a3 = a2 + kstep; const char* b3 = b2 + kstep;
;             if (last && has_next) S.a_ready(nxt);
;             if constexpr (SP2) {
;             PG8_LDB(B0, 0, 0); PG8_LDB(B1, 0, 1); PG8_SCHED; PG8_LDA(At, 0, 0); PG8_STAGE(PG8_SA(1, 1), a1 + hstepA, voffA);
;             PG8_WAIT_V(8); PG8_WAIT_L(0); PG8_BAR; PG8_MMA(0, 0, At, B0); PG8_MMA(0, 1, At, B1); PG8_BAR; PG8_SCHED;
;             PG8_LDA(At, 0, 1); PG8_STAGE(PG8_SB(0, 0), b2, voffB); PG8_STAGE(PG8_SB(0, 1), b2 + hstepB, voffB); PG8_STAGE(PG8_SA(0, 0), a2, voffA);
;             PG8_WAIT_V(8); PG8_WAIT_L(0); PG8_BAR; PG8_MMA(1, 0, At, B0); PG8_MMA(1, 1, At, B1); PG8_BAR; PG8_SCHED;
;             PG8_LDB(B0, 1, 0); PG8_LDB(B1, 1, 1); PG8_SCHED; PG8_LDA(At, 1, 0); PG8_STAGE(PG8_SA(0, 1), a2 + hstepA, voffA);
;             PG8_WAIT_V(8); PG8_WAIT_L(0); PG8_BAR; PG8_MMA(0, 0, At, B0); PG8_MMA(0, 1, At, B1); PG8_BAR; PG8_SCHED;
;             PG8_LDA(At, 1, 1); PG8_STAGE(PG8_SB(1, 0), b3, voffB); PG8_STAGE(PG8_SB(1, 1), b3 + hstepB, voffB); PG8_STAGE(PG8_SA(1, 0), a3, voffA);
;             PG8_WAIT_V(8); PG8_WAIT_L(0); PG8_BAR; PG8_MMA(1, 0, At, B0); PG8_MMA(1, 1, At, B1); PG8_BAR; PG8_SCHED;
	s_add_i32 s8, s43, s52
	s_add_i32 m0, s8, 0xffffff80
	ds_read_b128 v[190:193], v169 offset:49152
	ds_read_b128 v[194:197], v169 offset:50176
	ds_read_b128 v[198:201], v169 offset:51200
	ds_read_b128 v[202:205], v169 offset:52224
	ds_read_b128 v[216:219], v169 offset:53248
	ds_read_b128 v[220:223], v169 offset:54272
	ds_read_b128 v[224:227], v169 offset:55296
	ds_read_b128 v[228:231], v169 offset:56320
	global_load_lds_dwordx4 v[140:141], off offset:128
	s_add_i32 m0, s8, 0x1f80
	s_add_i32 s8, s69, s52
	global_load_lds_dwordx4 v[144:145], off offset:128
	s_add_i32 m0, s8, 0xffffff80
	s_nop 0
	global_load_lds_dwordx4 v[154:155], off offset:128
	s_add_i32 m0, s8, 0x1f80
	s_nop 0
	global_load_lds_dwordx4 v[234:235], off offset:128
	s_add_i32 m0, s62, 0xffffff80
	s_nop 0
	global_load_lds_dwordx4 v[236:237], off offset:128
	s_add_i32 m0, s63, 0xffffff80
	s_nop 0
	global_load_lds_dwordx4 v[238:239], off offset:128
	s_waitcnt vmcnt(8)
	s_waitcnt lgkmcnt(0)
	s_barrier
	s_setprio 1
	s_waitcnt lgkmcnt(0)
	v_mfma_f32_16x16x32_bf16 v[92:95], v[150:153], v[190:193], v[92:95]
	v_mfma_f32_16x16x32_bf16 v[88:91], v[164:167], v[190:193], v[88:91]
	v_mfma_f32_16x16x32_bf16 v[84:87], v[150:153], v[198:201], v[84:87]
	v_mfma_f32_16x16x32_bf16 v[80:83], v[164:167], v[198:201], v[80:83]
	v_mfma_f32_16x16x32_bf16 v[76:79], v[150:153], v[216:219], v[76:79]
	v_mfma_f32_16x16x32_bf16 v[72:75], v[164:167], v[216:219], v[72:75]
	v_mfma_f32_16x16x32_bf16 v[68:71], v[150:153], v[224:227], v[68:71]
	v_mfma_f32_16x16x32_bf16 v[64:67], v[164:167], v[224:227], v[64:67]
	v_mfma_f32_16x16x32_bf16 v[92:95], v[158:161], v[194:197], v[92:95]
	v_mfma_f32_16x16x32_bf16 v[88:91], v[170:173], v[194:197], v[88:91]
	v_mfma_f32_16x16x32_bf16 v[84:87], v[158:161], v[202:205], v[84:87]
	v_mfma_f32_16x16x32_bf16 v[80:83], v[170:173], v[202:205], v[80:83]
	v_mfma_f32_16x16x32_bf16 v[76:79], v[158:161], v[220:223], v[76:79]
	v_mfma_f32_16x16x32_bf16 v[72:75], v[170:173], v[220:223], v[72:75]
	v_mfma_f32_16x16x32_bf16 v[68:71], v[158:161], v[228:231], v[68:71]
	v_mfma_f32_16x16x32_bf16 v[64:67], v[170:173], v[228:231], v[64:67]
	s_setprio 0
	s_setprio 1
	v_mfma_f32_16x16x32_bf16 v[28:31], v[174:177], v[190:193], v[28:31]
	v_mfma_f32_16x16x32_bf16 v[24:27], v[182:185], v[190:193], v[24:27]
	v_mfma_f32_16x16x32_bf16 v[20:23], v[174:177], v[198:201], v[20:23]
	v_mfma_f32_16x16x32_bf16 v[16:19], v[182:185], v[198:201], v[16:19]
	v_mfma_f32_16x16x32_bf16 v[12:15], v[174:177], v[216:219], v[12:15]
	v_mfma_f32_16x16x32_bf16 v[8:11], v[182:185], v[216:219], v[8:11]
	v_mfma_f32_16x16x32_bf16 v[4:7], v[174:177], v[224:227], v[4:7]
	v_mfma_f32_16x16x32_bf16 v[0:3], v[182:185], v[224:227], v[0:3]
	v_mfma_f32_16x16x32_bf16 v[28:31], v[178:181], v[194:197], v[28:31]
	v_mfma_f32_16x16x32_bf16 v[24:27], v[186:189], v[194:197], v[24:27]
	v_mfma_f32_16x16x32_bf16 v[20:23], v[178:181], v[202:205], v[20:23]
	v_mfma_f32_16x16x32_bf16 v[16:19], v[186:189], v[202:205], v[16:19]
	v_mfma_f32_16x16x32_bf16 v[12:15], v[178:181], v[220:223], v[12:15]
	v_mfma_f32_16x16x32_bf16 v[8:11], v[186:189], v[220:223], v[8:11]
	v_mfma_f32_16x16x32_bf16 v[4:7], v[178:181], v[228:231], v[4:7]
	v_mfma_f32_16x16x32_bf16 v[0:3], v[186:189], v[228:231], v[0:3]
	s_setprio 0
	s_barrier
	s_add_u32 s4, s4, 0x100
	s_addc_u32 s5, s5, 0
	s_add_u32 s10, s10, 0x100
	s_addc_u32 s11, s11, 0
	s_cmp_ge_i32 s42, s61
	s_mov_b32 s8, s42
	s_cbranch_scc0 .LBB0_745

; #define PG8_STAGE(bufoff, gbase, voff) do { _Pragma("unroll") for (int _i = 0; _i < 2; ++_i) \
;         __builtin_amdgcn_global_load_lds((const unsigned*)((const char*)(gbase) + (voff)[_i]), (PG8_LAS unsigned*)(lds + (bufoff) + ldsw + _i * 8192), 16, 0, 0); } while (0)
; #define PG8_LDA(dst, b, h) do { _Pragma("unroll") for (int m = 0; m < 4; ++m) _Pragma("unroll") for (int k = 0; k < 2; ++k) dst[m][k] = *(const PG8_LAS bf16x8*)(lds + PG8_SA(b, h) + aoff + m * 2048 + k * 1024); } while (0)
; #define PG8_WAIT_V(n) asm volatile("s_waitcnt vmcnt(" #n ")" ::: "memory")
; template <class Epi, class Sched, bool ALIGN_EPI = false, bool SP2 = false>
; __device__ __forceinline__ void gemm_phase(PG8_LAS unsigned char* lds, const Gemm g, const Sched& S, const Epi& E, const int tid) {
;     ...
;         for (int t = 0; t < nt; t += 2) {
;             if constexpr (Epi::KHOOK) { if (t == 8 || t == 16) E.khook(acc, cur, t, wr, wc, fr, fq); }
;             const bool last = (t == nt - 2);
;             const char* a1 = cA + (size_t)(t + 1) * kstep;
;             const char* a2 = last ? nA : cA + (size_t)(t + 2) * kstep; const char* b2 = last ? nB : cB + (size_t)(t + 2) * kstep;
;             const char* a3 = a2 + kstep; const char* b3 = b2 + kstep;
;             if (last && has_next) S.a_ready(nxt);
;             if constexpr (SP2) {
;             PG8_LDB(B0, 0, 0); PG8_LDB(B1, 0, 1); PG8_SCHED; PG8_LDA(At, 0, 0); PG8_STAGE(PG8_SA(1, 1), a1 + hstepA, voffA);
;             PG8_WAIT_V(8); PG8_WAIT_L(0); PG8_BAR; PG8_MMA(0, 0, At, B0); PG8_MMA(0, 1, At, B1); PG8_BAR; PG8_SCHED;
;             PG8_LDA(At, 0, 1); PG8_STAGE(PG8_SB(0, 0), b2, voffB); PG8_STAGE(PG8_SB(0, 1), b2 + hstepB, voffB); PG8_STAGE(PG8_SA(0, 0), a2, voffA);
;             PG8_WAIT_V(8); PG8_WAIT_L(0); PG8_BAR; PG8_MMA(1, 0, At, B0); PG8_MMA(1, 1, At, B1); PG8_BAR; PG8_SCHED;
;             PG8_LDB(B0, 1, 0); PG8_LDB(B1, 1, 1); PG8_SCHED; PG8_LDA(At, 1, 0); PG8_STAGE(PG8_SA(0, 1), a2 + hstepA, voffA);
;             PG8_WAIT_V(8); PG8_WAIT_L(0); PG8_BAR; PG8_MMA(0, 0, At, B0); PG8_MMA(0, 1, At, B1); PG8_BAR; PG8_SCHED;
;             PG8_LDA(At, 1, 1); PG8_STAGE(PG8_SB(1, 0), b3, voffB); PG8_STAGE(PG8_SB(1, 1), b3 + hstepB, voffB); PG8_STAGE(PG8_SA(1, 0), a3, voffA);
;             PG8_WAIT_V(8); PG8_WAIT_L(0); PG8_BAR; PG8_MMA(1, 0, At, B0); PG8_MMA(1, 1, At, B1); PG8_BAR; PG8_SCHED;
.LBB0_817:
	s_add_i32 s12, s8, 2
	s_add_u32 s13, s4, 0x80
	s_addc_u32 s9, s5, 0
	s_add_i32 s80, 0, 0x10000
	s_cmp_eq_u32 s73, s8
	s_cselect_b32 s9, s51, s9
	s_cselect_b32 s8, s50, s13
	v_add_u32_e32 v146, s80, v153
	s_cselect_b32 s79, s53, s11
	s_cselect_b32 s78, s52, s10
	s_add_i32 s13, 0, 0x14000
	ds_read_b128 v[142:145], v146
	ds_read_b128 v[156:159], v146 offset:1024
	ds_read_b128 v[160:163], v146 offset:2048
	ds_read_b128 v[164:167], v146 offset:3072
	v_add_u32_e32 v146, s13, v153
	ds_read_b128 v[168:171], v146
	ds_read_b128 v[172:175], v146 offset:1024
	ds_read_b128 v[176:179], v146 offset:2048
	ds_read_b128 v[180:183], v146 offset:3072
	s_add_i32 m0, s65, 0xc000
	ds_read_b128 v[184:187], v155
	ds_read_b128 v[188:191], v155 offset:1024
	ds_read_b128 v[192:195], v155 offset:2048
	ds_read_b128 v[196:199], v155 offset:3072
	ds_read_b128 v[200:203], v155 offset:4096
	ds_read_b128 v[216:219], v155 offset:5120
	ds_read_b128 v[220:223], v155 offset:6144
	ds_read_b128 v[224:227], v155 offset:7168
	global_load_lds_dwordx4 v138, s[4:5]
	s_add_i32 m0, s65, 0xe000
	s_nop 0
	global_load_lds_dwordx4 v140, s[4:5]
	s_waitcnt vmcnt(8)
	s_waitcnt lgkmcnt(0)
	s_barrier
	s_setprio 1
	s_waitcnt lgkmcnt(0)
	v_mfma_f32_16x16x32_bf16 v[124:127], v[142:145], v[184:187], v[124:127]
	v_mfma_f32_16x16x32_bf16 v[120:123], v[160:163], v[184:187], v[120:123]
	v_mfma_f32_16x16x32_bf16 v[108:111], v[142:145], v[192:195], v[108:111]
	v_mfma_f32_16x16x32_bf16 v[104:107], v[160:163], v[192:195], v[104:107]
	v_mfma_f32_16x16x32_bf16 v[92:95], v[142:145], v[200:203], v[92:95]
	v_mfma_f32_16x16x32_bf16 v[88:91], v[160:163], v[200:203], v[88:91]
	v_mfma_f32_16x16x32_bf16 v[76:79], v[142:145], v[220:223], v[76:79]
	v_mfma_f32_16x16x32_bf16 v[72:75], v[160:163], v[220:223], v[72:75]
	v_mfma_f32_16x16x32_bf16 v[124:127], v[156:159], v[188:191], v[124:127]
	v_mfma_f32_16x16x32_bf16 v[120:123], v[164:167], v[188:191], v[120:123]
	v_mfma_f32_16x16x32_bf16 v[108:111], v[156:159], v[196:199], v[108:111]
	v_mfma_f32_16x16x32_bf16 v[104:107], v[164:167], v[196:199], v[104:107]
	v_mfma_f32_16x16x32_bf16 v[92:95], v[156:159], v[216:219], v[92:95]
	v_mfma_f32_16x16x32_bf16 v[88:91], v[164:167], v[216:219], v[88:91]
	v_mfma_f32_16x16x32_bf16 v[76:79], v[156:159], v[224:227], v[76:79]
	v_mfma_f32_16x16x32_bf16 v[72:75], v[164:167], v[224:227], v[72:75]
	s_setprio 0
	s_setprio 1
	v_mfma_f32_16x16x32_bf16 v[116:119], v[168:171], v[184:187], v[116:119]
	v_mfma_f32_16x16x32_bf16 v[112:115], v[176:179], v[184:187], v[112:115]
	v_mfma_f32_16x16x32_bf16 v[100:103], v[168:171], v[192:195], v[100:103]
	v_mfma_f32_16x16x32_bf16 v[96:99], v[176:179], v[192:195], v[96:99]
	v_mfma_f32_16x16x32_bf16 v[84:87], v[168:171], v[200:203], v[84:87]
	v_mfma_f32_16x16x32_bf16 v[80:83], v[176:179], v[200:203], v[80:83]
	v_mfma_f32_16x16x32_bf16 v[68:71], v[168:171], v[220:223], v[68:71]
	v_mfma_f32_16x16x32_bf16 v[64:67], v[176:179], v[220:223], v[64:67]
	v_mfma_f32_16x16x32_bf16 v[116:119], v[172:175], v[188:191], v[116:119]
	v_mfma_f32_16x16x32_bf16 v[112:115], v[180:183], v[188:191], v[112:115]
	v_mfma_f32_16x16x32_bf16 v[100:103], v[172:175], v[196:199], v[100:103]
	v_mfma_f32_16x16x32_bf16 v[96:99], v[180:183], v[196:199], v[96:99]
	v_mfma_f32_16x16x32_bf16 v[84:87], v[172:175], v[216:219], v[84:87]
	v_mfma_f32_16x16x32_bf16 v[80:83], v[180:183], v[216:219], v[80:83]
	v_mfma_f32_16x16x32_bf16 v[68:71], v[172:175], v[224:227], v[68:71]
	v_mfma_f32_16x16x32_bf16 v[64:67], v[180:183], v[224:227], v[64:67]
	s_setprio 0
	s_barrier
	s_add_i32 s80, s80, s60
	v_lshl_add_u64 v[146:147], s[78:79], 0, v[130:131]
	s_mov_b32 m0, s80
	ds_read_b128 v[184:187], v155 offset:16384
	ds_read_b128 v[188:191], v155 offset:17408
	ds_read_b128 v[192:195], v155 offset:18432
	ds_read_b128 v[196:199], v155 offset:19456
	ds_read_b128 v[200:203], v155 offset:20480
	ds_read_b128 v[216:219], v155 offset:21504
	ds_read_b128 v[220:223], v155 offset:22528
	ds_read_b128 v[224:227], v155 offset:23552
	global_load_lds_dwordx4 v[146:147], off
	s_add_i32 m0, s80, 0x2000
	v_lshl_add_u64 v[150:151], s[78:79], 0, v[134:135]
	s_add_u32 s78, s78, s20
	s_addc_u32 s79, s79, s21
	s_add_i32 s13, s13, s60
	global_load_lds_dwordx4 v[150:151], off
	v_lshl_add_u64 v[204:205], s[78:79], 0, v[130:131]
	s_mov_b32 m0, s13
	v_lshl_add_u64 v[228:229], s[78:79], 0, v[134:135]
	global_load_lds_dwordx4 v[204:205], off
	s_add_i32 m0, s13, 0x2000
	v_lshl_add_u64 v[230:231], s[8:9], 0, v[128:129]
	global_load_lds_dwordx4 v[228:229], off
	s_mov_b32 m0, s65
	v_lshl_add_u64 v[234:235], s[8:9], 0, v[132:133]
	global_load_lds_dwordx4 v[230:231], off
	s_mov_b32 m0, s66
	s_nop 0
	global_load_lds_dwordx4 v[234:235], off
	s_waitcnt vmcnt(8)
	s_waitcnt lgkmcnt(0)
	s_barrier
; #define PG8_STAGE(bufoff, gbase, voff) do { _Pragma("unroll") for (int _i = 0; _i < 2; ++_i) \
;         __builtin_amdgcn_global_load_lds((const unsigned*)((const char*)(gbase) + (voff)[_i]), (PG8_LAS unsigned*)(lds + (bufoff) + ldsw + _i * 8192), 16, 0, 0); } while (0)
; #define PG8_LDA(dst, b, h) do { _Pragma("unroll") for (int m = 0; m < 4; ++m) _Pragma("unroll") for (int k = 0; k < 2; ++k) dst[m][k] = *(const PG8_LAS bf16x8*)(lds + PG8_SA(b, h) + aoff + m * 2048 + k * 1024); } while (0)
; #define PG8_WAIT_V(n) asm volatile("s_waitcnt vmcnt(" #n ")" ::: "memory")
; template <class Epi, class Sched, bool ALIGN_EPI = false, bool SP2 = false>
; __device__ __forceinline__ void gemm_phase(PG8_LAS unsigned char* lds, const Gemm g, const Sched& S, const Epi& E, const int tid) {
;     ...
;         for (int t = 0; t < nt; t += 2) {
;             if constexpr (Epi::KHOOK) { if (t == 8 || t == 16) E.khook(acc, cur, t, wr, wc, fr, fq); }
;             const bool last = (t == nt - 2);
;             const char* a1 = cA + (size_t)(t + 1) * kstep;
;             const char* a2 = last ? nA : cA + (size_t)(t + 2) * kstep; const char* b2 = last ? nB : cB + (size_t)(t + 2) * kstep;
;             const char* a3 = a2 + kstep; const char* b3 = b2 + kstep;
;             if (last && has_next) S.a_ready(nxt);
;             if constexpr (SP2) {
;             PG8_LDB(B0, 0, 0); PG8_LDB(B1, 0, 1); PG8_SCHED; PG8_LDA(At, 0, 0); PG8_STAGE(PG8_SA(1, 1), a1 + hstepA, voffA);
;             PG8_WAIT_V(8); PG8_WAIT_L(0); PG8_BAR; PG8_MMA(0, 0, At, B0); PG8_MMA(0, 1, At, B1); PG8_BAR; PG8_SCHED;
;             PG8_LDA(At, 0, 1); PG8_STAGE(PG8_SB(0, 0), b2, voffB); PG8_STAGE(PG8_SB(0, 1), b2 + hstepB, voffB); PG8_STAGE(PG8_SA(0, 0), a2, voffA);
;             PG8_WAIT_V(8); PG8_WAIT_L(0); PG8_BAR; PG8_MMA(1, 0, At, B0); PG8_MMA(1, 1, At, B1); PG8_BAR; PG8_SCHED;
;             PG8_LDB(B0, 1, 0); PG8_LDB(B1, 1, 1); PG8_SCHED; PG8_LDA(At, 1, 0); PG8_STAGE(PG8_SA(0, 1), a2 + hstepA, voffA);
;             PG8_WAIT_V(8); PG8_WAIT_L(0); PG8_BAR; PG8_MMA(0, 0, At, B0); PG8_MMA(0, 1, At, B1); PG8_BAR; PG8_SCHED;
;             PG8_LDA(At, 1, 1); PG8_STAGE(PG8_SB(1, 0), b3, voffB); PG8_STAGE(PG8_SB(1, 1), b3 + hstepB, voffB); PG8_STAGE(PG8_SA(1, 0), a3, voffA);
;             PG8_WAIT_V(8); PG8_WAIT_L(0); PG8_BAR; PG8_MMA(1, 0, At, B0); PG8_MMA(1, 1, At, B1); PG8_BAR; PG8_SCHED;
	s_setprio 1
	s_waitcnt lgkmcnt(0)
	v_mfma_f32_16x16x32_bf16 v[60:63], v[142:145], v[184:187], v[60:63]
	v_mfma_f32_16x16x32_bf16 v[56:59], v[160:163], v[184:187], v[56:59]
	v_mfma_f32_16x16x32_bf16 v[44:47], v[142:145], v[192:195], v[44:47]
	v_mfma_f32_16x16x32_bf16 v[40:43], v[160:163], v[192:195], v[40:43]
	v_mfma_f32_16x16x32_bf16 v[28:31], v[142:145], v[200:203], v[28:31]
	v_mfma_f32_16x16x32_bf16 v[24:27], v[160:163], v[200:203], v[24:27]
	v_mfma_f32_16x16x32_bf16 v[12:15], v[142:145], v[220:223], v[12:15]
	v_mfma_f32_16x16x32_bf16 v[8:11], v[160:163], v[220:223], v[8:11]
	v_mfma_f32_16x16x32_bf16 v[60:63], v[156:159], v[188:191], v[60:63]
	v_mfma_f32_16x16x32_bf16 v[56:59], v[164:167], v[188:191], v[56:59]
	v_mfma_f32_16x16x32_bf16 v[44:47], v[156:159], v[196:199], v[44:47]
	v_mfma_f32_16x16x32_bf16 v[40:43], v[164:167], v[196:199], v[40:43]
	v_mfma_f32_16x16x32_bf16 v[28:31], v[156:159], v[216:219], v[28:31]
	v_mfma_f32_16x16x32_bf16 v[24:27], v[164:167], v[216:219], v[24:27]
	v_mfma_f32_16x16x32_bf16 v[12:15], v[156:159], v[224:227], v[12:15]
	v_mfma_f32_16x16x32_bf16 v[8:11], v[164:167], v[224:227], v[8:11]
	s_setprio 0
	s_setprio 1
	v_mfma_f32_16x16x32_bf16 v[52:55], v[168:171], v[184:187], v[52:55]
	v_mfma_f32_16x16x32_bf16 v[48:51], v[176:179], v[184:187], v[48:51]
	v_mfma_f32_16x16x32_bf16 v[36:39], v[168:171], v[192:195], v[36:39]
	v_mfma_f32_16x16x32_bf16 v[32:35], v[176:179], v[192:195], v[32:35]
	v_mfma_f32_16x16x32_bf16 v[20:23], v[168:171], v[200:203], v[20:23]
	v_mfma_f32_16x16x32_bf16 v[16:19], v[176:179], v[200:203], v[16:19]
	v_mfma_f32_16x16x32_bf16 v[4:7], v[168:171], v[220:223], v[4:7]
	v_mfma_f32_16x16x32_bf16 v[0:3], v[176:179], v[220:223], v[0:3]
	v_mfma_f32_16x16x32_bf16 v[52:55], v[172:175], v[188:191], v[52:55]
	v_mfma_f32_16x16x32_bf16 v[48:51], v[180:183], v[188:191], v[48:51]
	v_mfma_f32_16x16x32_bf16 v[36:39], v[172:175], v[196:199], v[36:39]
	v_mfma_f32_16x16x32_bf16 v[32:35], v[180:183], v[196:199], v[32:35]
	v_mfma_f32_16x16x32_bf16 v[20:23], v[172:175], v[216:219], v[20:23]
	v_mfma_f32_16x16x32_bf16 v[16:19], v[180:183], v[216:219], v[16:19]
	v_mfma_f32_16x16x32_bf16 v[4:7], v[172:175], v[224:227], v[4:7]
	v_mfma_f32_16x16x32_bf16 v[0:3], v[180:183], v[224:227], v[0:3]
	s_setprio 0
	s_barrier
	s_add_i32 s13, 0, 0x18000
	v_add_u32_e32 v148, s13, v153
	s_add_i32 s78, 0, 0x1c000
	ds_read_b128 v[142:145], v148
	ds_read_b128 v[156:159], v148 offset:1024
	ds_read_b128 v[160:163], v148 offset:2048
	ds_read_b128 v[164:167], v148 offset:3072
	v_add_u32_e32 v148, s78, v153
	ds_read_b128 v[168:171], v148
	ds_read_b128 v[172:175], v148 offset:1024
	ds_read_b128 v[176:179], v148 offset:2048
	ds_read_b128 v[180:183], v148 offset:3072
	s_add_u32 s8, s8, s18
	s_addc_u32 s9, s9, s19
	s_mov_b32 m0, s67
	ds_read_b128 v[184:187], v155 offset:32768
	ds_read_b128 v[188:191], v155 offset:33792
	ds_read_b128 v[192:195], v155 offset:34816
	ds_read_b128 v[196:199], v155 offset:35840
	ds_read_b128 v[200:203], v155 offset:36864
	ds_read_b128 v[216:219], v155 offset:37888
	ds_read_b128 v[220:223], v155 offset:38912
	ds_read_b128 v[224:227], v155 offset:39936
	global_load_lds_dwordx4 v128, s[8:9]
	s_mov_b32 m0, s68
	s_nop 0
	global_load_lds_dwordx4 v132, s[8:9]
	s_waitcnt vmcnt(8)
	s_waitcnt lgkmcnt(0)
	s_barrier
	s_setprio 1
	s_waitcnt lgkmcnt(0)
	v_mfma_f32_16x16x32_bf16 v[124:127], v[142:145], v[184:187], v[124:127]
	v_mfma_f32_16x16x32_bf16 v[120:123], v[160:163], v[184:187], v[120:123]
	v_mfma_f32_16x16x32_bf16 v[108:111], v[142:145], v[192:195], v[108:111]
	v_mfma_f32_16x16x32_bf16 v[104:107], v[160:163], v[192:195], v[104:107]
	v_mfma_f32_16x16x32_bf16 v[92:95], v[142:145], v[200:203], v[92:95]
	v_mfma_f32_16x16x32_bf16 v[88:91], v[160:163], v[200:203], v[88:91]
	v_mfma_f32_16x16x32_bf16 v[76:79], v[142:145], v[220:223], v[76:79]
	v_mfma_f32_16x16x32_bf16 v[72:75], v[160:163], v[220:223], v[72:75]
	v_mfma_f32_16x16x32_bf16 v[124:127], v[156:159], v[188:191], v[124:127]
	v_mfma_f32_16x16x32_bf16 v[120:123], v[164:167], v[188:191], v[120:123]
	v_mfma_f32_16x16x32_bf16 v[108:111], v[156:159], v[196:199], v[108:111]
	v_mfma_f32_16x16x32_bf16 v[104:107], v[164:167], v[196:199], v[104:107]
	v_mfma_f32_16x16x32_bf16 v[92:95], v[156:159], v[216:219], v[92:95]
	v_mfma_f32_16x16x32_bf16 v[88:91], v[164:167], v[216:219], v[88:91]
	v_mfma_f32_16x16x32_bf16 v[76:79], v[156:159], v[224:227], v[76:79]
	v_mfma_f32_16x16x32_bf16 v[72:75], v[164:167], v[224:227], v[72:75]
	s_setprio 0
	s_setprio 1
	v_mfma_f32_16x16x32_bf16 v[116:119], v[168:171], v[184:187], v[116:119]
	v_mfma_f32_16x16x32_bf16 v[112:115], v[176:179], v[184:187], v[112:115]
	v_mfma_f32_16x16x32_bf16 v[100:103], v[168:171], v[192:195], v[100:103]
	v_mfma_f32_16x16x32_bf16 v[96:99], v[176:179], v[192:195], v[96:99]
	v_mfma_f32_16x16x32_bf16 v[84:87], v[168:171], v[200:203], v[84:87]
	v_mfma_f32_16x16x32_bf16 v[80:83], v[176:179], v[200:203], v[80:83]
	v_mfma_f32_16x16x32_bf16 v[68:71], v[168:171], v[220:223], v[68:71]
	v_mfma_f32_16x16x32_bf16 v[64:67], v[176:179], v[220:223], v[64:67]
	v_mfma_f32_16x16x32_bf16 v[116:119], v[172:175], v[188:191], v[116:119]
	v_mfma_f32_16x16x32_bf16 v[112:115], v[180:183], v[188:191], v[112:115]
	v_mfma_f32_16x16x32_bf16 v[100:103], v[172:175], v[196:199], v[100:103]
	v_mfma_f32_16x16x32_bf16 v[96:99], v[180:183], v[196:199], v[96:99]
	v_mfma_f32_16x16x32_bf16 v[84:87], v[172:175], v[216:219], v[84:87]
	v_mfma_f32_16x16x32_bf16 v[80:83], v[180:183], v[216:219], v[80:83]
	v_mfma_f32_16x16x32_bf16 v[68:71], v[172:175], v[224:227], v[68:71]
	v_mfma_f32_16x16x32_bf16 v[64:67], v[180:183], v[224:227], v[64:67]
	s_setprio 0
	s_barrier
; #define PG8_STAGE(bufoff, gbase, voff) do { _Pragma("unroll") for (int _i = 0; _i < 2; ++_i) \
;         __builtin_amdgcn_global_load_lds((const unsigned*)((const char*)(gbase) + (voff)[_i]), (PG8_LAS unsigned*)(lds + (bufoff) + ldsw + _i * 8192), 16, 0, 0); } while (0)
; #define PG8_LDA(dst, b, h) do { _Pragma("unroll") for (int m = 0; m < 4; ++m) _Pragma("unroll") for (int k = 0; k < 2; ++k) dst[m][k] = *(const PG8_LAS bf16x8*)(lds + PG8_SA(b, h) + aoff + m * 2048 + k * 1024); } while (0)
; #define PG8_WAIT_V(n) asm volatile("s_waitcnt vmcnt(" #n ")" ::: "memory")
; template <class Epi, class Sched, bool ALIGN_EPI = false, bool SP2 = false>
; __device__ __forceinline__ void gemm_phase(PG8_LAS unsigned char* lds, const Gemm g, const Sched& S, const Epi& E, const int tid) {
;     ...
;         for (int t = 0; t < nt; t += 2) {
;             if constexpr (Epi::KHOOK) { if (t == 8 || t == 16) E.khook(acc, cur, t, wr, wc, fr, fq); }
;             const bool last = (t == nt - 2);
;             const char* a1 = cA + (size_t)(t + 1) * kstep;
;             const char* a2 = last ? nA : cA + (size_t)(t + 2) * kstep; const char* b2 = last ? nB : cB + (size_t)(t + 2) * kstep;
;             const char* a3 = a2 + kstep; const char* b3 = b2 + kstep;
;             if (last && has_next) S.a_ready(nxt);
;             if constexpr (SP2) {
;             PG8_LDB(B0, 0, 0); PG8_LDB(B1, 0, 1); PG8_SCHED; PG8_LDA(At, 0, 0); PG8_STAGE(PG8_SA(1, 1), a1 + hstepA, voffA);
;             PG8_WAIT_V(8); PG8_WAIT_L(0); PG8_BAR; PG8_MMA(0, 0, At, B0); PG8_MMA(0, 1, At, B1); PG8_BAR; PG8_SCHED;
;             PG8_LDA(At, 0, 1); PG8_STAGE(PG8_SB(0, 0), b2, voffB); PG8_STAGE(PG8_SB(0, 1), b2 + hstepB, voffB); PG8_STAGE(PG8_SA(0, 0), a2, voffA);
;             PG8_WAIT_V(8); PG8_WAIT_L(0); PG8_BAR; PG8_MMA(1, 0, At, B0); PG8_MMA(1, 1, At, B1); PG8_BAR; PG8_SCHED;
;             PG8_LDB(B0, 1, 0); PG8_LDB(B1, 1, 1); PG8_SCHED; PG8_LDA(At, 1, 0); PG8_STAGE(PG8_SA(0, 1), a2 + hstepA, voffA);
;             PG8_WAIT_V(8); PG8_WAIT_L(0); PG8_BAR; PG8_MMA(0, 0, At, B0); PG8_MMA(0, 1, At, B1); PG8_BAR; PG8_SCHED;
;             PG8_LDA(At, 1, 1); PG8_STAGE(PG8_SB(1, 0), b3, voffB); PG8_STAGE(PG8_SB(1, 1), b3 + hstepB, voffB); PG8_STAGE(PG8_SA(1, 0), a3, voffA);
;             PG8_WAIT_V(8); PG8_WAIT_L(0); PG8_BAR; PG8_MMA(1, 0, At, B0); PG8_MMA(1, 1, At, B1); PG8_BAR; PG8_SCHED;
	s_add_i32 s8, s13, s60
	s_add_i32 m0, s8, 0xffffff80
	ds_read_b128 v[184:187], v155 offset:49152
	ds_read_b128 v[188:191], v155 offset:50176
	ds_read_b128 v[192:195], v155 offset:51200
	ds_read_b128 v[196:199], v155 offset:52224
	ds_read_b128 v[200:203], v155 offset:53248
	ds_read_b128 v[216:219], v155 offset:54272
	ds_read_b128 v[220:223], v155 offset:55296
	ds_read_b128 v[224:227], v155 offset:56320
	global_load_lds_dwordx4 v[146:147], off offset:128
	s_add_i32 m0, s8, 0x1f80
	s_add_i32 s8, s78, s60
	global_load_lds_dwordx4 v[150:151], off offset:128
	s_add_i32 m0, s8, 0xffffff80
	s_nop 0
	global_load_lds_dwordx4 v[204:205], off offset:128
	s_add_i32 m0, s8, 0x1f80
	s_nop 0
	global_load_lds_dwordx4 v[228:229], off offset:128
	s_add_i32 m0, s71, 0xffffff80
	s_nop 0
	global_load_lds_dwordx4 v[230:231], off offset:128
	s_add_i32 m0, s72, 0xffffff80
	s_nop 0
	global_load_lds_dwordx4 v[234:235], off offset:128
	s_waitcnt vmcnt(8)
	s_waitcnt lgkmcnt(0)
	s_barrier
	s_setprio 1
	s_waitcnt lgkmcnt(0)
	v_mfma_f32_16x16x32_bf16 v[60:63], v[142:145], v[184:187], v[60:63]
	v_mfma_f32_16x16x32_bf16 v[56:59], v[160:163], v[184:187], v[56:59]
	v_mfma_f32_16x16x32_bf16 v[44:47], v[142:145], v[192:195], v[44:47]
	v_mfma_f32_16x16x32_bf16 v[40:43], v[160:163], v[192:195], v[40:43]
	v_mfma_f32_16x16x32_bf16 v[28:31], v[142:145], v[200:203], v[28:31]
	v_mfma_f32_16x16x32_bf16 v[24:27], v[160:163], v[200:203], v[24:27]
	v_mfma_f32_16x16x32_bf16 v[12:15], v[142:145], v[220:223], v[12:15]
	v_mfma_f32_16x16x32_bf16 v[8:11], v[160:163], v[220:223], v[8:11]
	v_mfma_f32_16x16x32_bf16 v[60:63], v[156:159], v[188:191], v[60:63]
	v_mfma_f32_16x16x32_bf16 v[56:59], v[164:167], v[188:191], v[56:59]
	v_mfma_f32_16x16x32_bf16 v[44:47], v[156:159], v[196:199], v[44:47]
	v_mfma_f32_16x16x32_bf16 v[40:43], v[164:167], v[196:199], v[40:43]
	v_mfma_f32_16x16x32_bf16 v[28:31], v[156:159], v[216:219], v[28:31]
	v_mfma_f32_16x16x32_bf16 v[24:27], v[164:167], v[216:219], v[24:27]
	v_mfma_f32_16x16x32_bf16 v[12:15], v[156:159], v[224:227], v[12:15]
	v_mfma_f32_16x16x32_bf16 v[8:11], v[164:167], v[224:227], v[8:11]
	s_setprio 0
	s_setprio 1
	v_mfma_f32_16x16x32_bf16 v[52:55], v[168:171], v[184:187], v[52:55]
	v_mfma_f32_16x16x32_bf16 v[48:51], v[176:179], v[184:187], v[48:51]
	v_mfma_f32_16x16x32_bf16 v[36:39], v[168:171], v[192:195], v[36:39]
	v_mfma_f32_16x16x32_bf16 v[32:35], v[176:179], v[192:195], v[32:35]
	v_mfma_f32_16x16x32_bf16 v[20:23], v[168:171], v[200:203], v[20:23]
	v_mfma_f32_16x16x32_bf16 v[16:19], v[176:179], v[200:203], v[16:19]
	v_mfma_f32_16x16x32_bf16 v[4:7], v[168:171], v[220:223], v[4:7]
	v_mfma_f32_16x16x32_bf16 v[0:3], v[176:179], v[220:223], v[0:3]
	v_mfma_f32_16x16x32_bf16 v[52:55], v[172:175], v[188:191], v[52:55]
	v_mfma_f32_16x16x32_bf16 v[48:51], v[180:183], v[188:191], v[48:51]
	v_mfma_f32_16x16x32_bf16 v[36:39], v[172:175], v[196:199], v[36:39]
	v_mfma_f32_16x16x32_bf16 v[32:35], v[180:183], v[196:199], v[32:35]
	v_mfma_f32_16x16x32_bf16 v[20:23], v[172:175], v[216:219], v[20:23]
	v_mfma_f32_16x16x32_bf16 v[16:19], v[180:183], v[216:219], v[16:19]
	v_mfma_f32_16x16x32_bf16 v[4:7], v[172:175], v[224:227], v[4:7]
	v_mfma_f32_16x16x32_bf16 v[0:3], v[180:183], v[224:227], v[0:3]
	s_setprio 0
	s_barrier
	s_add_u32 s4, s4, 0x100
	s_addc_u32 s5, s5, 0
	s_add_u32 s10, s10, 0x100
	s_addc_u32 s11, s11, 0
	s_cmp_ge_i32 s12, s69
	s_mov_b32 s8, s12
	s_cbranch_scc0 .LBB0_817
	v_readlane_b32 s79, v254, 40
	s_mov_b32 s80, 0xf800000

; #define PG8_STAGE(bufoff, gbase, voff) do { _Pragma("unroll") for (int _i = 0; _i < 2; ++_i) \
;         __builtin_amdgcn_global_load_lds((const unsigned*)((const char*)(gbase) + (voff)[_i]), (PG8_LAS unsigned*)(lds + (bufoff) + ldsw + _i * 8192), 16, 0, 0); } while (0)
; #define PG8_LDA(dst, b, h) do { _Pragma("unroll") for (int m = 0; m < 4; ++m) _Pragma("unroll") for (int k = 0; k < 2; ++k) dst[m][k] = *(const PG8_LAS bf16x8*)(lds + PG8_SA(b, h) + aoff + m * 2048 + k * 1024); } while (0)
; #define PG8_WAIT_V(n) asm volatile("s_waitcnt vmcnt(" #n ")" ::: "memory")
; template <class Epi, class Sched, bool ALIGN_EPI = false, bool SP2 = false>
; __device__ __forceinline__ void gemm_phase(PG8_LAS unsigned char* lds, const Gemm g, const Sched& S, const Epi& E, const int tid) {
;     ...
;         for (int t = 0; t < nt; t += 2) {
;             if constexpr (Epi::KHOOK) { if (t == 8 || t == 16) E.khook(acc, cur, t, wr, wc, fr, fq); }
;             const bool last = (t == nt - 2);
;             const char* a1 = cA + (size_t)(t + 1) * kstep;
;             const char* a2 = last ? nA : cA + (size_t)(t + 2) * kstep; const char* b2 = last ? nB : cB + (size_t)(t + 2) * kstep;
;             const char* a3 = a2 + kstep; const char* b3 = b2 + kstep;
;             if (last && has_next) S.a_ready(nxt);
;             if constexpr (SP2) {
;             PG8_LDB(B0, 0, 0); PG8_LDB(B1, 0, 1); PG8_SCHED; PG8_LDA(At, 0, 0); PG8_STAGE(PG8_SA(1, 1), a1 + hstepA, voffA);
;             PG8_WAIT_V(8); PG8_WAIT_L(0); PG8_BAR; PG8_MMA(0, 0, At, B0); PG8_MMA(0, 1, At, B1); PG8_BAR; PG8_SCHED;
;             PG8_LDA(At, 0, 1); PG8_STAGE(PG8_SB(0, 0), b2, voffB); PG8_STAGE(PG8_SB(0, 1), b2 + hstepB, voffB); PG8_STAGE(PG8_SA(0, 0), a2, voffA);
;             PG8_WAIT_V(8); PG8_WAIT_L(0); PG8_BAR; PG8_MMA(1, 0, At, B0); PG8_MMA(1, 1, At, B1); PG8_BAR; PG8_SCHED;
;             PG8_LDB(B0, 1, 0); PG8_LDB(B1, 1, 1); PG8_SCHED; PG8_LDA(At, 1, 0); PG8_STAGE(PG8_SA(0, 1), a2 + hstepA, voffA);
;             PG8_WAIT_V(8); PG8_WAIT_L(0); PG8_BAR; PG8_MMA(0, 0, At, B0); PG8_MMA(0, 1, At, B1); PG8_BAR; PG8_SCHED;
;             PG8_LDA(At, 1, 1); PG8_STAGE(PG8_SB(1, 0), b3, voffB); PG8_STAGE(PG8_SB(1, 1), b3 + hstepB, voffB); PG8_STAGE(PG8_SA(1, 0), a3, voffA);
;             PG8_WAIT_V(8); PG8_WAIT_L(0); PG8_BAR; PG8_MMA(1, 0, At, B0); PG8_MMA(1, 1, At, B1); PG8_BAR; PG8_SCHED;
.LBB0_1105:
	s_add_i32 s2, s64, 2
	s_add_u32 s3, s34, 0x80
	s_addc_u32 s4, s35, 0
	s_add_i32 s65, 0, 0x10000
	s_cmp_eq_u32 s57, s64
	s_cselect_b32 s5, s9, s4
	s_cselect_b32 s4, s8, s3
	v_add_u32_e32 v147, s65, v171
	s_cselect_b32 s37, s31, s62
	s_cselect_b32 s36, s30, s61
	s_add_i32 s3, 0, 0x14000
	ds_read_b128 v[128:131], v147
	ds_read_b128 v[132:135], v147 offset:1024
	ds_read_b128 v[174:177], v147 offset:2048
	ds_read_b128 v[178:181], v147 offset:3072
	v_add_u32_e32 v147, s3, v171
	ds_read_b128 v[182:185], v147
	ds_read_b128 v[186:189], v147 offset:1024
	ds_read_b128 v[190:193], v147 offset:2048
	ds_read_b128 v[194:197], v147 offset:3072
	s_add_i32 m0, s48, 0xc000
	ds_read_b128 v[198:201], v173
	ds_read_b128 v[202:205], v173 offset:1024
	ds_read_b128 v[216:219], v173 offset:2048
	ds_read_b128 v[220:223], v173 offset:3072
	ds_read_b128 v[224:227], v173 offset:4096
	ds_read_b128 v[228:231], v173 offset:5120
	ds_read_b128 v[234:237], v173 offset:6144
	ds_read_b128 v[238:241], v173 offset:7168
	global_load_lds_dwordx4 v142, s[34:35]
	s_add_i32 m0, s48, 0xe000
	s_nop 0
	global_load_lds_dwordx4 v144, s[34:35]
	s_waitcnt vmcnt(8)
	s_waitcnt lgkmcnt(0)
	s_barrier
	s_setprio 1
	s_waitcnt lgkmcnt(0)
	v_mfma_f32_16x16x32_bf16 v[124:127], v[128:131], v[198:201], v[124:127]
	v_mfma_f32_16x16x32_bf16 v[120:123], v[174:177], v[198:201], v[120:123]
	v_mfma_f32_16x16x32_bf16 v[108:111], v[128:131], v[216:219], v[108:111]
	v_mfma_f32_16x16x32_bf16 v[104:107], v[174:177], v[216:219], v[104:107]
	v_mfma_f32_16x16x32_bf16 v[92:95], v[128:131], v[224:227], v[92:95]
	v_mfma_f32_16x16x32_bf16 v[88:91], v[174:177], v[224:227], v[88:91]
	v_mfma_f32_16x16x32_bf16 v[76:79], v[128:131], v[234:237], v[76:79]
	v_mfma_f32_16x16x32_bf16 v[72:75], v[174:177], v[234:237], v[72:75]
	v_mfma_f32_16x16x32_bf16 v[124:127], v[132:135], v[202:205], v[124:127]
	v_mfma_f32_16x16x32_bf16 v[120:123], v[178:181], v[202:205], v[120:123]
	v_mfma_f32_16x16x32_bf16 v[108:111], v[132:135], v[220:223], v[108:111]
	v_mfma_f32_16x16x32_bf16 v[104:107], v[178:181], v[220:223], v[104:107]
	v_mfma_f32_16x16x32_bf16 v[92:95], v[132:135], v[228:231], v[92:95]
	v_mfma_f32_16x16x32_bf16 v[88:91], v[178:181], v[228:231], v[88:91]
	v_mfma_f32_16x16x32_bf16 v[76:79], v[132:135], v[238:241], v[76:79]
	v_mfma_f32_16x16x32_bf16 v[72:75], v[178:181], v[238:241], v[72:75]
	s_setprio 0
	s_setprio 1
	v_mfma_f32_16x16x32_bf16 v[116:119], v[182:185], v[198:201], v[116:119]
	v_mfma_f32_16x16x32_bf16 v[112:115], v[190:193], v[198:201], v[112:115]
	v_mfma_f32_16x16x32_bf16 v[100:103], v[182:185], v[216:219], v[100:103]
	v_mfma_f32_16x16x32_bf16 v[96:99], v[190:193], v[216:219], v[96:99]
	v_mfma_f32_16x16x32_bf16 v[84:87], v[182:185], v[224:227], v[84:87]
	v_mfma_f32_16x16x32_bf16 v[80:83], v[190:193], v[224:227], v[80:83]
	v_mfma_f32_16x16x32_bf16 v[68:71], v[182:185], v[234:237], v[68:71]
	v_mfma_f32_16x16x32_bf16 v[64:67], v[190:193], v[234:237], v[64:67]
	v_mfma_f32_16x16x32_bf16 v[116:119], v[186:189], v[202:205], v[116:119]
	v_mfma_f32_16x16x32_bf16 v[112:115], v[194:197], v[202:205], v[112:115]
	v_mfma_f32_16x16x32_bf16 v[100:103], v[186:189], v[220:223], v[100:103]
	v_mfma_f32_16x16x32_bf16 v[96:99], v[194:197], v[220:223], v[96:99]
	v_mfma_f32_16x16x32_bf16 v[84:87], v[186:189], v[228:231], v[84:87]
	v_mfma_f32_16x16x32_bf16 v[80:83], v[194:197], v[228:231], v[80:83]
	v_mfma_f32_16x16x32_bf16 v[68:71], v[186:189], v[238:241], v[68:71]
	v_mfma_f32_16x16x32_bf16 v[64:67], v[194:197], v[238:241], v[64:67]
	s_setprio 0
	s_barrier
	s_add_i32 s64, s65, s41
	v_lshl_add_u64 v[242:243], s[36:37], 0, v[148:149]
	s_mov_b32 m0, s64
	ds_read_b128 v[198:201], v173 offset:16384
	ds_read_b128 v[202:205], v173 offset:17408
	ds_read_b128 v[216:219], v173 offset:18432
	ds_read_b128 v[220:223], v173 offset:19456
	ds_read_b128 v[224:227], v173 offset:20480
	ds_read_b128 v[228:231], v173 offset:21504
	ds_read_b128 v[234:237], v173 offset:22528
	ds_read_b128 v[238:241], v173 offset:23552
	global_load_lds_dwordx4 v[242:243], off
	s_add_i32 m0, s64, 0x2000
	v_lshl_add_u64 v[244:245], s[36:37], 0, v[136:137]
	s_add_u32 s36, s36, s16
	s_addc_u32 s37, s37, s17
	s_add_i32 s3, s3, s41
	global_load_lds_dwordx4 v[244:245], off
	v_lshl_add_u64 v[246:247], s[36:37], 0, v[148:149]
	s_mov_b32 m0, s3
	v_lshl_add_u64 v[248:249], s[36:37], 0, v[136:137]
	global_load_lds_dwordx4 v[246:247], off
	s_add_i32 m0, s3, 0x2000
	v_lshl_add_u64 v[250:251], s[4:5], 0, v[140:141]
	global_load_lds_dwordx4 v[248:249], off
	s_mov_b32 m0, s48
	v_lshl_add_u64 v[252:253], s[4:5], 0, v[138:139]
	global_load_lds_dwordx4 v[250:251], off
	s_mov_b32 m0, s49
	s_nop 0
	global_load_lds_dwordx4 v[252:253], off
	s_waitcnt vmcnt(8)
	s_waitcnt lgkmcnt(0)
	s_barrier
; #define PG8_STAGE(bufoff, gbase, voff) do { _Pragma("unroll") for (int _i = 0; _i < 2; ++_i) \
;         __builtin_amdgcn_global_load_lds((const unsigned*)((const char*)(gbase) + (voff)[_i]), (PG8_LAS unsigned*)(lds + (bufoff) + ldsw + _i * 8192), 16, 0, 0); } while (0)
; #define PG8_LDA(dst, b, h) do { _Pragma("unroll") for (int m = 0; m < 4; ++m) _Pragma("unroll") for (int k = 0; k < 2; ++k) dst[m][k] = *(const PG8_LAS bf16x8*)(lds + PG8_SA(b, h) + aoff + m * 2048 + k * 1024); } while (0)
; #define PG8_WAIT_V(n) asm volatile("s_waitcnt vmcnt(" #n ")" ::: "memory")
; template <class Epi, class Sched, bool ALIGN_EPI = false, bool SP2 = false>
; __device__ __forceinline__ void gemm_phase(PG8_LAS unsigned char* lds, const Gemm g, const Sched& S, const Epi& E, const int tid) {
;     ...
;         for (int t = 0; t < nt; t += 2) {
;             if constexpr (Epi::KHOOK) { if (t == 8 || t == 16) E.khook(acc, cur, t, wr, wc, fr, fq); }
;             const bool last = (t == nt - 2);
;             const char* a1 = cA + (size_t)(t + 1) * kstep;
;             const char* a2 = last ? nA : cA + (size_t)(t + 2) * kstep; const char* b2 = last ? nB : cB + (size_t)(t + 2) * kstep;
;             const char* a3 = a2 + kstep; const char* b3 = b2 + kstep;
;             if (last && has_next) S.a_ready(nxt);
;             if constexpr (SP2) {
;             PG8_LDB(B0, 0, 0); PG8_LDB(B1, 0, 1); PG8_SCHED; PG8_LDA(At, 0, 0); PG8_STAGE(PG8_SA(1, 1), a1 + hstepA, voffA);
;             PG8_WAIT_V(8); PG8_WAIT_L(0); PG8_BAR; PG8_MMA(0, 0, At, B0); PG8_MMA(0, 1, At, B1); PG8_BAR; PG8_SCHED;
;             PG8_LDA(At, 0, 1); PG8_STAGE(PG8_SB(0, 0), b2, voffB); PG8_STAGE(PG8_SB(0, 1), b2 + hstepB, voffB); PG8_STAGE(PG8_SA(0, 0), a2, voffA);
;             PG8_WAIT_V(8); PG8_WAIT_L(0); PG8_BAR; PG8_MMA(1, 0, At, B0); PG8_MMA(1, 1, At, B1); PG8_BAR; PG8_SCHED;
;             PG8_LDB(B0, 1, 0); PG8_LDB(B1, 1, 1); PG8_SCHED; PG8_LDA(At, 1, 0); PG8_STAGE(PG8_SA(0, 1), a2 + hstepA, voffA);
;             PG8_WAIT_V(8); PG8_WAIT_L(0); PG8_BAR; PG8_MMA(0, 0, At, B0); PG8_MMA(0, 1, At, B1); PG8_BAR; PG8_SCHED;
;             PG8_LDA(At, 1, 1); PG8_STAGE(PG8_SB(1, 0), b3, voffB); PG8_STAGE(PG8_SB(1, 1), b3 + hstepB, voffB); PG8_STAGE(PG8_SA(1, 0), a3, voffA);
;             PG8_WAIT_V(8); PG8_WAIT_L(0); PG8_BAR; PG8_MMA(1, 0, At, B0); PG8_MMA(1, 1, At, B1); PG8_BAR; PG8_SCHED;
	s_setprio 1
	s_waitcnt lgkmcnt(0)
	v_mfma_f32_16x16x32_bf16 v[60:63], v[128:131], v[198:201], v[60:63]
	v_mfma_f32_16x16x32_bf16 v[56:59], v[174:177], v[198:201], v[56:59]
	v_mfma_f32_16x16x32_bf16 v[44:47], v[128:131], v[216:219], v[44:47]
	v_mfma_f32_16x16x32_bf16 v[40:43], v[174:177], v[216:219], v[40:43]
	v_mfma_f32_16x16x32_bf16 v[28:31], v[128:131], v[224:227], v[28:31]
	v_mfma_f32_16x16x32_bf16 v[24:27], v[174:177], v[224:227], v[24:27]
	v_mfma_f32_16x16x32_bf16 v[12:15], v[128:131], v[234:237], v[12:15]
	v_mfma_f32_16x16x32_bf16 v[8:11], v[174:177], v[234:237], v[8:11]
	v_mfma_f32_16x16x32_bf16 v[60:63], v[132:135], v[202:205], v[60:63]
	v_mfma_f32_16x16x32_bf16 v[56:59], v[178:181], v[202:205], v[56:59]
	v_mfma_f32_16x16x32_bf16 v[44:47], v[132:135], v[220:223], v[44:47]
	v_mfma_f32_16x16x32_bf16 v[40:43], v[178:181], v[220:223], v[40:43]
	v_mfma_f32_16x16x32_bf16 v[28:31], v[132:135], v[228:231], v[28:31]
	v_mfma_f32_16x16x32_bf16 v[24:27], v[178:181], v[228:231], v[24:27]
	v_mfma_f32_16x16x32_bf16 v[12:15], v[132:135], v[238:241], v[12:15]
	v_mfma_f32_16x16x32_bf16 v[8:11], v[178:181], v[238:241], v[8:11]
	s_setprio 0
	s_setprio 1
	v_mfma_f32_16x16x32_bf16 v[52:55], v[182:185], v[198:201], v[52:55]
	v_mfma_f32_16x16x32_bf16 v[48:51], v[190:193], v[198:201], v[48:51]
	v_mfma_f32_16x16x32_bf16 v[36:39], v[182:185], v[216:219], v[36:39]
	v_mfma_f32_16x16x32_bf16 v[32:35], v[190:193], v[216:219], v[32:35]
	v_mfma_f32_16x16x32_bf16 v[20:23], v[182:185], v[224:227], v[20:23]
	v_mfma_f32_16x16x32_bf16 v[16:19], v[190:193], v[224:227], v[16:19]
	v_mfma_f32_16x16x32_bf16 v[4:7], v[182:185], v[234:237], v[4:7]
	v_mfma_f32_16x16x32_bf16 v[0:3], v[190:193], v[234:237], v[0:3]
	v_mfma_f32_16x16x32_bf16 v[52:55], v[186:189], v[202:205], v[52:55]
	v_mfma_f32_16x16x32_bf16 v[48:51], v[194:197], v[202:205], v[48:51]
	v_mfma_f32_16x16x32_bf16 v[36:39], v[186:189], v[220:223], v[36:39]
	v_mfma_f32_16x16x32_bf16 v[32:35], v[194:197], v[220:223], v[32:35]
	v_mfma_f32_16x16x32_bf16 v[20:23], v[186:189], v[228:231], v[20:23]
	v_mfma_f32_16x16x32_bf16 v[16:19], v[194:197], v[228:231], v[16:19]
	v_mfma_f32_16x16x32_bf16 v[4:7], v[186:189], v[238:241], v[4:7]
	v_mfma_f32_16x16x32_bf16 v[0:3], v[194:197], v[238:241], v[0:3]
	s_setprio 0
	s_barrier
	s_add_i32 s3, 0, 0x18000
	v_add_u32_e32 v147, s3, v171
	s_add_i32 s36, 0, 0x1c000
	ds_read_b128 v[128:131], v147
	ds_read_b128 v[132:135], v147 offset:1024
	ds_read_b128 v[174:177], v147 offset:2048
	ds_read_b128 v[178:181], v147 offset:3072
	v_add_u32_e32 v147, s36, v171
	ds_read_b128 v[182:185], v147
	ds_read_b128 v[186:189], v147 offset:1024
	ds_read_b128 v[190:193], v147 offset:2048
	ds_read_b128 v[194:197], v147 offset:3072
	s_add_u32 s4, s4, s14
	s_addc_u32 s5, s5, s15
	s_mov_b32 m0, s50
	ds_read_b128 v[198:201], v173 offset:32768
	ds_read_b128 v[202:205], v173 offset:33792
	ds_read_b128 v[216:219], v173 offset:34816
	ds_read_b128 v[220:223], v173 offset:35840
	ds_read_b128 v[224:227], v173 offset:36864
	ds_read_b128 v[228:231], v173 offset:37888
	ds_read_b128 v[234:237], v173 offset:38912
	ds_read_b128 v[238:241], v173 offset:39936
	global_load_lds_dwordx4 v140, s[4:5]
	s_mov_b32 m0, s51
	s_nop 0
	global_load_lds_dwordx4 v138, s[4:5]
	s_waitcnt vmcnt(8)
	s_waitcnt lgkmcnt(0)
	s_barrier
	s_setprio 1
	s_waitcnt lgkmcnt(0)
	v_mfma_f32_16x16x32_bf16 v[124:127], v[128:131], v[198:201], v[124:127]
	v_mfma_f32_16x16x32_bf16 v[120:123], v[174:177], v[198:201], v[120:123]
	v_mfma_f32_16x16x32_bf16 v[108:111], v[128:131], v[216:219], v[108:111]
	v_mfma_f32_16x16x32_bf16 v[104:107], v[174:177], v[216:219], v[104:107]
	v_mfma_f32_16x16x32_bf16 v[92:95], v[128:131], v[224:227], v[92:95]
	v_mfma_f32_16x16x32_bf16 v[88:91], v[174:177], v[224:227], v[88:91]
	v_mfma_f32_16x16x32_bf16 v[76:79], v[128:131], v[234:237], v[76:79]
	v_mfma_f32_16x16x32_bf16 v[72:75], v[174:177], v[234:237], v[72:75]
	v_mfma_f32_16x16x32_bf16 v[124:127], v[132:135], v[202:205], v[124:127]
	v_mfma_f32_16x16x32_bf16 v[120:123], v[178:181], v[202:205], v[120:123]
	v_mfma_f32_16x16x32_bf16 v[108:111], v[132:135], v[220:223], v[108:111]
	v_mfma_f32_16x16x32_bf16 v[104:107], v[178:181], v[220:223], v[104:107]
	v_mfma_f32_16x16x32_bf16 v[92:95], v[132:135], v[228:231], v[92:95]
	v_mfma_f32_16x16x32_bf16 v[88:91], v[178:181], v[228:231], v[88:91]
	v_mfma_f32_16x16x32_bf16 v[76:79], v[132:135], v[238:241], v[76:79]
	v_mfma_f32_16x16x32_bf16 v[72:75], v[178:181], v[238:241], v[72:75]
	s_setprio 0
	s_setprio 1
	v_mfma_f32_16x16x32_bf16 v[116:119], v[182:185], v[198:201], v[116:119]
	v_mfma_f32_16x16x32_bf16 v[112:115], v[190:193], v[198:201], v[112:115]
	v_mfma_f32_16x16x32_bf16 v[100:103], v[182:185], v[216:219], v[100:103]
	v_mfma_f32_16x16x32_bf16 v[96:99], v[190:193], v[216:219], v[96:99]
	v_mfma_f32_16x16x32_bf16 v[84:87], v[182:185], v[224:227], v[84:87]
	v_mfma_f32_16x16x32_bf16 v[80:83], v[190:193], v[224:227], v[80:83]
	v_mfma_f32_16x16x32_bf16 v[68:71], v[182:185], v[234:237], v[68:71]
	v_mfma_f32_16x16x32_bf16 v[64:67], v[190:193], v[234:237], v[64:67]
	v_mfma_f32_16x16x32_bf16 v[116:119], v[186:189], v[202:205], v[116:119]
	v_mfma_f32_16x16x32_bf16 v[112:115], v[194:197], v[202:205], v[112:115]
	v_mfma_f32_16x16x32_bf16 v[100:103], v[186:189], v[220:223], v[100:103]
	v_mfma_f32_16x16x32_bf16 v[96:99], v[194:197], v[220:223], v[96:99]
	v_mfma_f32_16x16x32_bf16 v[84:87], v[186:189], v[228:231], v[84:87]
	v_mfma_f32_16x16x32_bf16 v[80:83], v[194:197], v[228:231], v[80:83]
	v_mfma_f32_16x16x32_bf16 v[68:71], v[186:189], v[238:241], v[68:71]
	v_mfma_f32_16x16x32_bf16 v[64:67], v[194:197], v[238:241], v[64:67]
	s_setprio 0
	s_barrier
; #define PG8_STAGE(bufoff, gbase, voff) do { _Pragma("unroll") for (int _i = 0; _i < 2; ++_i) \
;         __builtin_amdgcn_global_load_lds((const unsigned*)((const char*)(gbase) + (voff)[_i]), (PG8_LAS unsigned*)(lds + (bufoff) + ldsw + _i * 8192), 16, 0, 0); } while (0)
; #define PG8_LDA(dst, b, h) do { _Pragma("unroll") for (int m = 0; m < 4; ++m) _Pragma("unroll") for (int k = 0; k < 2; ++k) dst[m][k] = *(const PG8_LAS bf16x8*)(lds + PG8_SA(b, h) + aoff + m * 2048 + k * 1024); } while (0)
; #define PG8_MMA(ai, bj, At, Bt) do { __builtin_amdgcn_s_setprio(1); _Pragma("unroll") for (int m = 0; m < 4; ++m) _Pragma("unroll") for (int n = 0; n < 2; ++n) _Pragma("unroll") for (int k = 0; k < 2; ++k) \
;         acc[ai][bj][m][n] = __builtin_amdgcn_mfma_f32_16x16x32_bf16(Bt[n][k], At[m][k], acc[ai][bj][m][n], 0, 0, 0); __builtin_amdgcn_s_setprio(0); } while (0)
; #define PG8_WAIT_V(n) asm volatile("s_waitcnt vmcnt(" #n ")" ::: "memory")
; #define PG8_WAIT_L(n) asm volatile("s_waitcnt lgkmcnt(" #n ")" ::: "memory")
; #define PG8_BAR __builtin_amdgcn_s_barrier()
; #define PG8_SCHED __builtin_amdgcn_sched_barrier(0)
; template <class Epi, class Sched, bool ALIGN_EPI = false, bool SP2 = false>
; __device__ __forceinline__ void gemm_phase(PG8_LAS unsigned char* lds, const Gemm g, const Sched& S, const Epi& E, const int tid) {
;     ...
;             PG8_LDA(At, 1, 1); PG8_STAGE(PG8_SB(1, 0), b3, voffB); PG8_STAGE(PG8_SB(1, 1), b3 + hstepB, voffB); PG8_STAGE(PG8_SA(1, 0), a3, voffA);
;             PG8_WAIT_V(8); PG8_WAIT_L(0); PG8_BAR; PG8_MMA(1, 0, At, B0); PG8_MMA(1, 1, At, B1); PG8_BAR; PG8_SCHED;
	s_add_i32 s3, s3, s41
	s_add_i32 m0, s3, 0xffffff80
	ds_read_b128 v[198:201], v173 offset:49152
	ds_read_b128 v[202:205], v173 offset:50176
	ds_read_b128 v[216:219], v173 offset:51200
	ds_read_b128 v[220:223], v173 offset:52224
	ds_read_b128 v[224:227], v173 offset:53248
	ds_read_b128 v[228:231], v173 offset:54272
	ds_read_b128 v[234:237], v173 offset:55296
	ds_read_b128 v[238:241], v173 offset:56320
	global_load_lds_dwordx4 v[242:243], off offset:128
	s_add_i32 m0, s3, 0x1f80
	s_add_i32 s3, s36, s41
	global_load_lds_dwordx4 v[244:245], off offset:128
	s_add_i32 m0, s3, 0xffffff80
	s_nop 0
	global_load_lds_dwordx4 v[246:247], off offset:128
	s_add_i32 m0, s3, 0x1f80
	s_nop 0
	global_load_lds_dwordx4 v[248:249], off offset:128
	s_add_i32 m0, s55, 0xffffff80
	s_nop 0
	global_load_lds_dwordx4 v[250:251], off offset:128
	s_add_i32 m0, s56, 0xffffff80
	s_nop 0
	global_load_lds_dwordx4 v[252:253], off offset:128
	s_waitcnt vmcnt(8)
	s_waitcnt lgkmcnt(0)
	s_barrier
	s_setprio 1
	s_waitcnt lgkmcnt(0)
	v_mfma_f32_16x16x32_bf16 v[60:63], v[128:131], v[198:201], v[60:63]
	v_mfma_f32_16x16x32_bf16 v[56:59], v[174:177], v[198:201], v[56:59]
	v_mfma_f32_16x16x32_bf16 v[44:47], v[128:131], v[216:219], v[44:47]
	v_mfma_f32_16x16x32_bf16 v[40:43], v[174:177], v[216:219], v[40:43]
	v_mfma_f32_16x16x32_bf16 v[28:31], v[128:131], v[224:227], v[28:31]
	v_mfma_f32_16x16x32_bf16 v[24:27], v[174:177], v[224:227], v[24:27]
	v_mfma_f32_16x16x32_bf16 v[12:15], v[128:131], v[234:237], v[12:15]
	v_mfma_f32_16x16x32_bf16 v[8:11], v[174:177], v[234:237], v[8:11]
	v_mfma_f32_16x16x32_bf16 v[60:63], v[132:135], v[202:205], v[60:63]
	v_mfma_f32_16x16x32_bf16 v[56:59], v[178:181], v[202:205], v[56:59]
	v_mfma_f32_16x16x32_bf16 v[44:47], v[132:135], v[220:223], v[44:47]
	v_mfma_f32_16x16x32_bf16 v[40:43], v[178:181], v[220:223], v[40:43]
	v_mfma_f32_16x16x32_bf16 v[28:31], v[132:135], v[228:231], v[28:31]
	v_mfma_f32_16x16x32_bf16 v[24:27], v[178:181], v[228:231], v[24:27]
	v_mfma_f32_16x16x32_bf16 v[12:15], v[132:135], v[238:241], v[12:15]
	v_mfma_f32_16x16x32_bf16 v[8:11], v[178:181], v[238:241], v[8:11]
	s_setprio 0
	s_setprio 1
	v_mfma_f32_16x16x32_bf16 v[52:55], v[182:185], v[198:201], v[52:55]
	v_mfma_f32_16x16x32_bf16 v[48:51], v[190:193], v[198:201], v[48:51]
	v_mfma_f32_16x16x32_bf16 v[36:39], v[182:185], v[216:219], v[36:39]
	v_mfma_f32_16x16x32_bf16 v[32:35], v[190:193], v[216:219], v[32:35]
	v_mfma_f32_16x16x32_bf16 v[20:23], v[182:185], v[224:227], v[20:23]
	v_mfma_f32_16x16x32_bf16 v[16:19], v[190:193], v[224:227], v[16:19]
	v_mfma_f32_16x16x32_bf16 v[4:7], v[182:185], v[234:237], v[4:7]
	v_mfma_f32_16x16x32_bf16 v[0:3], v[190:193], v[234:237], v[0:3]
	v_mfma_f32_16x16x32_bf16 v[52:55], v[186:189], v[202:205], v[52:55]
	v_mfma_f32_16x16x32_bf16 v[48:51], v[194:197], v[202:205], v[48:51]
	v_mfma_f32_16x16x32_bf16 v[36:39], v[186:189], v[220:223], v[36:39]
	v_mfma_f32_16x16x32_bf16 v[32:35], v[194:197], v[220:223], v[32:35]
	v_mfma_f32_16x16x32_bf16 v[20:23], v[186:189], v[228:231], v[20:23]
	v_mfma_f32_16x16x32_bf16 v[16:19], v[194:197], v[228:231], v[16:19]
	v_mfma_f32_16x16x32_bf16 v[4:7], v[186:189], v[238:241], v[4:7]
	v_mfma_f32_16x16x32_bf16 v[0:3], v[194:197], v[238:241], v[0:3]
	s_setprio 0
	s_barrier
	s_add_u32 s34, s34, 0x100
	s_addc_u32 s35, s35, 0
	s_add_u32 s61, s61, 0x100
	s_addc_u32 s62, s62, 0
	s_addk_i32 s63, 0x80
	s_cmp_ge_i32 s2, s54
	s_cbranch_scc1 .LBB0_1108
	s_mov_b32 s64, s2
	s_cmp_lt_i32 s64, 16
	s_cbranch_scc1 .LBB0_1101

; #define PG8_STAGE(bufoff, gbase, voff) do { _Pragma("unroll") for (int _i = 0; _i < 2; ++_i) \
;         __builtin_amdgcn_global_load_lds((const unsigned*)((const char*)(gbase) + (voff)[_i]), (PG8_LAS unsigned*)(lds + (bufoff) + ldsw + _i * 8192), 16, 0, 0); } while (0)
; #define PG8_LDA(dst, b, h) do { _Pragma("unroll") for (int m = 0; m < 4; ++m) _Pragma("unroll") for (int k = 0; k < 2; ++k) dst[m][k] = *(const PG8_LAS bf16x8*)(lds + PG8_SA(b, h) + aoff + m * 2048 + k * 1024); } while (0)
; #define PG8_LDB(dst, b, h) do { _Pragma("unroll") for (int n = 0; n < 2; ++n) _Pragma("unroll") for (int k = 0; k < 2; ++k) dst[n][k] = *(const PG8_LAS bf16x8*)(lds + PG8_SB(b, h) + boff + n * 2048 + k * 1024); } while (0)
; #define PG8_MMA(ai, bj, At, Bt) do { __builtin_amdgcn_s_setprio(1); _Pragma("unroll") for (int m = 0; m < 4; ++m) _Pragma("unroll") for (int n = 0; n < 2; ++n) _Pragma("unroll") for (int k = 0; k < 2; ++k) \
;         acc[ai][bj][m][n] = __builtin_amdgcn_mfma_f32_16x16x32_bf16(Bt[n][k], At[m][k], acc[ai][bj][m][n], 0, 0, 0); __builtin_amdgcn_s_setprio(0); } while (0)
; #define PG8_WAIT_V(n) asm volatile("s_waitcnt vmcnt(" #n ")" ::: "memory")
; #define PG8_WAIT_L(n) asm volatile("s_waitcnt lgkmcnt(" #n ")" ::: "memory")
; #define PG8_BAR __builtin_amdgcn_s_barrier()
; #define PG8_SCHED __builtin_amdgcn_sched_barrier(0)
; template <class Epi, class Sched, bool ALIGN_EPI = false, bool SP2 = false>
; __device__ __forceinline__ void gemm_phase(PG8_LAS unsigned char* lds, const Gemm g, const Sched& S, const Epi& E, const int tid) {
;     ...
;             PG8_LDB(B0, 0, 0); PG8_LDB(B1, 0, 1); PG8_SCHED; PG8_LDA(At, 0, 0); PG8_STAGE(PG8_SA(1, 1), a1 + hstepA, voffA);
;             PG8_WAIT_V(8); PG8_WAIT_L(0); PG8_BAR; PG8_MMA(0, 0, At, B0); PG8_MMA(0, 1, At, B1); PG8_BAR; PG8_SCHED;
;             PG8_LDA(At, 0, 1); PG8_STAGE(PG8_SB(0, 0), b2, voffB); PG8_STAGE(PG8_SB(0, 1), b2 + hstepB, voffB); PG8_STAGE(PG8_SA(0, 0), a2, voffA);
;             PG8_WAIT_V(8); PG8_WAIT_L(0); PG8_BAR; PG8_MMA(1, 0, At, B0); PG8_MMA(1, 1, At, B1); PG8_BAR; PG8_SCHED;
.LBB0_1201:
	s_add_i32 s58, s34, 2
	s_add_u32 s59, s4, 0x80
	s_addc_u32 s35, s5, 0
	s_add_i32 s62, 0, 0x10000
	s_cmp_eq_u32 s47, s34
	s_cselect_b32 s35, s11, s35
	s_cselect_b32 s34, s10, s59
	v_add_u32_e32 v151, s62, v145
	s_cselect_b32 s61, s31, s57
	s_cselect_b32 s60, s30, s56
	s_add_i32 s59, 0, 0x14000
	ds_read_b128 v[140:143], v151
	ds_read_b128 v[152:155], v151 offset:1024
	ds_read_b128 v[156:159], v151 offset:2048
	ds_read_b128 v[160:163], v151 offset:3072
	v_add_u32_e32 v151, s59, v145
	ds_read_b128 v[164:167], v151
	ds_read_b128 v[168:171], v151 offset:1024
	ds_read_b128 v[172:175], v151 offset:2048
	ds_read_b128 v[176:179], v151 offset:3072
	s_add_i32 m0, s40, 0xc000
	ds_read_b128 v[180:183], v150
	ds_read_b128 v[184:187], v150 offset:1024
	ds_read_b128 v[188:191], v150 offset:2048
	ds_read_b128 v[192:195], v150 offset:3072
	ds_read_b128 v[196:199], v150 offset:4096
	ds_read_b128 v[200:203], v150 offset:5120
	ds_read_b128 v[216:219], v150 offset:6144
	ds_read_b128 v[220:223], v150 offset:7168
	global_load_lds_dwordx4 v136, s[4:5]
	s_add_i32 m0, s40, 0xe000
	s_nop 0
	global_load_lds_dwordx4 v138, s[4:5]
	s_waitcnt vmcnt(8)
	s_waitcnt lgkmcnt(0)
	s_barrier
	s_setprio 1
	s_waitcnt lgkmcnt(0)
	v_mfma_f32_16x16x32_bf16 v[124:127], v[140:143], v[180:183], v[124:127]
	v_mfma_f32_16x16x32_bf16 v[120:123], v[156:159], v[180:183], v[120:123]
	v_mfma_f32_16x16x32_bf16 v[108:111], v[140:143], v[188:191], v[108:111]
	v_mfma_f32_16x16x32_bf16 v[104:107], v[156:159], v[188:191], v[104:107]
	v_mfma_f32_16x16x32_bf16 v[92:95], v[140:143], v[196:199], v[92:95]
	v_mfma_f32_16x16x32_bf16 v[88:91], v[156:159], v[196:199], v[88:91]
	v_mfma_f32_16x16x32_bf16 v[76:79], v[140:143], v[216:219], v[76:79]
	v_mfma_f32_16x16x32_bf16 v[72:75], v[156:159], v[216:219], v[72:75]
	v_mfma_f32_16x16x32_bf16 v[124:127], v[152:155], v[184:187], v[124:127]
	v_mfma_f32_16x16x32_bf16 v[120:123], v[160:163], v[184:187], v[120:123]
	v_mfma_f32_16x16x32_bf16 v[108:111], v[152:155], v[192:195], v[108:111]
	v_mfma_f32_16x16x32_bf16 v[104:107], v[160:163], v[192:195], v[104:107]
	v_mfma_f32_16x16x32_bf16 v[92:95], v[152:155], v[200:203], v[92:95]
	v_mfma_f32_16x16x32_bf16 v[88:91], v[160:163], v[200:203], v[88:91]
	v_mfma_f32_16x16x32_bf16 v[76:79], v[152:155], v[220:223], v[76:79]
	v_mfma_f32_16x16x32_bf16 v[72:75], v[160:163], v[220:223], v[72:75]
	s_setprio 0
	s_setprio 1
	v_mfma_f32_16x16x32_bf16 v[116:119], v[164:167], v[180:183], v[116:119]
	v_mfma_f32_16x16x32_bf16 v[112:115], v[172:175], v[180:183], v[112:115]
	v_mfma_f32_16x16x32_bf16 v[100:103], v[164:167], v[188:191], v[100:103]
	v_mfma_f32_16x16x32_bf16 v[96:99], v[172:175], v[188:191], v[96:99]
	v_mfma_f32_16x16x32_bf16 v[84:87], v[164:167], v[196:199], v[84:87]
	v_mfma_f32_16x16x32_bf16 v[80:83], v[172:175], v[196:199], v[80:83]
	v_mfma_f32_16x16x32_bf16 v[68:71], v[164:167], v[216:219], v[68:71]
	v_mfma_f32_16x16x32_bf16 v[64:67], v[172:175], v[216:219], v[64:67]
	v_mfma_f32_16x16x32_bf16 v[116:119], v[168:171], v[184:187], v[116:119]
	v_mfma_f32_16x16x32_bf16 v[112:115], v[176:179], v[184:187], v[112:115]
	v_mfma_f32_16x16x32_bf16 v[100:103], v[168:171], v[192:195], v[100:103]
	v_mfma_f32_16x16x32_bf16 v[96:99], v[176:179], v[192:195], v[96:99]
	v_mfma_f32_16x16x32_bf16 v[84:87], v[168:171], v[200:203], v[84:87]
	v_mfma_f32_16x16x32_bf16 v[80:83], v[176:179], v[200:203], v[80:83]
	v_mfma_f32_16x16x32_bf16 v[68:71], v[168:171], v[220:223], v[68:71]
	v_mfma_f32_16x16x32_bf16 v[64:67], v[176:179], v[220:223], v[64:67]
	s_setprio 0
	s_barrier
	s_add_i32 s62, s62, s39
	v_lshl_add_u64 v[204:205], s[60:61], 0, v[148:149]
	s_mov_b32 m0, s62
	ds_read_b128 v[180:183], v150 offset:16384
	ds_read_b128 v[184:187], v150 offset:17408
	ds_read_b128 v[188:191], v150 offset:18432
	ds_read_b128 v[192:195], v150 offset:19456
	ds_read_b128 v[196:199], v150 offset:20480
	ds_read_b128 v[200:203], v150 offset:21504
	ds_read_b128 v[216:219], v150 offset:22528
	ds_read_b128 v[220:223], v150 offset:23552
	global_load_lds_dwordx4 v[204:205], off
	s_add_i32 m0, s62, 0x2000
	v_lshl_add_u64 v[208:209], s[60:61], 0, v[132:133]
	s_add_u32 s60, s60, s16
	s_addc_u32 s61, s61, s17
	s_add_i32 s59, s59, s39
	global_load_lds_dwordx4 v[208:209], off
	v_lshl_add_u64 v[224:225], s[60:61], 0, v[148:149]
	s_mov_b32 m0, s59
	v_lshl_add_u64 v[226:227], s[60:61], 0, v[132:133]
	global_load_lds_dwordx4 v[224:225], off
	s_add_i32 m0, s59, 0x2000
	v_lshl_add_u64 v[228:229], s[34:35], 0, v[128:129]
	global_load_lds_dwordx4 v[226:227], off
	s_mov_b32 m0, s40
	v_lshl_add_u64 v[230:231], s[34:35], 0, v[130:131]
	global_load_lds_dwordx4 v[228:229], off
	s_mov_b32 m0, s41
	s_nop 0
	global_load_lds_dwordx4 v[230:231], off
	s_waitcnt vmcnt(8)
	s_waitcnt lgkmcnt(0)
	s_barrier
; #define PG8_STAGE(bufoff, gbase, voff) do { _Pragma("unroll") for (int _i = 0; _i < 2; ++_i) \
;         __builtin_amdgcn_global_load_lds((const unsigned*)((const char*)(gbase) + (voff)[_i]), (PG8_LAS unsigned*)(lds + (bufoff) + ldsw + _i * 8192), 16, 0, 0); } while (0)
; #define PG8_LDA(dst, b, h) do { _Pragma("unroll") for (int m = 0; m < 4; ++m) _Pragma("unroll") for (int k = 0; k < 2; ++k) dst[m][k] = *(const PG8_LAS bf16x8*)(lds + PG8_SA(b, h) + aoff + m * 2048 + k * 1024); } while (0)
; #define PG8_LDB(dst, b, h) do { _Pragma("unroll") for (int n = 0; n < 2; ++n) _Pragma("unroll") for (int k = 0; k < 2; ++k) dst[n][k] = *(const PG8_LAS bf16x8*)(lds + PG8_SB(b, h) + boff + n * 2048 + k * 1024); } while (0)
; #define PG8_MMA(ai, bj, At, Bt) do { __builtin_amdgcn_s_setprio(1); _Pragma("unroll") for (int m = 0; m < 4; ++m) _Pragma("unroll") for (int n = 0; n < 2; ++n) _Pragma("unroll") for (int k = 0; k < 2; ++k) \
;         acc[ai][bj][m][n] = __builtin_amdgcn_mfma_f32_16x16x32_bf16(Bt[n][k], At[m][k], acc[ai][bj][m][n], 0, 0, 0); __builtin_amdgcn_s_setprio(0); } while (0)
; #define PG8_WAIT_V(n) asm volatile("s_waitcnt vmcnt(" #n ")" ::: "memory")
; #define PG8_WAIT_L(n) asm volatile("s_waitcnt lgkmcnt(" #n ")" ::: "memory")
; #define PG8_BAR __builtin_amdgcn_s_barrier()
; #define PG8_SCHED __builtin_amdgcn_sched_barrier(0)
; template <class Epi, class Sched, bool ALIGN_EPI = false, bool SP2 = false>
; __device__ __forceinline__ void gemm_phase(PG8_LAS unsigned char* lds, const Gemm g, const Sched& S, const Epi& E, const int tid) {
;     ...
;             PG8_WAIT_V(8); PG8_WAIT_L(0); PG8_BAR; PG8_MMA(1, 0, At, B0); PG8_MMA(1, 1, At, B1); PG8_BAR; PG8_SCHED;
;             PG8_LDB(B0, 1, 0); PG8_LDB(B1, 1, 1); PG8_SCHED; PG8_LDA(At, 1, 0); PG8_STAGE(PG8_SA(0, 1), a2 + hstepA, voffA);
;             PG8_WAIT_V(8); PG8_WAIT_L(0); PG8_BAR; PG8_MMA(0, 0, At, B0); PG8_MMA(0, 1, At, B1); PG8_BAR; PG8_SCHED;
	s_setprio 1
	s_waitcnt lgkmcnt(0)
	v_mfma_f32_16x16x32_bf16 v[60:63], v[140:143], v[180:183], v[60:63]
	v_mfma_f32_16x16x32_bf16 v[56:59], v[156:159], v[180:183], v[56:59]
	v_mfma_f32_16x16x32_bf16 v[44:47], v[140:143], v[188:191], v[44:47]
	v_mfma_f32_16x16x32_bf16 v[40:43], v[156:159], v[188:191], v[40:43]
	v_mfma_f32_16x16x32_bf16 v[28:31], v[140:143], v[196:199], v[28:31]
	v_mfma_f32_16x16x32_bf16 v[24:27], v[156:159], v[196:199], v[24:27]
	v_mfma_f32_16x16x32_bf16 v[12:15], v[140:143], v[216:219], v[12:15]
	v_mfma_f32_16x16x32_bf16 v[8:11], v[156:159], v[216:219], v[8:11]
	v_mfma_f32_16x16x32_bf16 v[60:63], v[152:155], v[184:187], v[60:63]
	v_mfma_f32_16x16x32_bf16 v[56:59], v[160:163], v[184:187], v[56:59]
	v_mfma_f32_16x16x32_bf16 v[44:47], v[152:155], v[192:195], v[44:47]
	v_mfma_f32_16x16x32_bf16 v[40:43], v[160:163], v[192:195], v[40:43]
	v_mfma_f32_16x16x32_bf16 v[28:31], v[152:155], v[200:203], v[28:31]
	v_mfma_f32_16x16x32_bf16 v[24:27], v[160:163], v[200:203], v[24:27]
	v_mfma_f32_16x16x32_bf16 v[12:15], v[152:155], v[220:223], v[12:15]
	v_mfma_f32_16x16x32_bf16 v[8:11], v[160:163], v[220:223], v[8:11]
	s_setprio 0
	s_setprio 1
	v_mfma_f32_16x16x32_bf16 v[52:55], v[164:167], v[180:183], v[52:55]
	v_mfma_f32_16x16x32_bf16 v[48:51], v[172:175], v[180:183], v[48:51]
	v_mfma_f32_16x16x32_bf16 v[36:39], v[164:167], v[188:191], v[36:39]
	v_mfma_f32_16x16x32_bf16 v[32:35], v[172:175], v[188:191], v[32:35]
	v_mfma_f32_16x16x32_bf16 v[20:23], v[164:167], v[196:199], v[20:23]
	v_mfma_f32_16x16x32_bf16 v[16:19], v[172:175], v[196:199], v[16:19]
	v_mfma_f32_16x16x32_bf16 v[4:7], v[164:167], v[216:219], v[4:7]
	v_mfma_f32_16x16x32_bf16 v[0:3], v[172:175], v[216:219], v[0:3]
	v_mfma_f32_16x16x32_bf16 v[52:55], v[168:171], v[184:187], v[52:55]
	v_mfma_f32_16x16x32_bf16 v[48:51], v[176:179], v[184:187], v[48:51]
	v_mfma_f32_16x16x32_bf16 v[36:39], v[168:171], v[192:195], v[36:39]
	v_mfma_f32_16x16x32_bf16 v[32:35], v[176:179], v[192:195], v[32:35]
	v_mfma_f32_16x16x32_bf16 v[20:23], v[168:171], v[200:203], v[20:23]
	v_mfma_f32_16x16x32_bf16 v[16:19], v[176:179], v[200:203], v[16:19]
	v_mfma_f32_16x16x32_bf16 v[4:7], v[168:171], v[220:223], v[4:7]
	v_mfma_f32_16x16x32_bf16 v[0:3], v[176:179], v[220:223], v[0:3]
	s_setprio 0
	s_barrier
	s_add_i32 s59, 0, 0x18000
	v_add_u32_e32 v151, s59, v145
	s_add_i32 s60, 0, 0x1c000
	ds_read_b128 v[140:143], v151
	ds_read_b128 v[152:155], v151 offset:1024
	ds_read_b128 v[156:159], v151 offset:2048
	ds_read_b128 v[160:163], v151 offset:3072
	v_add_u32_e32 v151, s60, v145
	ds_read_b128 v[164:167], v151
	ds_read_b128 v[168:171], v151 offset:1024
	ds_read_b128 v[172:175], v151 offset:2048
	ds_read_b128 v[176:179], v151 offset:3072
	s_add_u32 s34, s34, s14
	s_addc_u32 s35, s35, s15
	s_mov_b32 m0, s42
	ds_read_b128 v[180:183], v150 offset:32768
	ds_read_b128 v[184:187], v150 offset:33792
	ds_read_b128 v[188:191], v150 offset:34816
	ds_read_b128 v[192:195], v150 offset:35840
	ds_read_b128 v[196:199], v150 offset:36864
	ds_read_b128 v[200:203], v150 offset:37888
	ds_read_b128 v[216:219], v150 offset:38912
	ds_read_b128 v[220:223], v150 offset:39936
	global_load_lds_dwordx4 v128, s[34:35]
	s_mov_b32 m0, s43
	s_nop 0
	global_load_lds_dwordx4 v130, s[34:35]
	s_waitcnt vmcnt(8)
	s_waitcnt lgkmcnt(0)
	s_barrier
	s_setprio 1
	s_waitcnt lgkmcnt(0)
	v_mfma_f32_16x16x32_bf16 v[124:127], v[140:143], v[180:183], v[124:127]
	v_mfma_f32_16x16x32_bf16 v[120:123], v[156:159], v[180:183], v[120:123]
	v_mfma_f32_16x16x32_bf16 v[108:111], v[140:143], v[188:191], v[108:111]
	v_mfma_f32_16x16x32_bf16 v[104:107], v[156:159], v[188:191], v[104:107]
	v_mfma_f32_16x16x32_bf16 v[92:95], v[140:143], v[196:199], v[92:95]
	v_mfma_f32_16x16x32_bf16 v[88:91], v[156:159], v[196:199], v[88:91]
	v_mfma_f32_16x16x32_bf16 v[76:79], v[140:143], v[216:219], v[76:79]
	v_mfma_f32_16x16x32_bf16 v[72:75], v[156:159], v[216:219], v[72:75]
	v_mfma_f32_16x16x32_bf16 v[124:127], v[152:155], v[184:187], v[124:127]
	v_mfma_f32_16x16x32_bf16 v[120:123], v[160:163], v[184:187], v[120:123]
	v_mfma_f32_16x16x32_bf16 v[108:111], v[152:155], v[192:195], v[108:111]
	v_mfma_f32_16x16x32_bf16 v[104:107], v[160:163], v[192:195], v[104:107]
	v_mfma_f32_16x16x32_bf16 v[92:95], v[152:155], v[200:203], v[92:95]
	v_mfma_f32_16x16x32_bf16 v[88:91], v[160:163], v[200:203], v[88:91]
	v_mfma_f32_16x16x32_bf16 v[76:79], v[152:155], v[220:223], v[76:79]
	v_mfma_f32_16x16x32_bf16 v[72:75], v[160:163], v[220:223], v[72:75]
	s_setprio 0
	s_setprio 1
	v_mfma_f32_16x16x32_bf16 v[116:119], v[164:167], v[180:183], v[116:119]
	v_mfma_f32_16x16x32_bf16 v[112:115], v[172:175], v[180:183], v[112:115]
	v_mfma_f32_16x16x32_bf16 v[100:103], v[164:167], v[188:191], v[100:103]
	v_mfma_f32_16x16x32_bf16 v[96:99], v[172:175], v[188:191], v[96:99]
	v_mfma_f32_16x16x32_bf16 v[84:87], v[164:167], v[196:199], v[84:87]
	v_mfma_f32_16x16x32_bf16 v[80:83], v[172:175], v[196:199], v[80:83]
	v_mfma_f32_16x16x32_bf16 v[68:71], v[164:167], v[216:219], v[68:71]
	v_mfma_f32_16x16x32_bf16 v[64:67], v[172:175], v[216:219], v[64:67]
	v_mfma_f32_16x16x32_bf16 v[116:119], v[168:171], v[184:187], v[116:119]
	v_mfma_f32_16x16x32_bf16 v[112:115], v[176:179], v[184:187], v[112:115]
	v_mfma_f32_16x16x32_bf16 v[100:103], v[168:171], v[192:195], v[100:103]
	v_mfma_f32_16x16x32_bf16 v[96:99], v[176:179], v[192:195], v[96:99]
	v_mfma_f32_16x16x32_bf16 v[84:87], v[168:171], v[200:203], v[84:87]
	v_mfma_f32_16x16x32_bf16 v[80:83], v[176:179], v[200:203], v[80:83]
	v_mfma_f32_16x16x32_bf16 v[68:71], v[168:171], v[220:223], v[68:71]
	v_mfma_f32_16x16x32_bf16 v[64:67], v[176:179], v[220:223], v[64:67]
	s_setprio 0
	s_barrier
; #define PG8_STAGE(bufoff, gbase, voff) do { _Pragma("unroll") for (int _i = 0; _i < 2; ++_i) \
;         __builtin_amdgcn_global_load_lds((const unsigned*)((const char*)(gbase) + (voff)[_i]), (PG8_LAS unsigned*)(lds + (bufoff) + ldsw + _i * 8192), 16, 0, 0); } while (0)
; #define PG8_LDA(dst, b, h) do { _Pragma("unroll") for (int m = 0; m < 4; ++m) _Pragma("unroll") for (int k = 0; k < 2; ++k) dst[m][k] = *(const PG8_LAS bf16x8*)(lds + PG8_SA(b, h) + aoff + m * 2048 + k * 1024); } while (0)
; #define PG8_MMA(ai, bj, At, Bt) do { __builtin_amdgcn_s_setprio(1); _Pragma("unroll") for (int m = 0; m < 4; ++m) _Pragma("unroll") for (int n = 0; n < 2; ++n) _Pragma("unroll") for (int k = 0; k < 2; ++k) \
;         acc[ai][bj][m][n] = __builtin_amdgcn_mfma_f32_16x16x32_bf16(Bt[n][k], At[m][k], acc[ai][bj][m][n], 0, 0, 0); __builtin_amdgcn_s_setprio(0); } while (0)
; #define PG8_WAIT_V(n) asm volatile("s_waitcnt vmcnt(" #n ")" ::: "memory")
; #define PG8_WAIT_L(n) asm volatile("s_waitcnt lgkmcnt(" #n ")" ::: "memory")
; #define PG8_BAR __builtin_amdgcn_s_barrier()
; #define PG8_SCHED __builtin_amdgcn_sched_barrier(0)
; template <class Epi, class Sched, bool ALIGN_EPI = false, bool SP2 = false>
; __device__ __forceinline__ void gemm_phase(PG8_LAS unsigned char* lds, const Gemm g, const Sched& S, const Epi& E, const int tid) {
;     ...
;         for (int t = 0; t < nt; t += 2) {
;             if constexpr (Epi::KHOOK) { if (t == 8 || t == 16) E.khook(acc, cur, t, wr, wc, fr, fq); }
;             const bool last = (t == nt - 2);
;             const char* a1 = cA + (size_t)(t + 1) * kstep;
;             const char* a2 = last ? nA : cA + (size_t)(t + 2) * kstep; const char* b2 = last ? nB : cB + (size_t)(t + 2) * kstep;
;     ...
;             PG8_LDA(At, 1, 1); PG8_STAGE(PG8_SB(1, 0), b3, voffB); PG8_STAGE(PG8_SB(1, 1), b3 + hstepB, voffB); PG8_STAGE(PG8_SA(1, 0), a3, voffA);
;             PG8_WAIT_V(8); PG8_WAIT_L(0); PG8_BAR; PG8_MMA(1, 0, At, B0); PG8_MMA(1, 1, At, B1); PG8_BAR; PG8_SCHED;
	s_add_i32 s34, s59, s39
	s_add_i32 m0, s34, 0xffffff80
	ds_read_b128 v[180:183], v150 offset:49152
	ds_read_b128 v[184:187], v150 offset:50176
	ds_read_b128 v[188:191], v150 offset:51200
	ds_read_b128 v[192:195], v150 offset:52224
	ds_read_b128 v[196:199], v150 offset:53248
	ds_read_b128 v[200:203], v150 offset:54272
	ds_read_b128 v[216:219], v150 offset:55296
	ds_read_b128 v[220:223], v150 offset:56320
	global_load_lds_dwordx4 v[204:205], off offset:128
	s_add_i32 m0, s34, 0x1f80
	s_add_i32 s34, s60, s39
	global_load_lds_dwordx4 v[208:209], off offset:128
	s_add_i32 m0, s34, 0xffffff80
	s_nop 0
	global_load_lds_dwordx4 v[224:225], off offset:128
	s_add_i32 m0, s34, 0x1f80
	s_nop 0
	global_load_lds_dwordx4 v[226:227], off offset:128
	s_add_i32 m0, s45, 0xffffff80
	s_nop 0
	global_load_lds_dwordx4 v[228:229], off offset:128
	s_add_i32 m0, s46, 0xffffff80
	s_nop 0
	global_load_lds_dwordx4 v[230:231], off offset:128
	s_waitcnt vmcnt(8)
	s_waitcnt lgkmcnt(0)
	s_barrier
	s_setprio 1
	s_waitcnt lgkmcnt(0)
	v_mfma_f32_16x16x32_bf16 v[60:63], v[140:143], v[180:183], v[60:63]
	v_mfma_f32_16x16x32_bf16 v[56:59], v[156:159], v[180:183], v[56:59]
	v_mfma_f32_16x16x32_bf16 v[44:47], v[140:143], v[188:191], v[44:47]
	v_mfma_f32_16x16x32_bf16 v[40:43], v[156:159], v[188:191], v[40:43]
	v_mfma_f32_16x16x32_bf16 v[28:31], v[140:143], v[196:199], v[28:31]
	v_mfma_f32_16x16x32_bf16 v[24:27], v[156:159], v[196:199], v[24:27]
	v_mfma_f32_16x16x32_bf16 v[12:15], v[140:143], v[216:219], v[12:15]
	v_mfma_f32_16x16x32_bf16 v[8:11], v[156:159], v[216:219], v[8:11]
	v_mfma_f32_16x16x32_bf16 v[60:63], v[152:155], v[184:187], v[60:63]
	v_mfma_f32_16x16x32_bf16 v[56:59], v[160:163], v[184:187], v[56:59]
	v_mfma_f32_16x16x32_bf16 v[44:47], v[152:155], v[192:195], v[44:47]
	v_mfma_f32_16x16x32_bf16 v[40:43], v[160:163], v[192:195], v[40:43]
	v_mfma_f32_16x16x32_bf16 v[28:31], v[152:155], v[200:203], v[28:31]
	v_mfma_f32_16x16x32_bf16 v[24:27], v[160:163], v[200:203], v[24:27]
	v_mfma_f32_16x16x32_bf16 v[12:15], v[152:155], v[220:223], v[12:15]
	v_mfma_f32_16x16x32_bf16 v[8:11], v[160:163], v[220:223], v[8:11]
	s_setprio 0
	s_setprio 1
	v_mfma_f32_16x16x32_bf16 v[52:55], v[164:167], v[180:183], v[52:55]
	v_mfma_f32_16x16x32_bf16 v[48:51], v[172:175], v[180:183], v[48:51]
	v_mfma_f32_16x16x32_bf16 v[36:39], v[164:167], v[188:191], v[36:39]
	v_mfma_f32_16x16x32_bf16 v[32:35], v[172:175], v[188:191], v[32:35]
	v_mfma_f32_16x16x32_bf16 v[20:23], v[164:167], v[196:199], v[20:23]
	v_mfma_f32_16x16x32_bf16 v[16:19], v[172:175], v[196:199], v[16:19]
	v_mfma_f32_16x16x32_bf16 v[4:7], v[164:167], v[216:219], v[4:7]
	v_mfma_f32_16x16x32_bf16 v[0:3], v[172:175], v[216:219], v[0:3]
	v_mfma_f32_16x16x32_bf16 v[52:55], v[168:171], v[184:187], v[52:55]
	v_mfma_f32_16x16x32_bf16 v[48:51], v[176:179], v[184:187], v[48:51]
	v_mfma_f32_16x16x32_bf16 v[36:39], v[168:171], v[192:195], v[36:39]
	v_mfma_f32_16x16x32_bf16 v[32:35], v[176:179], v[192:195], v[32:35]
	v_mfma_f32_16x16x32_bf16 v[20:23], v[168:171], v[200:203], v[20:23]
	v_mfma_f32_16x16x32_bf16 v[16:19], v[176:179], v[200:203], v[16:19]
	v_mfma_f32_16x16x32_bf16 v[4:7], v[168:171], v[220:223], v[4:7]
	v_mfma_f32_16x16x32_bf16 v[0:3], v[176:179], v[220:223], v[0:3]
	s_setprio 0
	s_barrier
	s_add_u32 s4, s4, 0x100
	s_addc_u32 s5, s5, 0
	s_add_u32 s56, s56, 0x100
	s_addc_u32 s57, s57, 0
	s_cmp_ge_i32 s58, s44
	s_mov_b32 s34, s58
	s_cbranch_scc0 .LBB0_1201

; #define PG8_STAGE(bufoff, gbase, voff) do { _Pragma("unroll") for (int _i = 0; _i < 2; ++_i) \
;         __builtin_amdgcn_global_load_lds((const unsigned*)((const char*)(gbase) + (voff)[_i]), (PG8_LAS unsigned*)(lds + (bufoff) + ldsw + _i * 8192), 16, 0, 0); } while (0)
; #define PG8_LDA(dst, b, h) do { _Pragma("unroll") for (int m = 0; m < 4; ++m) _Pragma("unroll") for (int k = 0; k < 2; ++k) dst[m][k] = *(const PG8_LAS bf16x8*)(lds + PG8_SA(b, h) + aoff + m * 2048 + k * 1024); } while (0)
; #define PG8_LDB(dst, b, h) do { _Pragma("unroll") for (int n = 0; n < 2; ++n) _Pragma("unroll") for (int k = 0; k < 2; ++k) dst[n][k] = *(const PG8_LAS bf16x8*)(lds + PG8_SB(b, h) + boff + n * 2048 + k * 1024); } while (0)
; #define PG8_MMA(ai, bj, At, Bt) do { __builtin_amdgcn_s_setprio(1); _Pragma("unroll") for (int m = 0; m < 4; ++m) _Pragma("unroll") for (int n = 0; n < 2; ++n) _Pragma("unroll") for (int k = 0; k < 2; ++k) \
;         acc[ai][bj][m][n] = __builtin_amdgcn_mfma_f32_16x16x32_bf16(Bt[n][k], At[m][k], acc[ai][bj][m][n], 0, 0, 0); __builtin_amdgcn_s_setprio(0); } while (0)
; #define PG8_WAIT_V(n) asm volatile("s_waitcnt vmcnt(" #n ")" ::: "memory")
; #define PG8_WAIT_L(n) asm volatile("s_waitcnt lgkmcnt(" #n ")" ::: "memory")
; #define PG8_BAR __builtin_amdgcn_s_barrier()
; #define PG8_SCHED __builtin_amdgcn_sched_barrier(0)
; template <class Epi, class Sched, bool ALIGN_EPI = false, bool SP2 = false>
; __device__ __forceinline__ void gemm_phase(PG8_LAS unsigned char* lds, const Gemm g, const Sched& S, const Epi& E, const int tid) {
;     ...
;             PG8_LDB(B0, 0, 0); PG8_LDB(B1, 0, 1); PG8_SCHED; PG8_LDA(At, 0, 0); PG8_STAGE(PG8_SA(1, 1), a1 + hstepA, voffA);
;             PG8_WAIT_V(8); PG8_WAIT_L(0); PG8_BAR; PG8_MMA(0, 0, At, B0); PG8_MMA(0, 1, At, B1); PG8_BAR; PG8_SCHED;
;             PG8_LDA(At, 0, 1); PG8_STAGE(PG8_SB(0, 0), b2, voffB); PG8_STAGE(PG8_SB(0, 1), b2 + hstepB, voffB); PG8_STAGE(PG8_SA(0, 0), a2, voffA);
;             PG8_WAIT_V(8); PG8_WAIT_L(0); PG8_BAR; PG8_MMA(1, 0, At, B0); PG8_MMA(1, 1, At, B1); PG8_BAR; PG8_SCHED;
.LBB0_1320:
	s_add_i32 s38, s8, 2
	s_add_u32 s39, s4, 0x80
	s_addc_u32 s9, s5, 0
	s_add_i32 s61, 0, 0x10000
	s_cmp_eq_u32 s55, s8
	s_cselect_b32 s9, s35, s9
	s_cselect_b32 s8, s34, s39
	v_add_u32_e32 v144, s61, v146
	s_cselect_b32 s63, s37, s11
	s_cselect_b32 s62, s36, s10
	s_add_i32 s39, 0, 0x14000
	ds_read_b128 v[140:143], v144
	ds_read_b128 v[150:153], v144 offset:1024
	ds_read_b128 v[154:157], v144 offset:2048
	ds_read_b128 v[158:161], v144 offset:3072
	v_add_u32_e32 v144, s39, v146
	ds_read_b128 v[162:165], v144
	ds_read_b128 v[166:169], v144 offset:1024
	ds_read_b128 v[170:173], v144 offset:2048
	ds_read_b128 v[174:177], v144 offset:3072
	s_add_i32 m0, s48, 0xc000
	ds_read_b128 v[178:181], v147
	ds_read_b128 v[182:185], v147 offset:1024
	ds_read_b128 v[186:189], v147 offset:2048
	ds_read_b128 v[190:193], v147 offset:3072
	ds_read_b128 v[194:197], v147 offset:4096
	ds_read_b128 v[198:201], v147 offset:5120
	ds_read_b128 v[202:205], v147 offset:6144
	ds_read_b128 v[216:219], v147 offset:7168
	global_load_lds_dwordx4 v136, s[4:5]
	s_add_i32 m0, s48, 0xe000
	s_nop 0
	global_load_lds_dwordx4 v138, s[4:5]
	s_waitcnt vmcnt(8)
	s_waitcnt lgkmcnt(0)
	s_barrier
	s_setprio 1
	s_waitcnt lgkmcnt(0)
	v_mfma_f32_16x16x32_bf16 v[120:123], v[140:143], v[178:181], v[120:123]
	v_mfma_f32_16x16x32_bf16 v[124:127], v[154:157], v[178:181], v[124:127]
	v_mfma_f32_16x16x32_bf16 v[108:111], v[140:143], v[186:189], v[108:111]
	v_mfma_f32_16x16x32_bf16 v[104:107], v[154:157], v[186:189], v[104:107]
	v_mfma_f32_16x16x32_bf16 v[92:95], v[140:143], v[194:197], v[92:95]
	v_mfma_f32_16x16x32_bf16 v[88:91], v[154:157], v[194:197], v[88:91]
	v_mfma_f32_16x16x32_bf16 v[76:79], v[140:143], v[202:205], v[76:79]
	v_mfma_f32_16x16x32_bf16 v[72:75], v[154:157], v[202:205], v[72:75]
	v_mfma_f32_16x16x32_bf16 v[120:123], v[150:153], v[182:185], v[120:123]
	v_mfma_f32_16x16x32_bf16 v[124:127], v[158:161], v[182:185], v[124:127]
	v_mfma_f32_16x16x32_bf16 v[108:111], v[150:153], v[190:193], v[108:111]
	v_mfma_f32_16x16x32_bf16 v[104:107], v[158:161], v[190:193], v[104:107]
	v_mfma_f32_16x16x32_bf16 v[92:95], v[150:153], v[198:201], v[92:95]
	v_mfma_f32_16x16x32_bf16 v[88:91], v[158:161], v[198:201], v[88:91]
	v_mfma_f32_16x16x32_bf16 v[76:79], v[150:153], v[216:219], v[76:79]
	v_mfma_f32_16x16x32_bf16 v[72:75], v[158:161], v[216:219], v[72:75]
	s_setprio 0
	s_setprio 1
	v_mfma_f32_16x16x32_bf16 v[116:119], v[162:165], v[178:181], v[116:119]
	v_mfma_f32_16x16x32_bf16 v[112:115], v[170:173], v[178:181], v[112:115]
	v_mfma_f32_16x16x32_bf16 v[100:103], v[162:165], v[186:189], v[100:103]
	v_mfma_f32_16x16x32_bf16 v[96:99], v[170:173], v[186:189], v[96:99]
	v_mfma_f32_16x16x32_bf16 v[84:87], v[162:165], v[194:197], v[84:87]
	v_mfma_f32_16x16x32_bf16 v[80:83], v[170:173], v[194:197], v[80:83]
	v_mfma_f32_16x16x32_bf16 v[68:71], v[162:165], v[202:205], v[68:71]
	v_mfma_f32_16x16x32_bf16 v[64:67], v[170:173], v[202:205], v[64:67]
	v_mfma_f32_16x16x32_bf16 v[116:119], v[166:169], v[182:185], v[116:119]
	v_mfma_f32_16x16x32_bf16 v[112:115], v[174:177], v[182:185], v[112:115]
	v_mfma_f32_16x16x32_bf16 v[100:103], v[166:169], v[190:193], v[100:103]
	v_mfma_f32_16x16x32_bf16 v[96:99], v[174:177], v[190:193], v[96:99]
	v_mfma_f32_16x16x32_bf16 v[84:87], v[166:169], v[198:201], v[84:87]
	v_mfma_f32_16x16x32_bf16 v[80:83], v[174:177], v[198:201], v[80:83]
	v_mfma_f32_16x16x32_bf16 v[68:71], v[166:169], v[216:219], v[68:71]
	v_mfma_f32_16x16x32_bf16 v[64:67], v[174:177], v[216:219], v[64:67]
	s_setprio 0
	s_barrier
	s_add_i32 s61, s61, s2
	v_lshl_add_u64 v[208:209], s[62:63], 0, v[148:149]
	s_mov_b32 m0, s61
	ds_read_b128 v[178:181], v147 offset:16384
	ds_read_b128 v[182:185], v147 offset:17408
	ds_read_b128 v[186:189], v147 offset:18432
	ds_read_b128 v[190:193], v147 offset:19456
	ds_read_b128 v[194:197], v147 offset:20480
	ds_read_b128 v[198:201], v147 offset:21504
	ds_read_b128 v[202:205], v147 offset:22528
	ds_read_b128 v[216:219], v147 offset:23552
	global_load_lds_dwordx4 v[208:209], off
	s_add_i32 m0, s61, 0x2000
	v_lshl_add_u64 v[220:221], s[62:63], 0, v[132:133]
	s_add_u32 s62, s62, s20
	s_addc_u32 s63, s63, s21
	s_add_i32 s39, s39, s2
	global_load_lds_dwordx4 v[220:221], off
	v_lshl_add_u64 v[222:223], s[62:63], 0, v[148:149]
	s_mov_b32 m0, s39
	v_lshl_add_u64 v[224:225], s[62:63], 0, v[132:133]
	global_load_lds_dwordx4 v[222:223], off
	s_add_i32 m0, s39, 0x2000
	v_lshl_add_u64 v[226:227], s[8:9], 0, v[128:129]
	global_load_lds_dwordx4 v[224:225], off
	s_mov_b32 m0, s48
	v_lshl_add_u64 v[228:229], s[8:9], 0, v[130:131]
	global_load_lds_dwordx4 v[226:227], off
	s_mov_b32 m0, s49
	s_nop 0
	global_load_lds_dwordx4 v[228:229], off
	s_waitcnt vmcnt(8)
	s_waitcnt lgkmcnt(0)
	s_barrier
; #define PG8_STAGE(bufoff, gbase, voff) do { _Pragma("unroll") for (int _i = 0; _i < 2; ++_i) \
;         __builtin_amdgcn_global_load_lds((const unsigned*)((const char*)(gbase) + (voff)[_i]), (PG8_LAS unsigned*)(lds + (bufoff) + ldsw + _i * 8192), 16, 0, 0); } while (0)
; #define PG8_LDA(dst, b, h) do { _Pragma("unroll") for (int m = 0; m < 4; ++m) _Pragma("unroll") for (int k = 0; k < 2; ++k) dst[m][k] = *(const PG8_LAS bf16x8*)(lds + PG8_SA(b, h) + aoff + m * 2048 + k * 1024); } while (0)
; #define PG8_LDB(dst, b, h) do { _Pragma("unroll") for (int n = 0; n < 2; ++n) _Pragma("unroll") for (int k = 0; k < 2; ++k) dst[n][k] = *(const PG8_LAS bf16x8*)(lds + PG8_SB(b, h) + boff + n * 2048 + k * 1024); } while (0)
; #define PG8_MMA(ai, bj, At, Bt) do { __builtin_amdgcn_s_setprio(1); _Pragma("unroll") for (int m = 0; m < 4; ++m) _Pragma("unroll") for (int n = 0; n < 2; ++n) _Pragma("unroll") for (int k = 0; k < 2; ++k) \
;         acc[ai][bj][m][n] = __builtin_amdgcn_mfma_f32_16x16x32_bf16(Bt[n][k], At[m][k], acc[ai][bj][m][n], 0, 0, 0); __builtin_amdgcn_s_setprio(0); } while (0)
; #define PG8_WAIT_V(n) asm volatile("s_waitcnt vmcnt(" #n ")" ::: "memory")
; #define PG8_WAIT_L(n) asm volatile("s_waitcnt lgkmcnt(" #n ")" ::: "memory")
; #define PG8_BAR __builtin_amdgcn_s_barrier()
; #define PG8_SCHED __builtin_amdgcn_sched_barrier(0)
; template <class Epi, class Sched, bool ALIGN_EPI = false, bool SP2 = false>
; __device__ __forceinline__ void gemm_phase(PG8_LAS unsigned char* lds, const Gemm g, const Sched& S, const Epi& E, const int tid) {
;     ...
;             PG8_WAIT_V(8); PG8_WAIT_L(0); PG8_BAR; PG8_MMA(1, 0, At, B0); PG8_MMA(1, 1, At, B1); PG8_BAR; PG8_SCHED;
;             PG8_LDB(B0, 1, 0); PG8_LDB(B1, 1, 1); PG8_SCHED; PG8_LDA(At, 1, 0); PG8_STAGE(PG8_SA(0, 1), a2 + hstepA, voffA);
;             PG8_WAIT_V(8); PG8_WAIT_L(0); PG8_BAR; PG8_MMA(0, 0, At, B0); PG8_MMA(0, 1, At, B1); PG8_BAR; PG8_SCHED;
	s_setprio 1
	s_waitcnt lgkmcnt(0)
	v_mfma_f32_16x16x32_bf16 v[60:63], v[140:143], v[178:181], v[60:63]
	v_mfma_f32_16x16x32_bf16 v[56:59], v[154:157], v[178:181], v[56:59]
	v_mfma_f32_16x16x32_bf16 v[44:47], v[140:143], v[186:189], v[44:47]
	v_mfma_f32_16x16x32_bf16 v[40:43], v[154:157], v[186:189], v[40:43]
	v_mfma_f32_16x16x32_bf16 v[28:31], v[140:143], v[194:197], v[28:31]
	v_mfma_f32_16x16x32_bf16 v[24:27], v[154:157], v[194:197], v[24:27]
	v_mfma_f32_16x16x32_bf16 v[12:15], v[140:143], v[202:205], v[12:15]
	v_mfma_f32_16x16x32_bf16 v[8:11], v[154:157], v[202:205], v[8:11]
	v_mfma_f32_16x16x32_bf16 v[60:63], v[150:153], v[182:185], v[60:63]
	v_mfma_f32_16x16x32_bf16 v[56:59], v[158:161], v[182:185], v[56:59]
	v_mfma_f32_16x16x32_bf16 v[44:47], v[150:153], v[190:193], v[44:47]
	v_mfma_f32_16x16x32_bf16 v[40:43], v[158:161], v[190:193], v[40:43]
	v_mfma_f32_16x16x32_bf16 v[28:31], v[150:153], v[198:201], v[28:31]
	v_mfma_f32_16x16x32_bf16 v[24:27], v[158:161], v[198:201], v[24:27]
	v_mfma_f32_16x16x32_bf16 v[12:15], v[150:153], v[216:219], v[12:15]
	v_mfma_f32_16x16x32_bf16 v[8:11], v[158:161], v[216:219], v[8:11]
	s_setprio 0
	s_setprio 1
	v_mfma_f32_16x16x32_bf16 v[52:55], v[162:165], v[178:181], v[52:55]
	v_mfma_f32_16x16x32_bf16 v[48:51], v[170:173], v[178:181], v[48:51]
	v_mfma_f32_16x16x32_bf16 v[36:39], v[162:165], v[186:189], v[36:39]
	v_mfma_f32_16x16x32_bf16 v[32:35], v[170:173], v[186:189], v[32:35]
	v_mfma_f32_16x16x32_bf16 v[20:23], v[162:165], v[194:197], v[20:23]
	v_mfma_f32_16x16x32_bf16 v[16:19], v[170:173], v[194:197], v[16:19]
	v_mfma_f32_16x16x32_bf16 v[4:7], v[162:165], v[202:205], v[4:7]
	v_mfma_f32_16x16x32_bf16 v[0:3], v[170:173], v[202:205], v[0:3]
	v_mfma_f32_16x16x32_bf16 v[52:55], v[166:169], v[182:185], v[52:55]
	v_mfma_f32_16x16x32_bf16 v[48:51], v[174:177], v[182:185], v[48:51]
	v_mfma_f32_16x16x32_bf16 v[36:39], v[166:169], v[190:193], v[36:39]
	v_mfma_f32_16x16x32_bf16 v[32:35], v[174:177], v[190:193], v[32:35]
	v_mfma_f32_16x16x32_bf16 v[20:23], v[166:169], v[198:201], v[20:23]
	v_mfma_f32_16x16x32_bf16 v[16:19], v[174:177], v[198:201], v[16:19]
	v_mfma_f32_16x16x32_bf16 v[4:7], v[166:169], v[216:219], v[4:7]
	v_mfma_f32_16x16x32_bf16 v[0:3], v[174:177], v[216:219], v[0:3]
	s_setprio 0
	s_barrier
	s_add_i32 s39, 0, 0x18000
	v_add_u32_e32 v144, s39, v146
	s_add_i32 s61, 0, 0x1c000
	ds_read_b128 v[140:143], v144
	ds_read_b128 v[150:153], v144 offset:1024
	ds_read_b128 v[154:157], v144 offset:2048
	ds_read_b128 v[158:161], v144 offset:3072
	v_add_u32_e32 v144, s61, v146
	ds_read_b128 v[162:165], v144
	ds_read_b128 v[166:169], v144 offset:1024
	ds_read_b128 v[170:173], v144 offset:2048
	ds_read_b128 v[174:177], v144 offset:3072
	s_add_u32 s8, s8, s18
	s_addc_u32 s9, s9, s19
	s_mov_b32 m0, s50
	ds_read_b128 v[178:181], v147 offset:32768
	ds_read_b128 v[182:185], v147 offset:33792
	ds_read_b128 v[186:189], v147 offset:34816
	ds_read_b128 v[190:193], v147 offset:35840
	ds_read_b128 v[194:197], v147 offset:36864
	ds_read_b128 v[198:201], v147 offset:37888
	ds_read_b128 v[202:205], v147 offset:38912
	ds_read_b128 v[216:219], v147 offset:39936
	global_load_lds_dwordx4 v128, s[8:9]
	s_mov_b32 m0, s51
	s_nop 0
	global_load_lds_dwordx4 v130, s[8:9]
	s_waitcnt vmcnt(8)
	s_waitcnt lgkmcnt(0)
	s_barrier
	s_setprio 1
	s_waitcnt lgkmcnt(0)
	v_mfma_f32_16x16x32_bf16 v[120:123], v[140:143], v[178:181], v[120:123]
	v_mfma_f32_16x16x32_bf16 v[124:127], v[154:157], v[178:181], v[124:127]
	v_mfma_f32_16x16x32_bf16 v[108:111], v[140:143], v[186:189], v[108:111]
	v_mfma_f32_16x16x32_bf16 v[104:107], v[154:157], v[186:189], v[104:107]
	v_mfma_f32_16x16x32_bf16 v[92:95], v[140:143], v[194:197], v[92:95]
	v_mfma_f32_16x16x32_bf16 v[88:91], v[154:157], v[194:197], v[88:91]
	v_mfma_f32_16x16x32_bf16 v[76:79], v[140:143], v[202:205], v[76:79]
	v_mfma_f32_16x16x32_bf16 v[72:75], v[154:157], v[202:205], v[72:75]
	v_mfma_f32_16x16x32_bf16 v[120:123], v[150:153], v[182:185], v[120:123]
	v_mfma_f32_16x16x32_bf16 v[124:127], v[158:161], v[182:185], v[124:127]
	v_mfma_f32_16x16x32_bf16 v[108:111], v[150:153], v[190:193], v[108:111]
	v_mfma_f32_16x16x32_bf16 v[104:107], v[158:161], v[190:193], v[104:107]
	v_mfma_f32_16x16x32_bf16 v[92:95], v[150:153], v[198:201], v[92:95]
	v_mfma_f32_16x16x32_bf16 v[88:91], v[158:161], v[198:201], v[88:91]
	v_mfma_f32_16x16x32_bf16 v[76:79], v[150:153], v[216:219], v[76:79]
	v_mfma_f32_16x16x32_bf16 v[72:75], v[158:161], v[216:219], v[72:75]
	s_setprio 0
	s_setprio 1
	v_mfma_f32_16x16x32_bf16 v[116:119], v[162:165], v[178:181], v[116:119]
	v_mfma_f32_16x16x32_bf16 v[112:115], v[170:173], v[178:181], v[112:115]
	v_mfma_f32_16x16x32_bf16 v[100:103], v[162:165], v[186:189], v[100:103]
	v_mfma_f32_16x16x32_bf16 v[96:99], v[170:173], v[186:189], v[96:99]
	v_mfma_f32_16x16x32_bf16 v[84:87], v[162:165], v[194:197], v[84:87]
	v_mfma_f32_16x16x32_bf16 v[80:83], v[170:173], v[194:197], v[80:83]
	v_mfma_f32_16x16x32_bf16 v[68:71], v[162:165], v[202:205], v[68:71]
	v_mfma_f32_16x16x32_bf16 v[64:67], v[170:173], v[202:205], v[64:67]
	v_mfma_f32_16x16x32_bf16 v[116:119], v[166:169], v[182:185], v[116:119]
	v_mfma_f32_16x16x32_bf16 v[112:115], v[174:177], v[182:185], v[112:115]
	v_mfma_f32_16x16x32_bf16 v[100:103], v[166:169], v[190:193], v[100:103]
	v_mfma_f32_16x16x32_bf16 v[96:99], v[174:177], v[190:193], v[96:99]
	v_mfma_f32_16x16x32_bf16 v[84:87], v[166:169], v[198:201], v[84:87]
	v_mfma_f32_16x16x32_bf16 v[80:83], v[174:177], v[198:201], v[80:83]
	v_mfma_f32_16x16x32_bf16 v[68:71], v[166:169], v[216:219], v[68:71]
	v_mfma_f32_16x16x32_bf16 v[64:67], v[174:177], v[216:219], v[64:67]
	s_setprio 0
	s_barrier
; #define PG8_STAGE(bufoff, gbase, voff) do { _Pragma("unroll") for (int _i = 0; _i < 2; ++_i) \
;         __builtin_amdgcn_global_load_lds((const unsigned*)((const char*)(gbase) + (voff)[_i]), (PG8_LAS unsigned*)(lds + (bufoff) + ldsw + _i * 8192), 16, 0, 0); } while (0)
; #define PG8_LDA(dst, b, h) do { _Pragma("unroll") for (int m = 0; m < 4; ++m) _Pragma("unroll") for (int k = 0; k < 2; ++k) dst[m][k] = *(const PG8_LAS bf16x8*)(lds + PG8_SA(b, h) + aoff + m * 2048 + k * 1024); } while (0)
; #define PG8_MMA(ai, bj, At, Bt) do { __builtin_amdgcn_s_setprio(1); _Pragma("unroll") for (int m = 0; m < 4; ++m) _Pragma("unroll") for (int n = 0; n < 2; ++n) _Pragma("unroll") for (int k = 0; k < 2; ++k) \
;         acc[ai][bj][m][n] = __builtin_amdgcn_mfma_f32_16x16x32_bf16(Bt[n][k], At[m][k], acc[ai][bj][m][n], 0, 0, 0); __builtin_amdgcn_s_setprio(0); } while (0)
; #define PG8_WAIT_V(n) asm volatile("s_waitcnt vmcnt(" #n ")" ::: "memory")
; #define PG8_WAIT_L(n) asm volatile("s_waitcnt lgkmcnt(" #n ")" ::: "memory")
; #define PG8_BAR __builtin_amdgcn_s_barrier()
; #define PG8_SCHED __builtin_amdgcn_sched_barrier(0)
; template <class Epi, class Sched, bool ALIGN_EPI = false, bool SP2 = false>
; __device__ __forceinline__ void gemm_phase(PG8_LAS unsigned char* lds, const Gemm g, const Sched& S, const Epi& E, const int tid) {
;     ...
;         for (int t = 0; t < nt; t += 2) {
;             if constexpr (Epi::KHOOK) { if (t == 8 || t == 16) E.khook(acc, cur, t, wr, wc, fr, fq); }
;             const bool last = (t == nt - 2);
;             const char* a1 = cA + (size_t)(t + 1) * kstep;
;             const char* a2 = last ? nA : cA + (size_t)(t + 2) * kstep; const char* b2 = last ? nB : cB + (size_t)(t + 2) * kstep;
;     ...
;             PG8_LDA(At, 1, 1); PG8_STAGE(PG8_SB(1, 0), b3, voffB); PG8_STAGE(PG8_SB(1, 1), b3 + hstepB, voffB); PG8_STAGE(PG8_SA(1, 0), a3, voffA);
;             PG8_WAIT_V(8); PG8_WAIT_L(0); PG8_BAR; PG8_MMA(1, 0, At, B0); PG8_MMA(1, 1, At, B1); PG8_BAR; PG8_SCHED;
	s_add_i32 s8, s39, s2
	s_add_i32 m0, s8, 0xffffff80
	ds_read_b128 v[178:181], v147 offset:49152
	ds_read_b128 v[182:185], v147 offset:50176
	ds_read_b128 v[186:189], v147 offset:51200
	ds_read_b128 v[190:193], v147 offset:52224
	ds_read_b128 v[194:197], v147 offset:53248
	ds_read_b128 v[198:201], v147 offset:54272
	ds_read_b128 v[202:205], v147 offset:55296
	ds_read_b128 v[216:219], v147 offset:56320
	global_load_lds_dwordx4 v[208:209], off offset:128
	s_add_i32 m0, s8, 0x1f80
	s_add_i32 s8, s61, s2
	global_load_lds_dwordx4 v[220:221], off offset:128
	s_add_i32 m0, s8, 0xffffff80
	s_nop 0
	global_load_lds_dwordx4 v[222:223], off offset:128
	s_add_i32 m0, s8, 0x1f80
	s_nop 0
	global_load_lds_dwordx4 v[224:225], off offset:128
	s_add_i32 m0, s53, 0xffffff80
	s_nop 0
	global_load_lds_dwordx4 v[226:227], off offset:128
	s_add_i32 m0, s54, 0xffffff80
	s_nop 0
	global_load_lds_dwordx4 v[228:229], off offset:128
	s_waitcnt vmcnt(8)
	s_waitcnt lgkmcnt(0)
	s_barrier
	s_setprio 1
	s_waitcnt lgkmcnt(0)
	v_mfma_f32_16x16x32_bf16 v[60:63], v[140:143], v[178:181], v[60:63]
	v_mfma_f32_16x16x32_bf16 v[56:59], v[154:157], v[178:181], v[56:59]
	v_mfma_f32_16x16x32_bf16 v[44:47], v[140:143], v[186:189], v[44:47]
	v_mfma_f32_16x16x32_bf16 v[40:43], v[154:157], v[186:189], v[40:43]
	v_mfma_f32_16x16x32_bf16 v[28:31], v[140:143], v[194:197], v[28:31]
	v_mfma_f32_16x16x32_bf16 v[24:27], v[154:157], v[194:197], v[24:27]
	v_mfma_f32_16x16x32_bf16 v[12:15], v[140:143], v[202:205], v[12:15]
	v_mfma_f32_16x16x32_bf16 v[8:11], v[154:157], v[202:205], v[8:11]
	v_mfma_f32_16x16x32_bf16 v[60:63], v[150:153], v[182:185], v[60:63]
	v_mfma_f32_16x16x32_bf16 v[56:59], v[158:161], v[182:185], v[56:59]
	v_mfma_f32_16x16x32_bf16 v[44:47], v[150:153], v[190:193], v[44:47]
	v_mfma_f32_16x16x32_bf16 v[40:43], v[158:161], v[190:193], v[40:43]
	v_mfma_f32_16x16x32_bf16 v[28:31], v[150:153], v[198:201], v[28:31]
	v_mfma_f32_16x16x32_bf16 v[24:27], v[158:161], v[198:201], v[24:27]
	v_mfma_f32_16x16x32_bf16 v[12:15], v[150:153], v[216:219], v[12:15]
	v_mfma_f32_16x16x32_bf16 v[8:11], v[158:161], v[216:219], v[8:11]
	s_setprio 0
	s_setprio 1
	v_mfma_f32_16x16x32_bf16 v[52:55], v[162:165], v[178:181], v[52:55]
	v_mfma_f32_16x16x32_bf16 v[48:51], v[170:173], v[178:181], v[48:51]
	v_mfma_f32_16x16x32_bf16 v[36:39], v[162:165], v[186:189], v[36:39]
	v_mfma_f32_16x16x32_bf16 v[32:35], v[170:173], v[186:189], v[32:35]
	v_mfma_f32_16x16x32_bf16 v[20:23], v[162:165], v[194:197], v[20:23]
	v_mfma_f32_16x16x32_bf16 v[16:19], v[170:173], v[194:197], v[16:19]
	v_mfma_f32_16x16x32_bf16 v[4:7], v[162:165], v[202:205], v[4:7]
	v_mfma_f32_16x16x32_bf16 v[0:3], v[170:173], v[202:205], v[0:3]
	v_mfma_f32_16x16x32_bf16 v[52:55], v[166:169], v[182:185], v[52:55]
	v_mfma_f32_16x16x32_bf16 v[48:51], v[174:177], v[182:185], v[48:51]
	v_mfma_f32_16x16x32_bf16 v[36:39], v[166:169], v[190:193], v[36:39]
	v_mfma_f32_16x16x32_bf16 v[32:35], v[174:177], v[190:193], v[32:35]
	v_mfma_f32_16x16x32_bf16 v[20:23], v[166:169], v[198:201], v[20:23]
	v_mfma_f32_16x16x32_bf16 v[16:19], v[174:177], v[198:201], v[16:19]
	v_mfma_f32_16x16x32_bf16 v[4:7], v[166:169], v[216:219], v[4:7]
	v_mfma_f32_16x16x32_bf16 v[0:3], v[174:177], v[216:219], v[0:3]
	s_setprio 0
	s_barrier
	s_add_u32 s4, s4, 0x100
	s_addc_u32 s5, s5, 0
	s_add_u32 s10, s10, 0x100
	s_addc_u32 s11, s11, 0
	s_cmp_ge_i32 s38, s52
	s_mov_b32 s8, s38
	s_cbranch_scc0 .LBB0_1320

; #define PG8_STAGE(bufoff, gbase, voff) do { _Pragma("unroll") for (int _i = 0; _i < 2; ++_i) \
;         __builtin_amdgcn_global_load_lds((const unsigned*)((const char*)(gbase) + (voff)[_i]), (PG8_LAS unsigned*)(lds + (bufoff) + ldsw + _i * 8192), 16, 0, 0); } while (0)
; #define PG8_LDA(dst, b, h) do { _Pragma("unroll") for (int m = 0; m < 4; ++m) _Pragma("unroll") for (int k = 0; k < 2; ++k) dst[m][k] = *(const PG8_LAS bf16x8*)(lds + PG8_SA(b, h) + aoff + m * 2048 + k * 1024); } while (0)
; #define PG8_LDB(dst, b, h) do { _Pragma("unroll") for (int n = 0; n < 2; ++n) _Pragma("unroll") for (int k = 0; k < 2; ++k) dst[n][k] = *(const PG8_LAS bf16x8*)(lds + PG8_SB(b, h) + boff + n * 2048 + k * 1024); } while (0)
; #define PG8_MMA(ai, bj, At, Bt) do { __builtin_amdgcn_s_setprio(1); _Pragma("unroll") for (int m = 0; m < 4; ++m) _Pragma("unroll") for (int n = 0; n < 2; ++n) _Pragma("unroll") for (int k = 0; k < 2; ++k) \
;         acc[ai][bj][m][n] = __builtin_amdgcn_mfma_f32_16x16x32_bf16(Bt[n][k], At[m][k], acc[ai][bj][m][n], 0, 0, 0); __builtin_amdgcn_s_setprio(0); } while (0)
; #define PG8_WAIT_V(n) asm volatile("s_waitcnt vmcnt(" #n ")" ::: "memory")
; #define PG8_WAIT_L(n) asm volatile("s_waitcnt lgkmcnt(" #n ")" ::: "memory")
; #define PG8_BAR __builtin_amdgcn_s_barrier()
; #define PG8_SCHED __builtin_amdgcn_sched_barrier(0)
; template <class Epi, class Sched, bool ALIGN_EPI = false, bool SP2 = false>
; __device__ __forceinline__ void gemm_phase(PG8_LAS unsigned char* lds, const Gemm g, const Sched& S, const Epi& E, const int tid) {
;     ...
;             PG8_LDB(B0, 0, 0); PG8_LDB(B1, 0, 1); PG8_SCHED; PG8_LDA(At, 0, 0); PG8_STAGE(PG8_SA(1, 1), a1 + hstepA, voffA);
;             PG8_WAIT_V(8); PG8_WAIT_L(0); PG8_BAR; PG8_MMA(0, 0, At, B0); PG8_MMA(0, 1, At, B1); PG8_BAR; PG8_SCHED;
;             PG8_LDA(At, 0, 1); PG8_STAGE(PG8_SB(0, 0), b2, voffB); PG8_STAGE(PG8_SB(0, 1), b2 + hstepB, voffB); PG8_STAGE(PG8_SA(0, 0), a2, voffA);
;             PG8_WAIT_V(8); PG8_WAIT_L(0); PG8_BAR; PG8_MMA(1, 0, At, B0); PG8_MMA(1, 1, At, B1); PG8_BAR; PG8_SCHED;
.LBB0_1446:
	s_add_i32 s62, s38, 2
	s_add_u32 s63, s4, 0x80
	s_addc_u32 s39, s5, 0
	s_add_i32 s66, 0, 0x10000
	s_cmp_eq_u32 s51, s38
	s_cselect_b32 s39, s11, s39
	s_cselect_b32 s38, s10, s63
	s_cselect_b32 s65, s37, s61
	s_cselect_b32 s64, s36, s60
	s_add_i32 s63, 0, 0x14000
	v_add_u32_e32 v158, s66, v150
	v_add_u32_e32 v174, s63, v150
	ds_read_b128 v[140:143], v158
	ds_read_b128 v[144:147], v158 offset:1024
	ds_read_b128 v[154:157], v158 offset:2048
	ds_read_b128 v[158:161], v158 offset:3072
	ds_read_b128 v[162:165], v174
	ds_read_b128 v[166:169], v174 offset:1024
	ds_read_b128 v[170:173], v174 offset:2048
	ds_read_b128 v[174:177], v174 offset:3072
	s_add_i32 m0, s44, 0xc000
	ds_read_b128 v[178:181], v153
	ds_read_b128 v[182:185], v153 offset:1024
	ds_read_b128 v[186:189], v153 offset:2048
	ds_read_b128 v[190:193], v153 offset:3072
	ds_read_b128 v[194:197], v153 offset:4096
	ds_read_b128 v[198:201], v153 offset:5120
	ds_read_b128 v[202:205], v153 offset:6144
	ds_read_b128 v[216:219], v153 offset:7168
	global_load_lds_dwordx4 v136, s[4:5]
	s_add_i32 m0, s44, 0xe000
	s_nop 0
	global_load_lds_dwordx4 v138, s[4:5]
	s_waitcnt vmcnt(8)
	s_waitcnt lgkmcnt(0)
	s_barrier
	s_setprio 1
	s_waitcnt lgkmcnt(0)
	v_mfma_f32_16x16x32_bf16 v[124:127], v[140:143], v[178:181], v[124:127]
	v_mfma_f32_16x16x32_bf16 v[120:123], v[154:157], v[178:181], v[120:123]
	v_mfma_f32_16x16x32_bf16 v[108:111], v[140:143], v[186:189], v[108:111]
	v_mfma_f32_16x16x32_bf16 v[104:107], v[154:157], v[186:189], v[104:107]
	v_mfma_f32_16x16x32_bf16 v[92:95], v[140:143], v[194:197], v[92:95]
	v_mfma_f32_16x16x32_bf16 v[88:91], v[154:157], v[194:197], v[88:91]
	v_mfma_f32_16x16x32_bf16 v[76:79], v[140:143], v[202:205], v[76:79]
	v_mfma_f32_16x16x32_bf16 v[72:75], v[154:157], v[202:205], v[72:75]
	v_mfma_f32_16x16x32_bf16 v[124:127], v[144:147], v[182:185], v[124:127]
	v_mfma_f32_16x16x32_bf16 v[120:123], v[158:161], v[182:185], v[120:123]
	v_mfma_f32_16x16x32_bf16 v[108:111], v[144:147], v[190:193], v[108:111]
	v_mfma_f32_16x16x32_bf16 v[104:107], v[158:161], v[190:193], v[104:107]
	v_mfma_f32_16x16x32_bf16 v[92:95], v[144:147], v[198:201], v[92:95]
	v_mfma_f32_16x16x32_bf16 v[88:91], v[158:161], v[198:201], v[88:91]
	v_mfma_f32_16x16x32_bf16 v[76:79], v[144:147], v[216:219], v[76:79]
	v_mfma_f32_16x16x32_bf16 v[72:75], v[158:161], v[216:219], v[72:75]
	s_setprio 0
	s_setprio 1
	v_mfma_f32_16x16x32_bf16 v[116:119], v[162:165], v[178:181], v[116:119]
	v_mfma_f32_16x16x32_bf16 v[112:115], v[170:173], v[178:181], v[112:115]
	v_mfma_f32_16x16x32_bf16 v[100:103], v[162:165], v[186:189], v[100:103]
	v_mfma_f32_16x16x32_bf16 v[96:99], v[170:173], v[186:189], v[96:99]
	v_mfma_f32_16x16x32_bf16 v[84:87], v[162:165], v[194:197], v[84:87]
	v_mfma_f32_16x16x32_bf16 v[80:83], v[170:173], v[194:197], v[80:83]
	v_mfma_f32_16x16x32_bf16 v[68:71], v[162:165], v[202:205], v[68:71]
	v_mfma_f32_16x16x32_bf16 v[64:67], v[170:173], v[202:205], v[64:67]
	v_mfma_f32_16x16x32_bf16 v[116:119], v[166:169], v[182:185], v[116:119]
	v_mfma_f32_16x16x32_bf16 v[112:115], v[174:177], v[182:185], v[112:115]
	v_mfma_f32_16x16x32_bf16 v[100:103], v[166:169], v[190:193], v[100:103]
	v_mfma_f32_16x16x32_bf16 v[96:99], v[174:177], v[190:193], v[96:99]
	v_mfma_f32_16x16x32_bf16 v[84:87], v[166:169], v[198:201], v[84:87]
	v_mfma_f32_16x16x32_bf16 v[80:83], v[174:177], v[198:201], v[80:83]
	v_mfma_f32_16x16x32_bf16 v[68:71], v[166:169], v[216:219], v[68:71]
	v_mfma_f32_16x16x32_bf16 v[64:67], v[174:177], v[216:219], v[64:67]
	s_setprio 0
	s_barrier
	s_add_i32 s66, s66, s43
	v_lshl_add_u64 v[208:209], s[64:65], 0, v[148:149]
	s_mov_b32 m0, s66
	ds_read_b128 v[178:181], v153 offset:16384
	ds_read_b128 v[182:185], v153 offset:17408
	ds_read_b128 v[186:189], v153 offset:18432
	ds_read_b128 v[190:193], v153 offset:19456
	ds_read_b128 v[194:197], v153 offset:20480
	ds_read_b128 v[198:201], v153 offset:21504
	ds_read_b128 v[202:205], v153 offset:22528
	ds_read_b128 v[216:219], v153 offset:23552
	global_load_lds_dwordx4 v[208:209], off
	s_add_i32 m0, s66, 0x2000
	v_lshl_add_u64 v[220:221], s[64:65], 0, v[132:133]
	s_add_u32 s64, s64, s16
	s_addc_u32 s65, s65, s17
	s_add_i32 s63, s63, s43
	global_load_lds_dwordx4 v[220:221], off
	v_lshl_add_u64 v[222:223], s[64:65], 0, v[148:149]
	s_mov_b32 m0, s63
	v_lshl_add_u64 v[224:225], s[64:65], 0, v[132:133]
	global_load_lds_dwordx4 v[222:223], off
	s_add_i32 m0, s63, 0x2000
	v_lshl_add_u64 v[226:227], s[38:39], 0, v[128:129]
	global_load_lds_dwordx4 v[224:225], off
	s_mov_b32 m0, s44
	v_lshl_add_u64 v[228:229], s[38:39], 0, v[130:131]
	global_load_lds_dwordx4 v[226:227], off
	s_mov_b32 m0, s45
	s_nop 0
	global_load_lds_dwordx4 v[228:229], off
	s_waitcnt vmcnt(8)
	s_waitcnt lgkmcnt(0)
	s_barrier
; #define PG8_STAGE(bufoff, gbase, voff) do { _Pragma("unroll") for (int _i = 0; _i < 2; ++_i) \
;         __builtin_amdgcn_global_load_lds((const unsigned*)((const char*)(gbase) + (voff)[_i]), (PG8_LAS unsigned*)(lds + (bufoff) + ldsw + _i * 8192), 16, 0, 0); } while (0)
; #define PG8_LDA(dst, b, h) do { _Pragma("unroll") for (int m = 0; m < 4; ++m) _Pragma("unroll") for (int k = 0; k < 2; ++k) dst[m][k] = *(const PG8_LAS bf16x8*)(lds + PG8_SA(b, h) + aoff + m * 2048 + k * 1024); } while (0)
; #define PG8_LDB(dst, b, h) do { _Pragma("unroll") for (int n = 0; n < 2; ++n) _Pragma("unroll") for (int k = 0; k < 2; ++k) dst[n][k] = *(const PG8_LAS bf16x8*)(lds + PG8_SB(b, h) + boff + n * 2048 + k * 1024); } while (0)
; #define PG8_MMA(ai, bj, At, Bt) do { __builtin_amdgcn_s_setprio(1); _Pragma("unroll") for (int m = 0; m < 4; ++m) _Pragma("unroll") for (int n = 0; n < 2; ++n) _Pragma("unroll") for (int k = 0; k < 2; ++k) \
;         acc[ai][bj][m][n] = __builtin_amdgcn_mfma_f32_16x16x32_bf16(Bt[n][k], At[m][k], acc[ai][bj][m][n], 0, 0, 0); __builtin_amdgcn_s_setprio(0); } while (0)
; #define PG8_WAIT_V(n) asm volatile("s_waitcnt vmcnt(" #n ")" ::: "memory")
; #define PG8_WAIT_L(n) asm volatile("s_waitcnt lgkmcnt(" #n ")" ::: "memory")
; #define PG8_BAR __builtin_amdgcn_s_barrier()
; #define PG8_SCHED __builtin_amdgcn_sched_barrier(0)
; template <class Epi, class Sched, bool ALIGN_EPI = false, bool SP2 = false>
; __device__ __forceinline__ void gemm_phase(PG8_LAS unsigned char* lds, const Gemm g, const Sched& S, const Epi& E, const int tid) {
;     ...
;             PG8_WAIT_V(8); PG8_WAIT_L(0); PG8_BAR; PG8_MMA(1, 0, At, B0); PG8_MMA(1, 1, At, B1); PG8_BAR; PG8_SCHED;
;             PG8_LDB(B0, 1, 0); PG8_LDB(B1, 1, 1); PG8_SCHED; PG8_LDA(At, 1, 0); PG8_STAGE(PG8_SA(0, 1), a2 + hstepA, voffA);
;             PG8_WAIT_V(8); PG8_WAIT_L(0); PG8_BAR; PG8_MMA(0, 0, At, B0); PG8_MMA(0, 1, At, B1); PG8_BAR; PG8_SCHED;
	s_setprio 1
	s_waitcnt lgkmcnt(0)
	v_mfma_f32_16x16x32_bf16 v[60:63], v[140:143], v[178:181], v[60:63]
	v_mfma_f32_16x16x32_bf16 v[56:59], v[154:157], v[178:181], v[56:59]
	v_mfma_f32_16x16x32_bf16 v[44:47], v[140:143], v[186:189], v[44:47]
	v_mfma_f32_16x16x32_bf16 v[40:43], v[154:157], v[186:189], v[40:43]
	v_mfma_f32_16x16x32_bf16 v[28:31], v[140:143], v[194:197], v[28:31]
	v_mfma_f32_16x16x32_bf16 v[24:27], v[154:157], v[194:197], v[24:27]
	v_mfma_f32_16x16x32_bf16 v[12:15], v[140:143], v[202:205], v[12:15]
	v_mfma_f32_16x16x32_bf16 v[8:11], v[154:157], v[202:205], v[8:11]
	v_mfma_f32_16x16x32_bf16 v[60:63], v[144:147], v[182:185], v[60:63]
	v_mfma_f32_16x16x32_bf16 v[56:59], v[158:161], v[182:185], v[56:59]
	v_mfma_f32_16x16x32_bf16 v[44:47], v[144:147], v[190:193], v[44:47]
	v_mfma_f32_16x16x32_bf16 v[40:43], v[158:161], v[190:193], v[40:43]
	v_mfma_f32_16x16x32_bf16 v[28:31], v[144:147], v[198:201], v[28:31]
	v_mfma_f32_16x16x32_bf16 v[24:27], v[158:161], v[198:201], v[24:27]
	v_mfma_f32_16x16x32_bf16 v[12:15], v[144:147], v[216:219], v[12:15]
	v_mfma_f32_16x16x32_bf16 v[8:11], v[158:161], v[216:219], v[8:11]
	s_setprio 0
	s_setprio 1
	v_mfma_f32_16x16x32_bf16 v[52:55], v[162:165], v[178:181], v[52:55]
	v_mfma_f32_16x16x32_bf16 v[48:51], v[170:173], v[178:181], v[48:51]
	v_mfma_f32_16x16x32_bf16 v[36:39], v[162:165], v[186:189], v[36:39]
	v_mfma_f32_16x16x32_bf16 v[32:35], v[170:173], v[186:189], v[32:35]
	v_mfma_f32_16x16x32_bf16 v[20:23], v[162:165], v[194:197], v[20:23]
	v_mfma_f32_16x16x32_bf16 v[16:19], v[170:173], v[194:197], v[16:19]
	v_mfma_f32_16x16x32_bf16 v[4:7], v[162:165], v[202:205], v[4:7]
	v_mfma_f32_16x16x32_bf16 v[0:3], v[170:173], v[202:205], v[0:3]
	v_mfma_f32_16x16x32_bf16 v[52:55], v[166:169], v[182:185], v[52:55]
	v_mfma_f32_16x16x32_bf16 v[48:51], v[174:177], v[182:185], v[48:51]
	v_mfma_f32_16x16x32_bf16 v[36:39], v[166:169], v[190:193], v[36:39]
	v_mfma_f32_16x16x32_bf16 v[32:35], v[174:177], v[190:193], v[32:35]
	v_mfma_f32_16x16x32_bf16 v[20:23], v[166:169], v[198:201], v[20:23]
	v_mfma_f32_16x16x32_bf16 v[16:19], v[174:177], v[198:201], v[16:19]
	v_mfma_f32_16x16x32_bf16 v[4:7], v[166:169], v[216:219], v[4:7]
	v_mfma_f32_16x16x32_bf16 v[0:3], v[174:177], v[216:219], v[0:3]
	s_setprio 0
	s_barrier
	s_add_i32 s63, 0, 0x18000
	s_add_i32 s64, 0, 0x1c000
	v_add_u32_e32 v158, s63, v150
	v_add_u32_e32 v174, s64, v150
	ds_read_b128 v[140:143], v158
	ds_read_b128 v[144:147], v158 offset:1024
	ds_read_b128 v[154:157], v158 offset:2048
	ds_read_b128 v[158:161], v158 offset:3072
	ds_read_b128 v[162:165], v174
	ds_read_b128 v[166:169], v174 offset:1024
	ds_read_b128 v[170:173], v174 offset:2048
	ds_read_b128 v[174:177], v174 offset:3072
	s_add_u32 s38, s38, s14
	s_addc_u32 s39, s39, s15
	s_mov_b32 m0, s46
	ds_read_b128 v[178:181], v153 offset:32768
	ds_read_b128 v[182:185], v153 offset:33792
	ds_read_b128 v[186:189], v153 offset:34816
	ds_read_b128 v[190:193], v153 offset:35840
	ds_read_b128 v[194:197], v153 offset:36864
	ds_read_b128 v[198:201], v153 offset:37888
	ds_read_b128 v[202:205], v153 offset:38912
	ds_read_b128 v[216:219], v153 offset:39936
	global_load_lds_dwordx4 v128, s[38:39]
	s_mov_b32 m0, s47
	s_nop 0
	global_load_lds_dwordx4 v130, s[38:39]
	s_waitcnt vmcnt(8)
	s_waitcnt lgkmcnt(0)
	s_barrier
	s_setprio 1
	s_waitcnt lgkmcnt(0)
	v_mfma_f32_16x16x32_bf16 v[124:127], v[140:143], v[178:181], v[124:127]
	v_mfma_f32_16x16x32_bf16 v[120:123], v[154:157], v[178:181], v[120:123]
	v_mfma_f32_16x16x32_bf16 v[108:111], v[140:143], v[186:189], v[108:111]
	v_mfma_f32_16x16x32_bf16 v[104:107], v[154:157], v[186:189], v[104:107]
	v_mfma_f32_16x16x32_bf16 v[92:95], v[140:143], v[194:197], v[92:95]
	v_mfma_f32_16x16x32_bf16 v[88:91], v[154:157], v[194:197], v[88:91]
	v_mfma_f32_16x16x32_bf16 v[76:79], v[140:143], v[202:205], v[76:79]
	v_mfma_f32_16x16x32_bf16 v[72:75], v[154:157], v[202:205], v[72:75]
	v_mfma_f32_16x16x32_bf16 v[124:127], v[144:147], v[182:185], v[124:127]
	v_mfma_f32_16x16x32_bf16 v[120:123], v[158:161], v[182:185], v[120:123]
	v_mfma_f32_16x16x32_bf16 v[108:111], v[144:147], v[190:193], v[108:111]
	v_mfma_f32_16x16x32_bf16 v[104:107], v[158:161], v[190:193], v[104:107]
	v_mfma_f32_16x16x32_bf16 v[92:95], v[144:147], v[198:201], v[92:95]
	v_mfma_f32_16x16x32_bf16 v[88:91], v[158:161], v[198:201], v[88:91]
	v_mfma_f32_16x16x32_bf16 v[76:79], v[144:147], v[216:219], v[76:79]
	v_mfma_f32_16x16x32_bf16 v[72:75], v[158:161], v[216:219], v[72:75]
	s_setprio 0
	s_setprio 1
	v_mfma_f32_16x16x32_bf16 v[116:119], v[162:165], v[178:181], v[116:119]
	v_mfma_f32_16x16x32_bf16 v[112:115], v[170:173], v[178:181], v[112:115]
	v_mfma_f32_16x16x32_bf16 v[100:103], v[162:165], v[186:189], v[100:103]
	v_mfma_f32_16x16x32_bf16 v[96:99], v[170:173], v[186:189], v[96:99]
	v_mfma_f32_16x16x32_bf16 v[84:87], v[162:165], v[194:197], v[84:87]
	v_mfma_f32_16x16x32_bf16 v[80:83], v[170:173], v[194:197], v[80:83]
	v_mfma_f32_16x16x32_bf16 v[68:71], v[162:165], v[202:205], v[68:71]
	v_mfma_f32_16x16x32_bf16 v[64:67], v[170:173], v[202:205], v[64:67]
	v_mfma_f32_16x16x32_bf16 v[116:119], v[166:169], v[182:185], v[116:119]
	v_mfma_f32_16x16x32_bf16 v[112:115], v[174:177], v[182:185], v[112:115]
	v_mfma_f32_16x16x32_bf16 v[100:103], v[166:169], v[190:193], v[100:103]
	v_mfma_f32_16x16x32_bf16 v[96:99], v[174:177], v[190:193], v[96:99]
	v_mfma_f32_16x16x32_bf16 v[84:87], v[166:169], v[198:201], v[84:87]
	v_mfma_f32_16x16x32_bf16 v[80:83], v[174:177], v[198:201], v[80:83]
	v_mfma_f32_16x16x32_bf16 v[68:71], v[166:169], v[216:219], v[68:71]
	v_mfma_f32_16x16x32_bf16 v[64:67], v[174:177], v[216:219], v[64:67]
	s_setprio 0
	s_barrier
; #define PG8_STAGE(bufoff, gbase, voff) do { _Pragma("unroll") for (int _i = 0; _i < 2; ++_i) \
;         __builtin_amdgcn_global_load_lds((const unsigned*)((const char*)(gbase) + (voff)[_i]), (PG8_LAS unsigned*)(lds + (bufoff) + ldsw + _i * 8192), 16, 0, 0); } while (0)
; #define PG8_LDA(dst, b, h) do { _Pragma("unroll") for (int m = 0; m < 4; ++m) _Pragma("unroll") for (int k = 0; k < 2; ++k) dst[m][k] = *(const PG8_LAS bf16x8*)(lds + PG8_SA(b, h) + aoff + m * 2048 + k * 1024); } while (0)
; #define PG8_MMA(ai, bj, At, Bt) do { __builtin_amdgcn_s_setprio(1); _Pragma("unroll") for (int m = 0; m < 4; ++m) _Pragma("unroll") for (int n = 0; n < 2; ++n) _Pragma("unroll") for (int k = 0; k < 2; ++k) \
;         acc[ai][bj][m][n] = __builtin_amdgcn_mfma_f32_16x16x32_bf16(Bt[n][k], At[m][k], acc[ai][bj][m][n], 0, 0, 0); __builtin_amdgcn_s_setprio(0); } while (0)
; #define PG8_WAIT_V(n) asm volatile("s_waitcnt vmcnt(" #n ")" ::: "memory")
; #define PG8_WAIT_L(n) asm volatile("s_waitcnt lgkmcnt(" #n ")" ::: "memory")
; #define PG8_BAR __builtin_amdgcn_s_barrier()
; #define PG8_SCHED __builtin_amdgcn_sched_barrier(0)
; template <class Epi, class Sched, bool ALIGN_EPI = false, bool SP2 = false>
; __device__ __forceinline__ void gemm_phase(PG8_LAS unsigned char* lds, const Gemm g, const Sched& S, const Epi& E, const int tid) {
;     ...
;         for (int t = 0; t < nt; t += 2) {
;             if constexpr (Epi::KHOOK) { if (t == 8 || t == 16) E.khook(acc, cur, t, wr, wc, fr, fq); }
;             const bool last = (t == nt - 2);
;             const char* a1 = cA + (size_t)(t + 1) * kstep;
;             const char* a2 = last ? nA : cA + (size_t)(t + 2) * kstep; const char* b2 = last ? nB : cB + (size_t)(t + 2) * kstep;
;     ...
;             PG8_LDA(At, 1, 1); PG8_STAGE(PG8_SB(1, 0), b3, voffB); PG8_STAGE(PG8_SB(1, 1), b3 + hstepB, voffB); PG8_STAGE(PG8_SA(1, 0), a3, voffA);
;             PG8_WAIT_V(8); PG8_WAIT_L(0); PG8_BAR; PG8_MMA(1, 0, At, B0); PG8_MMA(1, 1, At, B1); PG8_BAR; PG8_SCHED;
	s_add_i32 s38, s63, s43
	s_add_i32 m0, s38, 0xffffff80
	ds_read_b128 v[178:181], v153 offset:49152
	ds_read_b128 v[182:185], v153 offset:50176
	ds_read_b128 v[186:189], v153 offset:51200
	ds_read_b128 v[190:193], v153 offset:52224
	ds_read_b128 v[194:197], v153 offset:53248
	ds_read_b128 v[198:201], v153 offset:54272
	ds_read_b128 v[202:205], v153 offset:55296
	ds_read_b128 v[216:219], v153 offset:56320
	global_load_lds_dwordx4 v[208:209], off offset:128
	s_add_i32 m0, s38, 0x1f80
	s_add_i32 s38, s64, s43
	global_load_lds_dwordx4 v[220:221], off offset:128
	s_add_i32 m0, s38, 0xffffff80
	s_nop 0
	global_load_lds_dwordx4 v[222:223], off offset:128
	s_add_i32 m0, s38, 0x1f80
	s_nop 0
	global_load_lds_dwordx4 v[224:225], off offset:128
	s_add_i32 m0, s49, 0xffffff80
	s_nop 0
	global_load_lds_dwordx4 v[226:227], off offset:128
	s_add_i32 m0, s50, 0xffffff80
	s_nop 0
	global_load_lds_dwordx4 v[228:229], off offset:128
	s_waitcnt vmcnt(8)
	s_waitcnt lgkmcnt(0)
	s_barrier
	s_setprio 1
	s_waitcnt lgkmcnt(0)
	v_mfma_f32_16x16x32_bf16 v[60:63], v[140:143], v[178:181], v[60:63]
	v_mfma_f32_16x16x32_bf16 v[56:59], v[154:157], v[178:181], v[56:59]
	v_mfma_f32_16x16x32_bf16 v[44:47], v[140:143], v[186:189], v[44:47]
	v_mfma_f32_16x16x32_bf16 v[40:43], v[154:157], v[186:189], v[40:43]
	v_mfma_f32_16x16x32_bf16 v[28:31], v[140:143], v[194:197], v[28:31]
	v_mfma_f32_16x16x32_bf16 v[24:27], v[154:157], v[194:197], v[24:27]
	v_mfma_f32_16x16x32_bf16 v[12:15], v[140:143], v[202:205], v[12:15]
	v_mfma_f32_16x16x32_bf16 v[8:11], v[154:157], v[202:205], v[8:11]
	v_mfma_f32_16x16x32_bf16 v[60:63], v[144:147], v[182:185], v[60:63]
	v_mfma_f32_16x16x32_bf16 v[56:59], v[158:161], v[182:185], v[56:59]
	v_mfma_f32_16x16x32_bf16 v[44:47], v[144:147], v[190:193], v[44:47]
	v_mfma_f32_16x16x32_bf16 v[40:43], v[158:161], v[190:193], v[40:43]
	v_mfma_f32_16x16x32_bf16 v[28:31], v[144:147], v[198:201], v[28:31]
	v_mfma_f32_16x16x32_bf16 v[24:27], v[158:161], v[198:201], v[24:27]
	v_mfma_f32_16x16x32_bf16 v[12:15], v[144:147], v[216:219], v[12:15]
	v_mfma_f32_16x16x32_bf16 v[8:11], v[158:161], v[216:219], v[8:11]
	s_setprio 0
	s_setprio 1
	v_mfma_f32_16x16x32_bf16 v[52:55], v[162:165], v[178:181], v[52:55]
	v_mfma_f32_16x16x32_bf16 v[48:51], v[170:173], v[178:181], v[48:51]
	v_mfma_f32_16x16x32_bf16 v[36:39], v[162:165], v[186:189], v[36:39]
	v_mfma_f32_16x16x32_bf16 v[32:35], v[170:173], v[186:189], v[32:35]
	v_mfma_f32_16x16x32_bf16 v[20:23], v[162:165], v[194:197], v[20:23]
	v_mfma_f32_16x16x32_bf16 v[16:19], v[170:173], v[194:197], v[16:19]
	v_mfma_f32_16x16x32_bf16 v[4:7], v[162:165], v[202:205], v[4:7]
	v_mfma_f32_16x16x32_bf16 v[0:3], v[170:173], v[202:205], v[0:3]
	v_mfma_f32_16x16x32_bf16 v[52:55], v[166:169], v[182:185], v[52:55]
	v_mfma_f32_16x16x32_bf16 v[48:51], v[174:177], v[182:185], v[48:51]
	v_mfma_f32_16x16x32_bf16 v[36:39], v[166:169], v[190:193], v[36:39]
	v_mfma_f32_16x16x32_bf16 v[32:35], v[174:177], v[190:193], v[32:35]
	v_mfma_f32_16x16x32_bf16 v[20:23], v[166:169], v[198:201], v[20:23]
	v_mfma_f32_16x16x32_bf16 v[16:19], v[174:177], v[198:201], v[16:19]
	v_mfma_f32_16x16x32_bf16 v[4:7], v[166:169], v[216:219], v[4:7]
	v_mfma_f32_16x16x32_bf16 v[0:3], v[174:177], v[216:219], v[0:3]
	s_setprio 0
	s_barrier
	s_add_u32 s4, s4, 0x100
	s_addc_u32 s5, s5, 0
	s_add_u32 s60, s60, 0x100
	s_addc_u32 s61, s61, 0
	s_cmp_ge_i32 s62, s48
	s_mov_b32 s38, s62
	s_cbranch_scc0 .LBB0_1446
